# producer-side priority extended to GEMM tile prologues (first loads through LDS writes and accumulator clear) and read-half priority removed from the last-K-tile bodies
# baseline (speedup 1.0000x reference)
; __device__ __forceinline__ int tidx() { int t = threadIdx.x; asm volatile("" : "+v"(t)); return t; }
; __device__ __forceinline__ void lds_barrier() { asm volatile("s_waitcnt lgkmcnt(0)\n\ts_barrier" ::: "memory"); }
; #define ZERO_ACC4(acc) { _Pragma("unroll") for (int _a = 0; _a < 2; ++_a) { _Pragma("unroll") for (int _b = 0; _b < 4; ++_b) { _Pragma("unroll") for (int _c = 0; _c < 16; ++_c) acc[_a][_b][_c] = 0.f; } } }
; __device__ __forceinline__ void gemm_big(const bf16_t* __restrict__ A, long lda, const bf16_t* __restrict__ Bt, int K, f32x16 (&acc)[2][4], unsigned char* lds) {
;     const int tid = tidx(), lane = tid & 63, wave = tid >> 6, wr = wave >> 1, wc = wave & 1;
;     const int r = lane & 31, h = lane >> 5;
;     bf16_t* As = (bf16_t*)lds;
;     bf16_t* Bs = As + 128 * GLD;
;     const int nk = K >> 6;
;     const int lrow = tid >> 3, lc = tid & 7;
;     const bf16_t* ap = A + (long)lrow * lda + lc * 8;
;     const bf16_t* bp = Bt + (long)lrow * K + lc * 8;
;     u32x4 ra[4], rb[8];
;     auto gload = [&](int kc) {
; #pragma unroll
;         for (int i = 0; i < 4; ++i) ra[i] = *(const u32x4*)(ap + (long)(32 * i) * lda + kc * 64);
; #pragma unroll
;         for (int i = 0; i < 8; ++i) rb[i] = *(const u32x4*)(bp + (long)(32 * i) * K + kc * 64);
;     };
;     auto lstore = [&]() {
; #pragma unroll
;         for (int i = 0; i < 4; ++i) *(u32x4*)(As + (lrow + 32 * i) * GLD + lc * 8) = ra[i];
; #pragma unroll
;         for (int i = 0; i < 8; ++i) *(u32x4*)(Bs + (lrow + 32 * i) * GLD + lc * 8) = rb[i];
;     };
;     const bf16_t* Ac = As + (wr * 64 + r) * GLD + h * 8;
;     const bf16_t* Bc = Bs + (wc * 128 + r) * GLD + h * 8;
;     gload(0);
;     __syncthreads();
;     lstore();
;     if (nk > 1) gload(1);
;     lds_barrier();
; __device__ __forceinline__ void phase_resid(const Params& p, const bf16_t* A, long lda, int mrows, const bf16_t* Bt, int K, float* xres, float scale, unsigned char* lds) {
;     ...
;     for (int k = 0; tile_at(k, mrows / 128, 4, pm, pn); ++k) {
;         f32x16 acc[2][4]; ZERO_ACC4(acc);
;         gemm_big(A + (size_t)pm * 128 * lda, lda, Bt + (size_t)pn * 256 * K, K, acc, lds);
.LBB0_53:
	s_lshr_b32 s5, s4, 2
	s_and_b32 s13, s5, 0x7fffff8
	s_and_b32 s23, s4, 7
	v_readlane_b32 s24, v252, 2
	s_lshl_b32 s5, s13, 2
	s_or_b32 s11, s23, s24
	s_sub_i32 s5, s4, s5
	s_add_i32 s11, s11, s13
	s_ashr_i32 s12, s5, 3
	s_mul_i32 s4, s11, 0xb0000
	s_mul_hi_u32 s5, s11, 0xb0000
	s_add_u32 s4, s3, s4
	s_addc_u32 s5, s6, s5
	s_mul_i32 s14, s12, 0x160000
	v_mov_b32_e32 v74, v179
	s_mul_hi_i32 s15, s12, 0x160000
	s_add_u32 s14, s7, s14
	v_mov_b64_e32 v[2:3], s[4:5]
	v_ashrrev_i32_e32 v75, 3, v74
	v_lshlrev_b32_e32 v0, 4, v74
	s_addc_u32 s15, s8, s15
	v_mad_i64_i32 v[2:3], s[4:5], v75, s63, v[2:3]
	v_and_b32_e32 v0, 0x70, v0
	v_lshl_add_u64 v[50:51], v[2:3], 0, v[0:1]
	v_mov_b64_e32 v[2:3], s[14:15]
	v_mad_i64_i32 v[2:3], s[4:5], v75, s63, v[2:3]
	s_mov_b32 s4, 0x2c000
	s_nop 0
	v_add_co_u32_e32 v54, vcc, s4, v50
	s_mov_b32 s5, 0x58000
	s_nop 0
	v_addc_co_u32_e32 v55, vcc, 0, v51, vcc
	v_add_co_u32_e32 v56, vcc, s5, v50
	s_mov_b32 s14, 0x84000
	s_nop 0
	v_addc_co_u32_e32 v57, vcc, 0, v51, vcc
	v_add_co_u32_e32 v58, vcc, s14, v50
	v_lshl_add_u64 v[52:53], v[2:3], 0, v[0:1]
	s_nop 0
	v_addc_co_u32_e32 v59, vcc, 0, v51, vcc
	v_add_co_u32_e32 v60, vcc, s4, v52
	s_mov_b32 s4, 0xb0000
	s_nop 0
	v_addc_co_u32_e32 v61, vcc, 0, v53, vcc
	v_add_co_u32_e32 v62, vcc, s5, v52
	s_setprio 3
	global_load_dwordx4 v[2:5], v[54:55], off
	global_load_dwordx4 v[6:9], v[56:57], off
	v_addc_co_u32_e32 v63, vcc, 0, v53, vcc
	v_add_co_u32_e32 v64, vcc, s14, v52
	global_load_dwordx4 v[10:13], v[50:51], off
	global_load_dwordx4 v[14:17], v[52:53], off
	v_addc_co_u32_e32 v65, vcc, 0, v53, vcc
	v_add_co_u32_e32 v66, vcc, s4, v52
	s_mov_b32 s4, 0xdc000
	s_nop 0
	v_addc_co_u32_e32 v67, vcc, 0, v53, vcc
	v_add_co_u32_e32 v68, vcc, s4, v52
	s_mov_b32 s4, 0x108000
	s_nop 0
	v_addc_co_u32_e32 v69, vcc, 0, v53, vcc
	v_add_co_u32_e32 v70, vcc, s4, v52
	s_mov_b32 s4, 0x134000
	s_nop 0
	v_addc_co_u32_e32 v71, vcc, 0, v53, vcc
	v_add_co_u32_e32 v72, vcc, s4, v52
	global_load_dwordx4 v[18:21], v[58:59], off
	global_load_dwordx4 v[22:25], v[60:61], off
	global_load_dwordx4 v[26:29], v[62:63], off
	global_load_dwordx4 v[30:33], v[64:65], off
	global_load_dwordx4 v[34:37], v[66:67], off
	global_load_dwordx4 v[38:41], v[68:69], off
	v_addc_co_u32_e32 v73, vcc, 0, v53, vcc
	global_load_dwordx4 v[42:45], v[70:71], off
	global_load_dwordx4 v[46:49], v[72:73], off
	v_and_b32_e32 v76, 31, v74
	v_lshrrev_b32_e32 v77, 1, v74
	s_mov_b32 s4, 0xfffffc0
	v_and_or_b32 v78, v77, s4, v76
	v_lshlrev_b32_e32 v74, 1, v74
	s_movk_i32 s4, 0x80
	v_and_or_b32 v74, v74, s4, v76
	s_movk_i32 s5, 0x90
	v_and_b32_e32 v77, 16, v77
	v_mul_u32_u24_e32 v74, 0x90, v74
	v_add3_u32 v188, 0, v74, v77
	v_mul_lo_u32 v74, v75, s5
	v_add3_u32 v189, 0, v74, v0
	s_barrier
	v_mul_lo_u32 v78, v78, s5
	v_add3_u32 v187, 0, v78, v77
	s_waitcnt vmcnt(9)
	ds_write_b128 v189, v[10:13]
	ds_write_b128 v189, v[2:5] offset:4608
	ds_write_b128 v189, v[6:9] offset:9216
	s_waitcnt vmcnt(7)
	ds_write_b128 v189, v[18:21] offset:13824
	ds_write_b128 v189, v[14:17] offset:18432
	s_waitcnt vmcnt(6)
	ds_write_b128 v189, v[22:25] offset:23040
	s_waitcnt vmcnt(5)
	ds_write_b128 v189, v[26:29] offset:27648
	s_waitcnt vmcnt(4)
	ds_write_b128 v189, v[30:33] offset:32256
	s_waitcnt vmcnt(3)
	ds_write_b128 v189, v[34:37] offset:36864
	s_waitcnt vmcnt(2)
	ds_write_b128 v189, v[38:41] offset:41472
	s_waitcnt vmcnt(1)
	ds_write_b128 v189, v[42:45] offset:46080
	s_waitcnt vmcnt(0)
	ds_write_b128 v189, v[46:49] offset:50688
	global_load_dwordx4 v[134:137], v[54:55], off offset:128
	global_load_dwordx4 v[138:141], v[56:57], off offset:128
	global_load_dwordx4 v[130:133], v[50:51], off offset:128
	global_load_dwordx4 v[146:149], v[52:53], off offset:128
	global_load_dwordx4 v[142:145], v[58:59], off offset:128
	global_load_dwordx4 v[150:153], v[60:61], off offset:128
	global_load_dwordx4 v[154:157], v[62:63], off offset:128
	global_load_dwordx4 v[158:161], v[64:65], off offset:128
	global_load_dwordx4 v[162:165], v[66:67], off offset:128
	global_load_dwordx4 v[166:169], v[68:69], off offset:128
	global_load_dwordx4 v[170:173], v[70:71], off offset:128
	global_load_dwordx4 v[174:177], v[72:73], off offset:128
	v_mad_i64_i32 v[2:3], s[4:5], v75, s63, 0
	v_mad_i64_i32 v[4:5], s[4:5], s12, v250, v[2:3]
	s_add_i32 s4, s24, s13
	s_add_i32 s4, s4, s23
	v_mad_u64_u32 v[2:3], s[4:5], s4, v251, v[2:3]
	s_waitcnt lgkmcnt(0)
	s_barrier
; __device__ __forceinline__ void gemm_big(const bf16_t* __restrict__ A, long lda, const bf16_t* __restrict__ Bt, int K, f32x16 (&acc)[2][4], unsigned char* lds) {
;     ...
;     const bf16_t* ap = A + (long)lrow * lda + lc * 8;
;     const bf16_t* bp = Bt + (long)lrow * K + lc * 8;
	v_or_b32_e32 v2, v2, v0
	v_or_b32_e32 v4, v4, v0
	v_lshl_add_u64 v[184:185], s[0:1], 0, v[2:3]
	v_mov_b32_e32 v2, 0
	v_lshl_add_u64 v[182:183], s[0:1], 0, v[4:5]
	s_mov_b64 s[4:5], 0
	s_mov_b32 s13, 0
	v_mov_b32_e32 v3, v2
	v_mov_b32_e32 v4, v2
	v_mov_b32_e32 v5, v2
	v_mov_b32_e32 v6, v2
	v_mov_b32_e32 v7, v2
	v_mov_b32_e32 v8, v2
	v_mov_b32_e32 v9, v2
	v_mov_b32_e32 v10, v2
	v_mov_b32_e32 v11, v2
	v_mov_b32_e32 v12, v2
	v_mov_b32_e32 v13, v2
	v_mov_b32_e32 v14, v2
	v_mov_b32_e32 v15, v2
	v_mov_b32_e32 v16, v2
	v_mov_b32_e32 v17, v2
	v_mov_b32_e32 v66, v2
	v_mov_b32_e32 v67, v2
	v_mov_b32_e32 v68, v2
	v_mov_b32_e32 v69, v2
	v_mov_b32_e32 v70, v2
	v_mov_b32_e32 v71, v2
	v_mov_b32_e32 v72, v2
	v_mov_b32_e32 v73, v2
	v_mov_b32_e32 v74, v2
	v_mov_b32_e32 v75, v2
	v_mov_b32_e32 v76, v2
	v_mov_b32_e32 v77, v2
	v_mov_b32_e32 v78, v2
	v_mov_b32_e32 v79, v2
	v_mov_b32_e32 v80, v2
	v_mov_b32_e32 v81, v2
	v_mov_b32_e32 v18, v2
	v_mov_b32_e32 v19, v2
	v_mov_b32_e32 v20, v2
	v_mov_b32_e32 v21, v2
	v_mov_b32_e32 v22, v2
	v_mov_b32_e32 v23, v2
	v_mov_b32_e32 v24, v2
	v_mov_b32_e32 v25, v2
	v_mov_b32_e32 v26, v2
	v_mov_b32_e32 v27, v2
	v_mov_b32_e32 v28, v2
	v_mov_b32_e32 v29, v2
	v_mov_b32_e32 v30, v2
	v_mov_b32_e32 v31, v2
	v_mov_b32_e32 v32, v2
	v_mov_b32_e32 v33, v2
	v_mov_b32_e32 v82, v2
	v_mov_b32_e32 v83, v2
	v_mov_b32_e32 v84, v2
	v_mov_b32_e32 v85, v2
	v_mov_b32_e32 v86, v2
	v_mov_b32_e32 v87, v2
	v_mov_b32_e32 v88, v2
	v_mov_b32_e32 v89, v2
	v_mov_b32_e32 v90, v2
	v_mov_b32_e32 v91, v2
	v_mov_b32_e32 v92, v2
	v_mov_b32_e32 v93, v2
	v_mov_b32_e32 v94, v2
	v_mov_b32_e32 v95, v2
	v_mov_b32_e32 v96, v2
	v_mov_b32_e32 v97, v2
	v_mov_b32_e32 v34, v2
	v_mov_b32_e32 v35, v2
	v_mov_b32_e32 v36, v2
	v_mov_b32_e32 v37, v2
	v_mov_b32_e32 v38, v2
	v_mov_b32_e32 v39, v2
	v_mov_b32_e32 v40, v2
	v_mov_b32_e32 v41, v2
	v_mov_b32_e32 v42, v2
	v_mov_b32_e32 v43, v2
	v_mov_b32_e32 v44, v2
	v_mov_b32_e32 v45, v2
	v_mov_b32_e32 v46, v2
	v_mov_b32_e32 v47, v2
	v_mov_b32_e32 v48, v2
	v_mov_b32_e32 v49, v2
	v_mov_b32_e32 v98, v2
	v_mov_b32_e32 v99, v2
	v_mov_b32_e32 v100, v2
	v_mov_b32_e32 v101, v2
	v_mov_b32_e32 v102, v2
	v_mov_b32_e32 v103, v2
	v_mov_b32_e32 v104, v2
	v_mov_b32_e32 v105, v2
	v_mov_b32_e32 v106, v2
	v_mov_b32_e32 v107, v2
	v_mov_b32_e32 v108, v2
	v_mov_b32_e32 v109, v2
	v_mov_b32_e32 v110, v2
	v_mov_b32_e32 v111, v2
	v_mov_b32_e32 v112, v2
	v_mov_b32_e32 v113, v2
	v_mov_b32_e32 v50, v2
	v_mov_b32_e32 v51, v2
	v_mov_b32_e32 v52, v2
	v_mov_b32_e32 v53, v2
	v_mov_b32_e32 v54, v2
	v_mov_b32_e32 v55, v2
	v_mov_b32_e32 v56, v2
	v_mov_b32_e32 v57, v2
	v_mov_b32_e32 v58, v2
	v_mov_b32_e32 v59, v2
	v_mov_b32_e32 v60, v2
	v_mov_b32_e32 v61, v2
	v_mov_b32_e32 v62, v2
	v_mov_b32_e32 v63, v2
	v_mov_b32_e32 v64, v2
	v_mov_b32_e32 v65, v2
	v_mov_b32_e32 v114, v2
	v_mov_b32_e32 v115, v2
	v_mov_b32_e32 v116, v2
	v_mov_b32_e32 v117, v2
	v_mov_b32_e32 v118, v2
	v_mov_b32_e32 v119, v2
	v_mov_b32_e32 v120, v2
	v_mov_b32_e32 v121, v2
	v_mov_b32_e32 v122, v2
	v_mov_b32_e32 v123, v2
	v_mov_b32_e32 v124, v2
	v_mov_b32_e32 v125, v2
	v_mov_b32_e32 v126, v2
	v_mov_b32_e32 v127, v2
	v_mov_b32_e32 v128, v2
	v_mov_b32_e32 v129, v2
	s_setprio 0
	s_branch .LBB0_56

; __device__ __forceinline__ void lds_barrier() { asm volatile("s_waitcnt lgkmcnt(0)\n\ts_barrier" ::: "memory"); }
; __device__ __forceinline__ f32x16 mfma32(bf16x8 a, bf16x8 b, f32x16 c) { return __builtin_amdgcn_mfma_f32_32x32x16_bf16(a, b, c, 0, 0, 0); }
; __device__ __forceinline__ void gemm_big(const bf16_t* __restrict__ A, long lda, const bf16_t* __restrict__ Bt, int K, f32x16 (&acc)[2][4], unsigned char* lds) {
;     ...
;     for (int kc = 0; kc < nk; ++kc) {
;         bf16x8 af[2][2], bfr[2][4];
;         af[0][0] = *(const bf16x8*)(Ac); af[0][1] = *(const bf16x8*)(Ac + 32 * GLD);
; #pragma unroll
;         for (int ni = 0; ni < 4; ++ni) bfr[0][ni] = *(const bf16x8*)(Bc + ni * 32 * GLD);
;         __builtin_amdgcn_s_setprio(3);
; #pragma unroll
;         for (int ks = 0; ks < 4; ++ks) {
;             const int cb = ks & 1, nb = cb ^ 1;
;             if (ks < 3) {
;                 af[nb][0] = *(const bf16x8*)(Ac + (ks + 1) * 16); af[nb][1] = *(const bf16x8*)(Ac + 32 * GLD + (ks + 1) * 16);
; #pragma unroll
;                 for (int ni = 0; ni < 4; ++ni) bfr[nb][ni] = *(const bf16x8*)(Bc + ni * 32 * GLD + (ks + 1) * 16);
;             }
;             __builtin_amdgcn_sched_barrier(0);
; #pragma unroll
;             for (int ni = 0; ni < 4; ++ni) { acc[0][ni] = mfma32(af[cb][0], bfr[cb][ni], acc[0][ni]); acc[1][ni] = mfma32(af[cb][1], bfr[cb][ni], acc[1][ni]); }
;             __builtin_amdgcn_sched_barrier(0);
;         }
;         __builtin_amdgcn_s_setprio(0);
;         lds_barrier();
;         if (kc + 1 < nk) {
;             lstore();
;             if (kc + 2 < nk) gload(kc + 2);
;             lds_barrier();
;         }
.Lmy_gorig_8:
	ds_read_b128 v[190:193], v187
	ds_read_b128 v[194:197], v187 offset:4608
	ds_read_b128 v[198:201], v188 offset:18432
	ds_read_b128 v[202:205], v188 offset:23040
	ds_read_b128 v[206:209], v188 offset:27648
	ds_read_b128 v[210:213], v188 offset:32256
	ds_read_b128 v[214:217], v187 offset:32
	ds_read_b128 v[218:221], v187 offset:4640
	ds_read_b128 v[224:227], v188 offset:18464
	ds_read_b128 v[234:237], v188 offset:23072
	ds_read_b128 v[238:241], v188 offset:27680
	ds_read_b128 v[242:245], v188 offset:32288
	s_waitcnt lgkmcnt(9)
	v_mfma_f32_32x32x16_bf16 v[114:129], v[190:193], v[198:201], v[114:129]
	v_mfma_f32_32x32x16_bf16 v[50:65], v[194:197], v[198:201], v[50:65]
	s_waitcnt lgkmcnt(8)
	v_mfma_f32_32x32x16_bf16 v[98:113], v[190:193], v[202:205], v[98:113]
	v_mfma_f32_32x32x16_bf16 v[34:49], v[194:197], v[202:205], v[34:49]
	s_waitcnt lgkmcnt(7)
	v_mfma_f32_32x32x16_bf16 v[82:97], v[190:193], v[206:209], v[82:97]
	v_mfma_f32_32x32x16_bf16 v[18:33], v[194:197], v[206:209], v[18:33]
	s_waitcnt lgkmcnt(6)
	v_mfma_f32_32x32x16_bf16 v[66:81], v[190:193], v[210:213], v[66:81]
	v_mfma_f32_32x32x16_bf16 v[2:17], v[194:197], v[210:213], v[2:17]
	ds_read_b128 v[190:193], v187 offset:64
	ds_read_b128 v[194:197], v187 offset:4672
	ds_read_b128 v[198:201], v188 offset:18496
	ds_read_b128 v[202:205], v188 offset:23104
	ds_read_b128 v[206:209], v188 offset:27712
	ds_read_b128 v[210:213], v188 offset:32320
	s_waitcnt lgkmcnt(9)
	v_mfma_f32_32x32x16_bf16 v[114:129], v[214:217], v[224:227], v[114:129]
	v_mfma_f32_32x32x16_bf16 v[50:65], v[218:221], v[224:227], v[50:65]
	s_waitcnt lgkmcnt(8)
	v_mfma_f32_32x32x16_bf16 v[98:113], v[214:217], v[234:237], v[98:113]
	v_mfma_f32_32x32x16_bf16 v[34:49], v[218:221], v[234:237], v[34:49]
	s_waitcnt lgkmcnt(7)
	v_mfma_f32_32x32x16_bf16 v[82:97], v[214:217], v[238:241], v[82:97]
	v_mfma_f32_32x32x16_bf16 v[18:33], v[218:221], v[238:241], v[18:33]
	s_waitcnt lgkmcnt(6)
	v_mfma_f32_32x32x16_bf16 v[66:81], v[214:217], v[242:245], v[66:81]
	v_mfma_f32_32x32x16_bf16 v[2:17], v[218:221], v[242:245], v[2:17]
	ds_read_b128 v[214:217], v187 offset:96
	ds_read_b128 v[218:221], v187 offset:4704
	ds_read_b128 v[224:227], v188 offset:18528
	ds_read_b128 v[234:237], v188 offset:23136
	ds_read_b128 v[238:241], v188 offset:27744
	ds_read_b128 v[242:245], v188 offset:32352
	s_waitcnt lgkmcnt(9)
	v_mfma_f32_32x32x16_bf16 v[114:129], v[190:193], v[198:201], v[114:129]
	v_mfma_f32_32x32x16_bf16 v[50:65], v[194:197], v[198:201], v[50:65]
	s_waitcnt lgkmcnt(8)
	v_mfma_f32_32x32x16_bf16 v[98:113], v[190:193], v[202:205], v[98:113]
	v_mfma_f32_32x32x16_bf16 v[34:49], v[194:197], v[202:205], v[34:49]
	s_waitcnt lgkmcnt(7)
	v_mfma_f32_32x32x16_bf16 v[82:97], v[190:193], v[206:209], v[82:97]
	v_mfma_f32_32x32x16_bf16 v[18:33], v[194:197], v[206:209], v[18:33]
	s_waitcnt lgkmcnt(6)
	v_mfma_f32_32x32x16_bf16 v[66:81], v[190:193], v[210:213], v[66:81]
	v_mfma_f32_32x32x16_bf16 v[2:17], v[194:197], v[210:213], v[2:17]
	s_waitcnt lgkmcnt(3)
	v_mfma_f32_32x32x16_bf16 v[114:129], v[214:217], v[224:227], v[114:129]
	v_mfma_f32_32x32x16_bf16 v[50:65], v[218:221], v[224:227], v[50:65]
	s_waitcnt lgkmcnt(2)
	v_mfma_f32_32x32x16_bf16 v[98:113], v[214:217], v[234:237], v[98:113]
	v_mfma_f32_32x32x16_bf16 v[34:49], v[218:221], v[234:237], v[34:49]
	s_waitcnt lgkmcnt(1)
	v_mfma_f32_32x32x16_bf16 v[82:97], v[214:217], v[238:241], v[82:97]
	v_mfma_f32_32x32x16_bf16 v[18:33], v[218:221], v[238:241], v[18:33]
	s_waitcnt lgkmcnt(0)
	v_mfma_f32_32x32x16_bf16 v[66:81], v[214:217], v[242:245], v[66:81]
	v_mfma_f32_32x32x16_bf16 v[2:17], v[218:221], v[242:245], v[2:17]
	s_setprio 0
	s_waitcnt lgkmcnt(0)
	s_barrier
	s_cmp_gt_u32 s13, 42
	s_cbranch_scc1 .LBB0_55
	s_cmpk_eq_i32 s4, 0x1500
	s_waitcnt vmcnt(9)
	ds_write_b128 v189, v[130:133]
	ds_write_b128 v189, v[134:137] offset:4608
	ds_write_b128 v189, v[138:141] offset:9216
	s_waitcnt vmcnt(7)
	ds_write_b128 v189, v[142:145] offset:13824
	ds_write_b128 v189, v[146:149] offset:18432
	s_waitcnt vmcnt(6)
	ds_write_b128 v189, v[150:153] offset:23040
	s_waitcnt vmcnt(5)
	ds_write_b128 v189, v[154:157] offset:27648
	s_waitcnt vmcnt(4)
	ds_write_b128 v189, v[158:161] offset:32256
	s_waitcnt vmcnt(3)
	ds_write_b128 v189, v[162:165] offset:36864
	s_waitcnt vmcnt(2)
	ds_write_b128 v189, v[166:169] offset:41472
	s_waitcnt vmcnt(1)
	ds_write_b128 v189, v[170:173] offset:46080
	s_waitcnt vmcnt(0)
	ds_write_b128 v189, v[174:177] offset:50688
	s_cbranch_scc1 .LBB0_54
	v_lshl_add_u64 v[138:139], v[184:185], 0, s[4:5]
	v_add_co_u32_e32 v130, vcc, 0x78a8000, v138
	v_lshl_add_u64 v[170:171], v[182:183], 0, s[4:5]
	s_nop 0
	v_addc_co_u32_e32 v131, vcc, 0, v139, vcc
	v_add_co_u32_e32 v134, vcc, 0x78d4000, v138
	s_nop 1
	v_addc_co_u32_e32 v135, vcc, 0, v139, vcc
	v_add_co_u32_e32 v140, vcc, 0x7900000, v138
	global_load_dwordx4 v[130:133], v[130:131], off offset:256
	s_nop 0
	global_load_dwordx4 v[134:137], v[134:135], off offset:256
	v_addc_co_u32_e32 v141, vcc, 0, v139, vcc
	v_add_co_u32_e32 v142, vcc, 0x792c000, v138
	s_nop 1
	v_addc_co_u32_e32 v143, vcc, 0, v139, vcc
	v_add_co_u32_e32 v146, vcc, 0x3328000, v170
	global_load_dwordx4 v[138:141], v[140:141], off offset:256
	s_nop 0
	global_load_dwordx4 v[142:145], v[142:143], off offset:256
	v_addc_co_u32_e32 v147, vcc, 0, v171, vcc
	v_add_co_u32_e32 v150, vcc, 0x3354000, v170
	s_nop 1
	v_addc_co_u32_e32 v151, vcc, 0, v171, vcc
	v_add_co_u32_e32 v154, vcc, 0x3380000, v170
	global_load_dwordx4 v[146:149], v[146:147], off offset:256
	s_nop 0
	global_load_dwordx4 v[150:153], v[150:151], off offset:256
	v_addc_co_u32_e32 v155, vcc, 0, v171, vcc
	v_add_co_u32_e32 v158, vcc, 0x33ac000, v170
	s_nop 1
	v_addc_co_u32_e32 v159, vcc, 0, v171, vcc
	v_add_co_u32_e32 v162, vcc, 0x33d8000, v170
	global_load_dwordx4 v[154:157], v[154:155], off offset:256
	s_nop 0
	global_load_dwordx4 v[158:161], v[158:159], off offset:256
	v_addc_co_u32_e32 v163, vcc, 0, v171, vcc
	v_add_co_u32_e32 v166, vcc, 0x3404000, v170
	s_nop 1
	v_addc_co_u32_e32 v167, vcc, 0, v171, vcc
	v_add_co_u32_e32 v172, vcc, 0x3430000, v170
	global_load_dwordx4 v[162:165], v[162:163], off offset:256
	s_nop 0
	global_load_dwordx4 v[166:169], v[166:167], off offset:256
	v_addc_co_u32_e32 v173, vcc, 0, v171, vcc
	v_add_co_u32_e32 v174, vcc, 0x345c000, v170
	s_nop 1
	v_addc_co_u32_e32 v175, vcc, 0, v171, vcc
	global_load_dwordx4 v[170:173], v[172:173], off offset:256
	s_nop 0
	global_load_dwordx4 v[174:177], v[174:175], off offset:256
	s_branch .LBB0_54

; __device__ __forceinline__ void lds_barrier() { asm volatile("s_waitcnt lgkmcnt(0)\n\ts_barrier" ::: "memory"); }
; __device__ __forceinline__ void gemm_big(const bf16_t* __restrict__ A, long lda, const bf16_t* __restrict__ Bt, int K, f32x16 (&acc)[2][4], unsigned char* lds) {
;     ...
;     const bf16_t* ap = A + (long)lrow * lda + lc * 8;
;     const bf16_t* bp = Bt + (long)lrow * K + lc * 8;
;     u32x4 ra[4], rb[8];
;     auto gload = [&](int kc) {
; #pragma unroll
;         for (int i = 0; i < 4; ++i) ra[i] = *(const u32x4*)(ap + (long)(32 * i) * lda + kc * 64);
; #pragma unroll
;         for (int i = 0; i < 8; ++i) rb[i] = *(const u32x4*)(bp + (long)(32 * i) * K + kc * 64);
;     };
;     auto lstore = [&]() {
; #pragma unroll
;         for (int i = 0; i < 4; ++i) *(u32x4*)(As + (lrow + 32 * i) * GLD + lc * 8) = ra[i];
; #pragma unroll
;         for (int i = 0; i < 8; ++i) *(u32x4*)(Bs + (lrow + 32 * i) * GLD + lc * 8) = rb[i];
;     };
;     const bf16_t* Ac = As + (wr * 64 + r) * GLD + h * 8;
;     const bf16_t* Bc = Bs + (wc * 128 + r) * GLD + h * 8;
;     gload(0);
;     __syncthreads();
;     lstore();
;     if (nk > 1) gload(1);
;     lds_barrier();
; __device__ __forceinline__ bool tile_at(int k, int NPM, int NPN, int& pm, int& pn) {
;     const int nb = gridDim.x >> 3, x = blockIdx.x & 7, jb = blockIdx.x >> 3;
;     const int t = jb + k * nb, perx = (NPM >> 3) * NPN;
;     if (t >= perx) return false;
;     const int pmg = t / (8 * NPN), rem = t - pmg * 8 * NPN;
;     pn = rem >> 3; pm = x * (NPM >> 3) + pmg * 8 + (rem & 7);
.LBB0_64:
	s_mul_hi_u32 s5, s4, 0xba2e8ba3
	s_lshr_b32 s5, s5, 7
	s_and_b32 s23, s4, 7
	v_readlane_b32 s27, v252, 2
	s_mul_i32 s6, s5, 0xffffff50
	s_or_b32 s13, s23, s27
	s_lshl_b32 s26, s5, 3
	s_add_i32 s6, s6, s4
	s_add_i32 s13, s13, s26
	v_mov_b32_e32 v78, v179
	s_ashr_i32 s4, s6, 3
	s_lshl_b32 s5, s13, 18
	s_add_u32 s14, s9, s5
	s_waitcnt vmcnt(27)
	v_ashrrev_i32_e32 v50, 3, v78
	s_waitcnt vmcnt(26)
	v_ashrrev_i32_e32 v51, 31, v50
	s_addc_u32 s15, s10, 0
	s_waitcnt vmcnt(24)
	v_lshlrev_b64 v[52:53], 11, v[50:51]
	v_lshlrev_b32_e32 v0, 4, v78
	v_lshl_add_u64 v[2:3], s[14:15], 0, v[52:53]
	v_and_b32_e32 v0, 0x70, v0
	v_lshl_add_u64 v[54:55], v[2:3], 0, v[0:1]
	s_ashr_i32 s5, s4, 31
	v_add_co_u32_e32 v58, vcc, s67, v54
	s_lshl_b64 s[6:7], s[4:5], 19
	s_nop 0
	v_addc_co_u32_e32 v59, vcc, 0, v55, vcc
	s_mov_b32 s5, 0x20000
	s_add_u32 s24, s3, s6
	v_add_co_u32_e32 v60, vcc, s5, v54
	s_addc_u32 s25, s8, s7
	s_nop 0
	v_addc_co_u32_e32 v61, vcc, 0, v55, vcc
	s_mov_b32 s14, 0x30000
	v_lshl_add_u64 v[2:3], s[24:25], 0, v[52:53]
	s_waitcnt vmcnt(23)
	v_add_co_u32_e32 v62, vcc, s14, v54
	v_lshl_add_u64 v[56:57], v[2:3], 0, v[0:1]
	s_waitcnt vmcnt(22)
	v_addc_co_u32_e32 v63, vcc, 0, v55, vcc
	s_waitcnt vmcnt(21)
	v_add_co_u32_e32 v64, vcc, s67, v56
	s_setprio 3
	global_load_dwordx4 v[2:5], v[58:59], off
	global_load_dwordx4 v[6:9], v[60:61], off
	s_waitcnt vmcnt(22)
	v_addc_co_u32_e32 v65, vcc, 0, v57, vcc
	s_waitcnt vmcnt(21)
	v_add_co_u32_e32 v66, vcc, s5, v56
	s_mov_b32 s5, 0x40000
	s_waitcnt vmcnt(20)
	v_addc_co_u32_e32 v67, vcc, 0, v57, vcc
	s_waitcnt vmcnt(19)
	v_add_co_u32_e32 v68, vcc, s14, v56
	global_load_dwordx4 v[10:13], v[54:55], off
	global_load_dwordx4 v[14:17], v[56:57], off
	s_waitcnt vmcnt(20)
	v_addc_co_u32_e32 v69, vcc, 0, v57, vcc
	v_add_co_u32_e32 v70, vcc, s5, v56
	s_mov_b32 s5, 0x50000
	s_nop 0
	v_addc_co_u32_e32 v71, vcc, 0, v57, vcc
	v_add_co_u32_e32 v72, vcc, s5, v56
	s_mov_b32 s5, 0x60000
	s_nop 0
	v_addc_co_u32_e32 v73, vcc, 0, v57, vcc
	v_add_co_u32_e32 v74, vcc, s5, v56
	s_mov_b32 s5, 0x70000
	s_nop 0
	v_addc_co_u32_e32 v75, vcc, 0, v57, vcc
	v_add_co_u32_e32 v76, vcc, s5, v56
	global_load_dwordx4 v[18:21], v[62:63], off
	global_load_dwordx4 v[22:25], v[64:65], off
	global_load_dwordx4 v[26:29], v[66:67], off
	global_load_dwordx4 v[30:33], v[68:69], off
	global_load_dwordx4 v[34:37], v[70:71], off
	global_load_dwordx4 v[38:41], v[72:73], off
	v_addc_co_u32_e32 v77, vcc, 0, v57, vcc
	global_load_dwordx4 v[42:45], v[74:75], off
	global_load_dwordx4 v[46:49], v[76:77], off
	s_movk_i32 s14, 0x90
	v_mul_lo_u32 v50, v50, s14
	v_add3_u32 v189, 0, v50, v0
	s_barrier
	v_and_b32_e32 v51, 31, v78
	v_lshrrev_b32_e32 v79, 1, v78
	s_mov_b32 s5, 0xfffffc0
	v_and_or_b32 v80, v79, s5, v51
	v_lshlrev_b32_e32 v78, 1, v78
	s_movk_i32 s5, 0x80
	v_and_or_b32 v51, v78, s5, v51
	s_add_i32 s5, s27, s26
	s_add_i32 s5, s5, s23
	s_lshl_b32 s5, s5, 18
	v_mul_lo_u32 v80, v80, s14
	v_and_b32_e32 v79, 16, v79
	v_mul_u32_u24_e32 v51, 0x90, v51
	v_add3_u32 v187, 0, v80, v79
	v_add3_u32 v188, 0, v51, v79
	s_waitcnt vmcnt(9)
	ds_write_b128 v189, v[10:13]
	ds_write_b128 v189, v[2:5] offset:4608
	ds_write_b128 v189, v[6:9] offset:9216
	s_waitcnt vmcnt(7)
	ds_write_b128 v189, v[18:21] offset:13824
	ds_write_b128 v189, v[14:17] offset:18432
	s_waitcnt vmcnt(6)
	ds_write_b128 v189, v[22:25] offset:23040
	s_waitcnt vmcnt(5)
	ds_write_b128 v189, v[26:29] offset:27648
	s_waitcnt vmcnt(4)
	ds_write_b128 v189, v[30:33] offset:32256
	s_waitcnt vmcnt(3)
	ds_write_b128 v189, v[34:37] offset:36864
	s_waitcnt vmcnt(2)
	ds_write_b128 v189, v[38:41] offset:41472
	s_waitcnt vmcnt(1)
	ds_write_b128 v189, v[42:45] offset:46080
	s_waitcnt vmcnt(0)
	ds_write_b128 v189, v[46:49] offset:50688
	global_load_dwordx4 v[134:137], v[58:59], off offset:128
	global_load_dwordx4 v[138:141], v[60:61], off offset:128
	global_load_dwordx4 v[130:133], v[54:55], off offset:128
	global_load_dwordx4 v[146:149], v[56:57], off offset:128
	global_load_dwordx4 v[142:145], v[62:63], off offset:128
	global_load_dwordx4 v[150:153], v[64:65], off offset:128
	global_load_dwordx4 v[154:157], v[66:67], off offset:128
	global_load_dwordx4 v[158:161], v[68:69], off offset:128
	global_load_dwordx4 v[162:165], v[70:71], off offset:128
	global_load_dwordx4 v[166:169], v[72:73], off offset:128
	global_load_dwordx4 v[170:173], v[74:75], off offset:128
	global_load_dwordx4 v[174:177], v[76:77], off offset:128
	v_lshl_add_u64 v[2:3], s[6:7], 0, v[52:53]
	s_waitcnt lgkmcnt(0)
	s_barrier
; __device__ __forceinline__ void gemm_big(const bf16_t* __restrict__ A, long lda, const bf16_t* __restrict__ Bt, int K, f32x16 (&acc)[2][4], unsigned char* lds) {
;     ...
;     const bf16_t* ap = A + (long)lrow * lda + lc * 8;
;     const bf16_t* bp = Bt + (long)lrow * K + lc * 8;
	v_or_b32_e32 v2, v2, v0
	s_add_u32 s6, s0, s5
	v_lshl_add_u64 v[182:183], s[0:1], 0, v[2:3]
	v_or_b32_e32 v52, v52, v0
	s_addc_u32 s7, s1, 0
	v_mov_b32_e32 v2, 0
	v_lshl_add_u64 v[184:185], s[6:7], 0, v[52:53]
	s_mov_b64 s[6:7], 0
	s_mov_b32 s5, 0
	v_mov_b32_e32 v3, v2
	v_mov_b32_e32 v4, v2
	v_mov_b32_e32 v5, v2
	v_mov_b32_e32 v6, v2
	v_mov_b32_e32 v7, v2
	v_mov_b32_e32 v8, v2
	v_mov_b32_e32 v9, v2
	v_mov_b32_e32 v10, v2
	v_mov_b32_e32 v11, v2
	v_mov_b32_e32 v12, v2
	v_mov_b32_e32 v13, v2
	v_mov_b32_e32 v14, v2
	v_mov_b32_e32 v15, v2
	v_mov_b32_e32 v16, v2
	v_mov_b32_e32 v17, v2
	v_mov_b32_e32 v34, v2
	v_mov_b32_e32 v35, v2
	v_mov_b32_e32 v36, v2
	v_mov_b32_e32 v37, v2
	v_mov_b32_e32 v38, v2
	v_mov_b32_e32 v39, v2
	v_mov_b32_e32 v40, v2
	v_mov_b32_e32 v41, v2
	v_mov_b32_e32 v42, v2
	v_mov_b32_e32 v43, v2
	v_mov_b32_e32 v44, v2
	v_mov_b32_e32 v45, v2
	v_mov_b32_e32 v46, v2
	v_mov_b32_e32 v47, v2
	v_mov_b32_e32 v48, v2
	v_mov_b32_e32 v49, v2
	v_mov_b32_e32 v18, v2
	v_mov_b32_e32 v19, v2
	v_mov_b32_e32 v20, v2
	v_mov_b32_e32 v21, v2
	v_mov_b32_e32 v22, v2
	v_mov_b32_e32 v23, v2
	v_mov_b32_e32 v24, v2
	v_mov_b32_e32 v25, v2
	v_mov_b32_e32 v26, v2
	v_mov_b32_e32 v27, v2
	v_mov_b32_e32 v28, v2
	v_mov_b32_e32 v29, v2
	v_mov_b32_e32 v30, v2
	v_mov_b32_e32 v31, v2
	v_mov_b32_e32 v32, v2
	v_mov_b32_e32 v33, v2
	v_mov_b32_e32 v50, v2
	v_mov_b32_e32 v51, v2
	v_mov_b32_e32 v52, v2
	v_mov_b32_e32 v53, v2
	v_mov_b32_e32 v54, v2
	v_mov_b32_e32 v55, v2
	v_mov_b32_e32 v56, v2
	v_mov_b32_e32 v57, v2
	v_mov_b32_e32 v58, v2
	v_mov_b32_e32 v59, v2
	v_mov_b32_e32 v60, v2
	v_mov_b32_e32 v61, v2
	v_mov_b32_e32 v62, v2
	v_mov_b32_e32 v63, v2
	v_mov_b32_e32 v64, v2
	v_mov_b32_e32 v65, v2
	v_mov_b32_e32 v66, v2
	v_mov_b32_e32 v67, v2
	v_mov_b32_e32 v68, v2
	v_mov_b32_e32 v69, v2
	v_mov_b32_e32 v70, v2
	v_mov_b32_e32 v71, v2
	v_mov_b32_e32 v72, v2
	v_mov_b32_e32 v73, v2
	v_mov_b32_e32 v74, v2
	v_mov_b32_e32 v75, v2
	v_mov_b32_e32 v76, v2
	v_mov_b32_e32 v77, v2
	v_mov_b32_e32 v78, v2
	v_mov_b32_e32 v79, v2
	v_mov_b32_e32 v80, v2
	v_mov_b32_e32 v81, v2
	v_mov_b32_e32 v98, v2
	v_mov_b32_e32 v99, v2
	v_mov_b32_e32 v100, v2
	v_mov_b32_e32 v101, v2
	v_mov_b32_e32 v102, v2
	v_mov_b32_e32 v103, v2
	v_mov_b32_e32 v104, v2
	v_mov_b32_e32 v105, v2
	v_mov_b32_e32 v106, v2
	v_mov_b32_e32 v107, v2
	v_mov_b32_e32 v108, v2
	v_mov_b32_e32 v109, v2
	v_mov_b32_e32 v110, v2
	v_mov_b32_e32 v111, v2
	v_mov_b32_e32 v112, v2
	v_mov_b32_e32 v113, v2
	v_mov_b32_e32 v82, v2
	v_mov_b32_e32 v83, v2
	v_mov_b32_e32 v84, v2
	v_mov_b32_e32 v85, v2
	v_mov_b32_e32 v86, v2
	v_mov_b32_e32 v87, v2
	v_mov_b32_e32 v88, v2
	v_mov_b32_e32 v89, v2
	v_mov_b32_e32 v90, v2
	v_mov_b32_e32 v91, v2
	v_mov_b32_e32 v92, v2
	v_mov_b32_e32 v93, v2
	v_mov_b32_e32 v94, v2
	v_mov_b32_e32 v95, v2
	v_mov_b32_e32 v96, v2
	v_mov_b32_e32 v97, v2
	v_mov_b32_e32 v114, v2
	v_mov_b32_e32 v115, v2
	v_mov_b32_e32 v116, v2
	v_mov_b32_e32 v117, v2
	v_mov_b32_e32 v118, v2
	v_mov_b32_e32 v119, v2
	v_mov_b32_e32 v120, v2
	v_mov_b32_e32 v121, v2
	v_mov_b32_e32 v122, v2
	v_mov_b32_e32 v123, v2
	v_mov_b32_e32 v124, v2
	v_mov_b32_e32 v125, v2
	v_mov_b32_e32 v126, v2
	v_mov_b32_e32 v127, v2
	v_mov_b32_e32 v128, v2
	v_mov_b32_e32 v129, v2
	s_setprio 0
	s_branch .LBB0_67

; __device__ __forceinline__ void lds_barrier() { asm volatile("s_waitcnt lgkmcnt(0)\n\ts_barrier" ::: "memory"); }
; __device__ __forceinline__ f32x16 mfma32(bf16x8 a, bf16x8 b, f32x16 c) { return __builtin_amdgcn_mfma_f32_32x32x16_bf16(a, b, c, 0, 0, 0); }
; __device__ __forceinline__ void gemm_big(const bf16_t* __restrict__ A, long lda, const bf16_t* __restrict__ Bt, int K, f32x16 (&acc)[2][4], unsigned char* lds) {
;     ...
;     for (int kc = 0; kc < nk; ++kc) {
;         bf16x8 af[2][2], bfr[2][4];
;         af[0][0] = *(const bf16x8*)(Ac); af[0][1] = *(const bf16x8*)(Ac + 32 * GLD);
; #pragma unroll
;         for (int ni = 0; ni < 4; ++ni) bfr[0][ni] = *(const bf16x8*)(Bc + ni * 32 * GLD);
;         __builtin_amdgcn_s_setprio(3);
; #pragma unroll
;         for (int ks = 0; ks < 4; ++ks) {
;             const int cb = ks & 1, nb = cb ^ 1;
;             if (ks < 3) {
;                 af[nb][0] = *(const bf16x8*)(Ac + (ks + 1) * 16); af[nb][1] = *(const bf16x8*)(Ac + 32 * GLD + (ks + 1) * 16);
; #pragma unroll
;                 for (int ni = 0; ni < 4; ++ni) bfr[nb][ni] = *(const bf16x8*)(Bc + ni * 32 * GLD + (ks + 1) * 16);
;             }
;             __builtin_amdgcn_sched_barrier(0);
; #pragma unroll
;             for (int ni = 0; ni < 4; ++ni) { acc[0][ni] = mfma32(af[cb][0], bfr[cb][ni], acc[0][ni]); acc[1][ni] = mfma32(af[cb][1], bfr[cb][ni], acc[1][ni]); }
;             __builtin_amdgcn_sched_barrier(0);
;         }
;         __builtin_amdgcn_s_setprio(0);
;         lds_barrier();
;         if (kc + 1 < nk) {
;             lstore();
;             if (kc + 2 < nk) gload(kc + 2);
;             lds_barrier();
;         }
.Lmy_gorig_7:
	ds_read_b128 v[190:193], v187
	ds_read_b128 v[194:197], v187 offset:4608
	ds_read_b128 v[198:201], v188 offset:18432
	ds_read_b128 v[202:205], v188 offset:23040
	ds_read_b128 v[206:209], v188 offset:27648
	ds_read_b128 v[210:213], v188 offset:32256
	ds_read_b128 v[214:217], v187 offset:32
	ds_read_b128 v[218:221], v187 offset:4640
	ds_read_b128 v[224:227], v188 offset:18464
	ds_read_b128 v[234:237], v188 offset:23072
	ds_read_b128 v[238:241], v188 offset:27680
	ds_read_b128 v[242:245], v188 offset:32288
	s_waitcnt lgkmcnt(9)
	v_mfma_f32_32x32x16_bf16 v[114:129], v[190:193], v[198:201], v[114:129]
	v_mfma_f32_32x32x16_bf16 v[82:97], v[194:197], v[198:201], v[82:97]
	s_waitcnt lgkmcnt(8)
	v_mfma_f32_32x32x16_bf16 v[98:113], v[190:193], v[202:205], v[98:113]
	v_mfma_f32_32x32x16_bf16 v[66:81], v[194:197], v[202:205], v[66:81]
	s_waitcnt lgkmcnt(7)
	v_mfma_f32_32x32x16_bf16 v[50:65], v[190:193], v[206:209], v[50:65]
	v_mfma_f32_32x32x16_bf16 v[18:33], v[194:197], v[206:209], v[18:33]
	s_waitcnt lgkmcnt(6)
	v_mfma_f32_32x32x16_bf16 v[34:49], v[190:193], v[210:213], v[34:49]
	v_mfma_f32_32x32x16_bf16 v[2:17], v[194:197], v[210:213], v[2:17]
	ds_read_b128 v[190:193], v187 offset:64
	ds_read_b128 v[194:197], v187 offset:4672
	ds_read_b128 v[198:201], v188 offset:18496
	ds_read_b128 v[202:205], v188 offset:23104
	ds_read_b128 v[206:209], v188 offset:27712
	ds_read_b128 v[210:213], v188 offset:32320
	s_waitcnt lgkmcnt(9)
	v_mfma_f32_32x32x16_bf16 v[114:129], v[214:217], v[224:227], v[114:129]
	v_mfma_f32_32x32x16_bf16 v[82:97], v[218:221], v[224:227], v[82:97]
	s_waitcnt lgkmcnt(8)
	v_mfma_f32_32x32x16_bf16 v[98:113], v[214:217], v[234:237], v[98:113]
	v_mfma_f32_32x32x16_bf16 v[66:81], v[218:221], v[234:237], v[66:81]
	s_waitcnt lgkmcnt(7)
	v_mfma_f32_32x32x16_bf16 v[50:65], v[214:217], v[238:241], v[50:65]
	v_mfma_f32_32x32x16_bf16 v[18:33], v[218:221], v[238:241], v[18:33]
	s_waitcnt lgkmcnt(6)
	v_mfma_f32_32x32x16_bf16 v[34:49], v[214:217], v[242:245], v[34:49]
	v_mfma_f32_32x32x16_bf16 v[2:17], v[218:221], v[242:245], v[2:17]
	ds_read_b128 v[214:217], v187 offset:96
	ds_read_b128 v[218:221], v187 offset:4704
	ds_read_b128 v[224:227], v188 offset:18528
	ds_read_b128 v[234:237], v188 offset:23136
	ds_read_b128 v[238:241], v188 offset:27744
	ds_read_b128 v[242:245], v188 offset:32352
	s_waitcnt lgkmcnt(9)
	v_mfma_f32_32x32x16_bf16 v[114:129], v[190:193], v[198:201], v[114:129]
	v_mfma_f32_32x32x16_bf16 v[82:97], v[194:197], v[198:201], v[82:97]
	s_waitcnt lgkmcnt(8)
	v_mfma_f32_32x32x16_bf16 v[98:113], v[190:193], v[202:205], v[98:113]
	v_mfma_f32_32x32x16_bf16 v[66:81], v[194:197], v[202:205], v[66:81]
	s_waitcnt lgkmcnt(7)
	v_mfma_f32_32x32x16_bf16 v[50:65], v[190:193], v[206:209], v[50:65]
	v_mfma_f32_32x32x16_bf16 v[18:33], v[194:197], v[206:209], v[18:33]
	s_waitcnt lgkmcnt(6)
	v_mfma_f32_32x32x16_bf16 v[34:49], v[190:193], v[210:213], v[34:49]
	v_mfma_f32_32x32x16_bf16 v[2:17], v[194:197], v[210:213], v[2:17]
	s_waitcnt lgkmcnt(3)
	v_mfma_f32_32x32x16_bf16 v[114:129], v[214:217], v[224:227], v[114:129]
	v_mfma_f32_32x32x16_bf16 v[82:97], v[218:221], v[224:227], v[82:97]
	s_waitcnt lgkmcnt(2)
	v_mfma_f32_32x32x16_bf16 v[98:113], v[214:217], v[234:237], v[98:113]
	v_mfma_f32_32x32x16_bf16 v[66:81], v[218:221], v[234:237], v[66:81]
	s_waitcnt lgkmcnt(1)
	v_mfma_f32_32x32x16_bf16 v[50:65], v[214:217], v[238:241], v[50:65]
	v_mfma_f32_32x32x16_bf16 v[18:33], v[218:221], v[238:241], v[18:33]
	s_waitcnt lgkmcnt(0)
	v_mfma_f32_32x32x16_bf16 v[34:49], v[214:217], v[242:245], v[34:49]
	v_mfma_f32_32x32x16_bf16 v[2:17], v[218:221], v[242:245], v[2:17]
	s_setprio 0
	s_waitcnt lgkmcnt(0)
	s_barrier
	s_cmp_gt_u32 s5, 14
	s_cbranch_scc1 .LBB0_66
	s_cmpk_eq_i32 s6, 0x700
	s_waitcnt vmcnt(9)
	ds_write_b128 v189, v[130:133]
	ds_write_b128 v189, v[134:137] offset:4608
	ds_write_b128 v189, v[138:141] offset:9216
	s_waitcnt vmcnt(7)
	ds_write_b128 v189, v[142:145] offset:13824
	ds_write_b128 v189, v[146:149] offset:18432
	s_waitcnt vmcnt(6)
	ds_write_b128 v189, v[150:153] offset:23040
	s_waitcnt vmcnt(5)
	ds_write_b128 v189, v[154:157] offset:27648
	s_waitcnt vmcnt(4)
	ds_write_b128 v189, v[158:161] offset:32256
	s_waitcnt vmcnt(3)
	ds_write_b128 v189, v[162:165] offset:36864
	s_waitcnt vmcnt(2)
	ds_write_b128 v189, v[166:169] offset:41472
	s_waitcnt vmcnt(1)
	ds_write_b128 v189, v[170:173] offset:46080
	s_waitcnt vmcnt(0)
	ds_write_b128 v189, v[174:177] offset:50688
	s_cbranch_scc1 .LBB0_65
	v_lshl_add_u64 v[138:139], v[184:185], 0, s[6:7]
	v_add_co_u32_e32 v130, vcc, 0x38a8000, v138
	v_lshl_add_u64 v[170:171], v[182:183], 0, s[6:7]
	s_nop 0
	v_addc_co_u32_e32 v131, vcc, 0, v139, vcc
	v_add_co_u32_e32 v134, vcc, 0x38b8000, v138
	s_nop 1
	v_addc_co_u32_e32 v135, vcc, 0, v139, vcc
	v_add_co_u32_e32 v140, vcc, 0x38c8000, v138
	global_load_dwordx4 v[130:133], v[130:131], off offset:256
	s_nop 0
	global_load_dwordx4 v[134:137], v[134:135], off offset:256
	v_addc_co_u32_e32 v141, vcc, 0, v139, vcc
	v_add_co_u32_e32 v142, vcc, 0x38d8000, v138
	s_nop 1
	v_addc_co_u32_e32 v143, vcc, 0, v139, vcc
	v_add_co_u32_e32 v146, vcc, 0x2828000, v170
	global_load_dwordx4 v[138:141], v[140:141], off offset:256
	s_nop 0
	global_load_dwordx4 v[142:145], v[142:143], off offset:256
	v_addc_co_u32_e32 v147, vcc, 0, v171, vcc
	v_add_co_u32_e32 v150, vcc, 0x2838000, v170
	s_nop 1
	v_addc_co_u32_e32 v151, vcc, 0, v171, vcc
	v_add_co_u32_e32 v154, vcc, 0x2848000, v170
	global_load_dwordx4 v[146:149], v[146:147], off offset:256
	s_nop 0
	global_load_dwordx4 v[150:153], v[150:151], off offset:256
	v_addc_co_u32_e32 v155, vcc, 0, v171, vcc
	v_add_co_u32_e32 v158, vcc, 0x2858000, v170
	s_nop 1
	v_addc_co_u32_e32 v159, vcc, 0, v171, vcc
	v_add_co_u32_e32 v162, vcc, 0x2868000, v170
	global_load_dwordx4 v[154:157], v[154:155], off offset:256
	s_nop 0
	global_load_dwordx4 v[158:161], v[158:159], off offset:256
	v_addc_co_u32_e32 v163, vcc, 0, v171, vcc
	v_add_co_u32_e32 v166, vcc, 0x2878000, v170
	s_nop 1
	v_addc_co_u32_e32 v167, vcc, 0, v171, vcc
	v_add_co_u32_e32 v172, vcc, 0x2888000, v170
	global_load_dwordx4 v[162:165], v[162:163], off offset:256
	s_nop 0
	global_load_dwordx4 v[166:169], v[166:167], off offset:256
	v_addc_co_u32_e32 v173, vcc, 0, v171, vcc
	v_add_co_u32_e32 v174, vcc, 0x2898000, v170
	s_nop 1
	v_addc_co_u32_e32 v175, vcc, 0, v171, vcc
	global_load_dwordx4 v[170:173], v[172:173], off offset:256
	s_nop 0
	global_load_dwordx4 v[174:177], v[174:175], off offset:256
	s_branch .LBB0_65

; __device__ __forceinline__ void lds_barrier() { asm volatile("s_waitcnt lgkmcnt(0)\n\ts_barrier" ::: "memory"); }
; __device__ __forceinline__ void gemm_big(const bf16_t* __restrict__ A, long lda, const bf16_t* __restrict__ Bt, int K, f32x16 (&acc)[2][4], unsigned char* lds) {
;     ...
;     const bf16_t* ap = A + (long)lrow * lda + lc * 8;
;     const bf16_t* bp = Bt + (long)lrow * K + lc * 8;
;     u32x4 ra[4], rb[8];
;     auto gload = [&](int kc) {
; #pragma unroll
;         for (int i = 0; i < 4; ++i) ra[i] = *(const u32x4*)(ap + (long)(32 * i) * lda + kc * 64);
; #pragma unroll
;         for (int i = 0; i < 8; ++i) rb[i] = *(const u32x4*)(bp + (long)(32 * i) * K + kc * 64);
;     };
;     auto lstore = [&]() {
; #pragma unroll
;         for (int i = 0; i < 4; ++i) *(u32x4*)(As + (lrow + 32 * i) * GLD + lc * 8) = ra[i];
; #pragma unroll
;         for (int i = 0; i < 8; ++i) *(u32x4*)(Bs + (lrow + 32 * i) * GLD + lc * 8) = rb[i];
;     };
;     const bf16_t* Ac = As + (wr * 64 + r) * GLD + h * 8;
;     const bf16_t* Bc = Bs + (wc * 128 + r) * GLD + h * 8;
;     gload(0);
;     __syncthreads();
;     lstore();
;     if (nk > 1) gload(1);
;     lds_barrier();
; __device__ __forceinline__ bool tile_at(int k, int NPM, int NPN, int& pm, int& pn) {
;     const int nb = gridDim.x >> 3, x = blockIdx.x & 7, jb = blockIdx.x >> 3;
;     const int t = jb + k * nb, perx = (NPM >> 3) * NPN;
;     if (t >= perx) return false;
;     const int pmg = t / (8 * NPN), rem = t - pmg * 8 * NPN;
;     pn = rem >> 3; pm = x * (NPM >> 3) + pmg * 8 + (rem & 7);
.LBB0_81:
	s_lshr_b32 s5, s4, 2
	s_and_b32 s13, s5, 0x7fffff8
	s_and_b32 s23, s4, 7
	v_readlane_b32 s26, v252, 8
	s_lshl_b32 s5, s13, 2
	s_or_b32 s6, s23, s26
	s_sub_i32 s5, s4, s5
	s_add_i32 s88, s6, s13
	v_mov_b32_e32 v78, v179
	s_ashr_i32 s4, s5, 3
	s_lshl_b64 s[6:7], s[88:89], 18
	s_add_u32 s14, s8, s6
	v_ashrrev_i32_e32 v50, 3, v78
	v_ashrrev_i32_e32 v51, 31, v50
	s_addc_u32 s15, s9, s7
	v_lshlrev_b64 v[52:53], 11, v[50:51]
	v_lshlrev_b32_e32 v0, 4, v78
	v_lshl_add_u64 v[2:3], s[14:15], 0, v[52:53]
	v_and_b32_e32 v0, 0x70, v0
	v_lshl_add_u64 v[54:55], v[2:3], 0, v[0:1]
	s_ashr_i32 s5, s4, 31
	v_add_co_u32_e32 v58, vcc, s67, v54
	s_lshl_b64 s[6:7], s[4:5], 19
	s_nop 0
	v_addc_co_u32_e32 v59, vcc, 0, v55, vcc
	s_mov_b32 s5, 0x20000
	s_add_u32 s24, s10, s6
	v_add_co_u32_e32 v60, vcc, s5, v54
	s_addc_u32 s25, s11, s7
	s_nop 0
	v_addc_co_u32_e32 v61, vcc, 0, v55, vcc
	s_mov_b32 s14, 0x30000
	v_lshl_add_u64 v[2:3], s[24:25], 0, v[52:53]
	v_add_co_u32_e32 v62, vcc, s14, v54
	v_lshl_add_u64 v[56:57], v[2:3], 0, v[0:1]
	s_nop 0
	v_addc_co_u32_e32 v63, vcc, 0, v55, vcc
	v_add_co_u32_e32 v64, vcc, s67, v56
	s_setprio 3
	global_load_dwordx4 v[2:5], v[58:59], off
	global_load_dwordx4 v[6:9], v[60:61], off
	v_addc_co_u32_e32 v65, vcc, 0, v57, vcc
	v_add_co_u32_e32 v66, vcc, s5, v56
	s_mov_b32 s5, 0x40000
	s_nop 0
	v_addc_co_u32_e32 v67, vcc, 0, v57, vcc
	v_add_co_u32_e32 v68, vcc, s14, v56
	global_load_dwordx4 v[10:13], v[54:55], off
	global_load_dwordx4 v[14:17], v[56:57], off
	v_addc_co_u32_e32 v69, vcc, 0, v57, vcc
	v_add_co_u32_e32 v70, vcc, s5, v56
	s_mov_b32 s5, 0x50000
	s_nop 0
	v_addc_co_u32_e32 v71, vcc, 0, v57, vcc
	v_add_co_u32_e32 v72, vcc, s5, v56
	s_mov_b32 s5, 0x60000
	s_nop 0
	v_addc_co_u32_e32 v73, vcc, 0, v57, vcc
	v_add_co_u32_e32 v74, vcc, s5, v56
	s_mov_b32 s5, 0x70000
	s_nop 0
	v_addc_co_u32_e32 v75, vcc, 0, v57, vcc
	v_add_co_u32_e32 v76, vcc, s5, v56
	global_load_dwordx4 v[18:21], v[62:63], off
	global_load_dwordx4 v[22:25], v[64:65], off
	global_load_dwordx4 v[26:29], v[66:67], off
	global_load_dwordx4 v[30:33], v[68:69], off
	global_load_dwordx4 v[34:37], v[70:71], off
	global_load_dwordx4 v[38:41], v[72:73], off
	v_addc_co_u32_e32 v77, vcc, 0, v57, vcc
	global_load_dwordx4 v[42:45], v[74:75], off
	global_load_dwordx4 v[46:49], v[76:77], off
	s_movk_i32 s14, 0x90
	v_mul_lo_u32 v50, v50, s14
	v_add3_u32 v189, 0, v50, v0
	s_waitcnt vmcnt(63) expcnt(7) lgkmcnt(15)
	s_barrier
	v_and_b32_e32 v51, 31, v78
	v_lshrrev_b32_e32 v79, 1, v78
	s_mov_b32 s5, 0xfffffc0
	v_and_or_b32 v80, v79, s5, v51
	v_lshlrev_b32_e32 v78, 1, v78
	s_movk_i32 s5, 0x80
	v_and_or_b32 v51, v78, s5, v51
	s_add_i32 s5, s26, s13
	v_mul_lo_u32 v80, v80, s14
	v_and_b32_e32 v79, 16, v79
	v_mul_u32_u24_e32 v51, 0x90, v51
	v_add3_u32 v187, 0, v80, v79
	v_add3_u32 v188, 0, v51, v79
	s_waitcnt vmcnt(9)
	ds_write_b128 v189, v[10:13]
	ds_write_b128 v189, v[2:5] offset:4608
	ds_write_b128 v189, v[6:9] offset:9216
	s_waitcnt vmcnt(7)
	ds_write_b128 v189, v[18:21] offset:13824
	ds_write_b128 v189, v[14:17] offset:18432
	s_waitcnt vmcnt(6)
	ds_write_b128 v189, v[22:25] offset:23040
	s_waitcnt vmcnt(5)
	ds_write_b128 v189, v[26:29] offset:27648
	s_waitcnt vmcnt(4)
	ds_write_b128 v189, v[30:33] offset:32256
	s_waitcnt vmcnt(3)
	ds_write_b128 v189, v[34:37] offset:36864
	s_waitcnt vmcnt(2)
	ds_write_b128 v189, v[38:41] offset:41472
	s_waitcnt vmcnt(1)
	ds_write_b128 v189, v[42:45] offset:46080
	s_waitcnt vmcnt(0)
	ds_write_b128 v189, v[46:49] offset:50688
	global_load_dwordx4 v[134:137], v[58:59], off offset:128
	global_load_dwordx4 v[138:141], v[60:61], off offset:128
	global_load_dwordx4 v[130:133], v[54:55], off offset:128
	global_load_dwordx4 v[146:149], v[56:57], off offset:128
	global_load_dwordx4 v[142:145], v[62:63], off offset:128
	global_load_dwordx4 v[150:153], v[64:65], off offset:128
	global_load_dwordx4 v[154:157], v[66:67], off offset:128
	global_load_dwordx4 v[158:161], v[68:69], off offset:128
	global_load_dwordx4 v[162:165], v[70:71], off offset:128
	global_load_dwordx4 v[166:169], v[72:73], off offset:128
	global_load_dwordx4 v[170:173], v[74:75], off offset:128
	global_load_dwordx4 v[174:177], v[76:77], off offset:128
	v_lshl_add_u64 v[2:3], s[6:7], 0, v[52:53]
	s_add_i32 s6, s5, s23
	s_mov_b32 s7, s89
	v_or_b32_e32 v2, v2, v0
	s_lshl_b64 s[6:7], s[6:7], 18
	v_lshl_add_u64 v[182:183], s[0:1], 0, v[2:3]
	v_lshl_add_u64 v[2:3], s[6:7], 0, v[52:53]
	s_waitcnt lgkmcnt(0)
	s_barrier
; __device__ __forceinline__ void gemm_big(const bf16_t* __restrict__ A, long lda, const bf16_t* __restrict__ Bt, int K, f32x16 (&acc)[2][4], unsigned char* lds) {
;     ...
;     const bf16_t* ap = A + (long)lrow * lda + lc * 8;
;     const bf16_t* bp = Bt + (long)lrow * K + lc * 8;
	v_or_b32_e32 v2, v2, v0
	v_lshl_add_u64 v[184:185], s[0:1], 0, v[2:3]
	v_mov_b32_e32 v2, 0
	s_mov_b64 s[6:7], 0
	s_mov_b32 s5, 0
	v_mov_b32_e32 v3, v2
	v_mov_b32_e32 v4, v2
	v_mov_b32_e32 v5, v2
	v_mov_b32_e32 v6, v2
	v_mov_b32_e32 v7, v2
	v_mov_b32_e32 v8, v2
	v_mov_b32_e32 v9, v2
	v_mov_b32_e32 v10, v2
	v_mov_b32_e32 v11, v2
	v_mov_b32_e32 v12, v2
	v_mov_b32_e32 v13, v2
	v_mov_b32_e32 v14, v2
	v_mov_b32_e32 v15, v2
	v_mov_b32_e32 v16, v2
	v_mov_b32_e32 v17, v2
	v_mov_b32_e32 v66, v2
	v_mov_b32_e32 v67, v2
	v_mov_b32_e32 v68, v2
	v_mov_b32_e32 v69, v2
	v_mov_b32_e32 v70, v2
	v_mov_b32_e32 v71, v2
	v_mov_b32_e32 v72, v2
	v_mov_b32_e32 v73, v2
	v_mov_b32_e32 v74, v2
	v_mov_b32_e32 v75, v2
	v_mov_b32_e32 v76, v2
	v_mov_b32_e32 v77, v2
	v_mov_b32_e32 v78, v2
	v_mov_b32_e32 v79, v2
	v_mov_b32_e32 v80, v2
	v_mov_b32_e32 v81, v2
	v_mov_b32_e32 v18, v2
	v_mov_b32_e32 v19, v2
	v_mov_b32_e32 v20, v2
	v_mov_b32_e32 v21, v2
	v_mov_b32_e32 v22, v2
	v_mov_b32_e32 v23, v2
	v_mov_b32_e32 v24, v2
	v_mov_b32_e32 v25, v2
	v_mov_b32_e32 v26, v2
	v_mov_b32_e32 v27, v2
	v_mov_b32_e32 v28, v2
	v_mov_b32_e32 v29, v2
	v_mov_b32_e32 v30, v2
	v_mov_b32_e32 v31, v2
	v_mov_b32_e32 v32, v2
	v_mov_b32_e32 v33, v2
	v_mov_b32_e32 v82, v2
	v_mov_b32_e32 v83, v2
	v_mov_b32_e32 v84, v2
	v_mov_b32_e32 v85, v2
	v_mov_b32_e32 v86, v2
	v_mov_b32_e32 v87, v2
	v_mov_b32_e32 v88, v2
	v_mov_b32_e32 v89, v2
	v_mov_b32_e32 v90, v2
	v_mov_b32_e32 v91, v2
	v_mov_b32_e32 v92, v2
	v_mov_b32_e32 v93, v2
	v_mov_b32_e32 v94, v2
	v_mov_b32_e32 v95, v2
	v_mov_b32_e32 v96, v2
	v_mov_b32_e32 v97, v2
	v_mov_b32_e32 v34, v2
	v_mov_b32_e32 v35, v2
	v_mov_b32_e32 v36, v2
	v_mov_b32_e32 v37, v2
	v_mov_b32_e32 v38, v2
	v_mov_b32_e32 v39, v2
	v_mov_b32_e32 v40, v2
	v_mov_b32_e32 v41, v2
	v_mov_b32_e32 v42, v2
	v_mov_b32_e32 v43, v2
	v_mov_b32_e32 v44, v2
	v_mov_b32_e32 v45, v2
	v_mov_b32_e32 v46, v2
	v_mov_b32_e32 v47, v2
	v_mov_b32_e32 v48, v2
	v_mov_b32_e32 v49, v2
	v_mov_b32_e32 v98, v2
	v_mov_b32_e32 v99, v2
	v_mov_b32_e32 v100, v2
	v_mov_b32_e32 v101, v2
	v_mov_b32_e32 v102, v2
	v_mov_b32_e32 v103, v2
	v_mov_b32_e32 v104, v2
	v_mov_b32_e32 v105, v2
	v_mov_b32_e32 v106, v2
	v_mov_b32_e32 v107, v2
	v_mov_b32_e32 v108, v2
	v_mov_b32_e32 v109, v2
	v_mov_b32_e32 v110, v2
	v_mov_b32_e32 v111, v2
	v_mov_b32_e32 v112, v2
	v_mov_b32_e32 v113, v2
	v_mov_b32_e32 v50, v2
	v_mov_b32_e32 v51, v2
	v_mov_b32_e32 v52, v2
	v_mov_b32_e32 v53, v2
	v_mov_b32_e32 v54, v2
	v_mov_b32_e32 v55, v2
	v_mov_b32_e32 v56, v2
	v_mov_b32_e32 v57, v2
	v_mov_b32_e32 v58, v2
	v_mov_b32_e32 v59, v2
	v_mov_b32_e32 v60, v2
	v_mov_b32_e32 v61, v2
	v_mov_b32_e32 v62, v2
	v_mov_b32_e32 v63, v2
	v_mov_b32_e32 v64, v2
	v_mov_b32_e32 v65, v2
	v_mov_b32_e32 v114, v2
	v_mov_b32_e32 v115, v2
	v_mov_b32_e32 v116, v2
	v_mov_b32_e32 v117, v2
	v_mov_b32_e32 v118, v2
	v_mov_b32_e32 v119, v2
	v_mov_b32_e32 v120, v2
	v_mov_b32_e32 v121, v2
	v_mov_b32_e32 v122, v2
	v_mov_b32_e32 v123, v2
	v_mov_b32_e32 v124, v2
	v_mov_b32_e32 v125, v2
	v_mov_b32_e32 v126, v2
	v_mov_b32_e32 v127, v2
	v_mov_b32_e32 v128, v2
	v_mov_b32_e32 v129, v2
	s_setprio 0
	s_branch .LBB0_84

; __device__ __forceinline__ void lds_barrier() { asm volatile("s_waitcnt lgkmcnt(0)\n\ts_barrier" ::: "memory"); }
; __device__ __forceinline__ f32x16 mfma32(bf16x8 a, bf16x8 b, f32x16 c) { return __builtin_amdgcn_mfma_f32_32x32x16_bf16(a, b, c, 0, 0, 0); }
; __device__ __forceinline__ void gemm_big(const bf16_t* __restrict__ A, long lda, const bf16_t* __restrict__ Bt, int K, f32x16 (&acc)[2][4], unsigned char* lds) {
;     ...
;     for (int kc = 0; kc < nk; ++kc) {
;         bf16x8 af[2][2], bfr[2][4];
;         af[0][0] = *(const bf16x8*)(Ac); af[0][1] = *(const bf16x8*)(Ac + 32 * GLD);
; #pragma unroll
;         for (int ni = 0; ni < 4; ++ni) bfr[0][ni] = *(const bf16x8*)(Bc + ni * 32 * GLD);
;         __builtin_amdgcn_s_setprio(3);
; #pragma unroll
;         for (int ks = 0; ks < 4; ++ks) {
;             const int cb = ks & 1, nb = cb ^ 1;
;             if (ks < 3) {
;                 af[nb][0] = *(const bf16x8*)(Ac + (ks + 1) * 16); af[nb][1] = *(const bf16x8*)(Ac + 32 * GLD + (ks + 1) * 16);
; #pragma unroll
;                 for (int ni = 0; ni < 4; ++ni) bfr[nb][ni] = *(const bf16x8*)(Bc + ni * 32 * GLD + (ks + 1) * 16);
;             }
;             __builtin_amdgcn_sched_barrier(0);
; #pragma unroll
;             for (int ni = 0; ni < 4; ++ni) { acc[0][ni] = mfma32(af[cb][0], bfr[cb][ni], acc[0][ni]); acc[1][ni] = mfma32(af[cb][1], bfr[cb][ni], acc[1][ni]); }
;             __builtin_amdgcn_sched_barrier(0);
;         }
;         __builtin_amdgcn_s_setprio(0);
;         lds_barrier();
;         if (kc + 1 < nk) {
;             lstore();
;             if (kc + 2 < nk) gload(kc + 2);
;             lds_barrier();
;         }
.Lmy_gorig_6:
	ds_read_b128 v[190:193], v187
	ds_read_b128 v[194:197], v187 offset:4608
	ds_read_b128 v[198:201], v188 offset:18432
	ds_read_b128 v[202:205], v188 offset:23040
	ds_read_b128 v[206:209], v188 offset:27648
	ds_read_b128 v[210:213], v188 offset:32256
	ds_read_b128 v[214:217], v187 offset:32
	ds_read_b128 v[218:221], v187 offset:4640
	ds_read_b128 v[224:227], v188 offset:18464
	ds_read_b128 v[234:237], v188 offset:23072
	ds_read_b128 v[238:241], v188 offset:27680
	ds_read_b128 v[242:245], v188 offset:32288
	s_waitcnt lgkmcnt(9)
	v_mfma_f32_32x32x16_bf16 v[114:129], v[190:193], v[198:201], v[114:129]
	v_mfma_f32_32x32x16_bf16 v[50:65], v[194:197], v[198:201], v[50:65]
	s_waitcnt lgkmcnt(8)
	v_mfma_f32_32x32x16_bf16 v[98:113], v[190:193], v[202:205], v[98:113]
	v_mfma_f32_32x32x16_bf16 v[34:49], v[194:197], v[202:205], v[34:49]
	s_waitcnt lgkmcnt(7)
	v_mfma_f32_32x32x16_bf16 v[82:97], v[190:193], v[206:209], v[82:97]
	v_mfma_f32_32x32x16_bf16 v[18:33], v[194:197], v[206:209], v[18:33]
	s_waitcnt lgkmcnt(6)
	v_mfma_f32_32x32x16_bf16 v[66:81], v[190:193], v[210:213], v[66:81]
	v_mfma_f32_32x32x16_bf16 v[2:17], v[194:197], v[210:213], v[2:17]
	ds_read_b128 v[190:193], v187 offset:64
	ds_read_b128 v[194:197], v187 offset:4672
	ds_read_b128 v[198:201], v188 offset:18496
	ds_read_b128 v[202:205], v188 offset:23104
	ds_read_b128 v[206:209], v188 offset:27712
	ds_read_b128 v[210:213], v188 offset:32320
	s_waitcnt lgkmcnt(9)
	v_mfma_f32_32x32x16_bf16 v[114:129], v[214:217], v[224:227], v[114:129]
	v_mfma_f32_32x32x16_bf16 v[50:65], v[218:221], v[224:227], v[50:65]
	s_waitcnt lgkmcnt(8)
	v_mfma_f32_32x32x16_bf16 v[98:113], v[214:217], v[234:237], v[98:113]
	v_mfma_f32_32x32x16_bf16 v[34:49], v[218:221], v[234:237], v[34:49]
	s_waitcnt lgkmcnt(7)
	v_mfma_f32_32x32x16_bf16 v[82:97], v[214:217], v[238:241], v[82:97]
	v_mfma_f32_32x32x16_bf16 v[18:33], v[218:221], v[238:241], v[18:33]
	s_waitcnt lgkmcnt(6)
	v_mfma_f32_32x32x16_bf16 v[66:81], v[214:217], v[242:245], v[66:81]
	v_mfma_f32_32x32x16_bf16 v[2:17], v[218:221], v[242:245], v[2:17]
	ds_read_b128 v[214:217], v187 offset:96
	ds_read_b128 v[218:221], v187 offset:4704
	ds_read_b128 v[224:227], v188 offset:18528
	ds_read_b128 v[234:237], v188 offset:23136
	ds_read_b128 v[238:241], v188 offset:27744
	ds_read_b128 v[242:245], v188 offset:32352
	s_waitcnt lgkmcnt(9)
	v_mfma_f32_32x32x16_bf16 v[114:129], v[190:193], v[198:201], v[114:129]
	v_mfma_f32_32x32x16_bf16 v[50:65], v[194:197], v[198:201], v[50:65]
	s_waitcnt lgkmcnt(8)
	v_mfma_f32_32x32x16_bf16 v[98:113], v[190:193], v[202:205], v[98:113]
	v_mfma_f32_32x32x16_bf16 v[34:49], v[194:197], v[202:205], v[34:49]
	s_waitcnt lgkmcnt(7)
	v_mfma_f32_32x32x16_bf16 v[82:97], v[190:193], v[206:209], v[82:97]
	v_mfma_f32_32x32x16_bf16 v[18:33], v[194:197], v[206:209], v[18:33]
	s_waitcnt lgkmcnt(6)
	v_mfma_f32_32x32x16_bf16 v[66:81], v[190:193], v[210:213], v[66:81]
	v_mfma_f32_32x32x16_bf16 v[2:17], v[194:197], v[210:213], v[2:17]
	s_waitcnt lgkmcnt(3)
	v_mfma_f32_32x32x16_bf16 v[114:129], v[214:217], v[224:227], v[114:129]
	v_mfma_f32_32x32x16_bf16 v[50:65], v[218:221], v[224:227], v[50:65]
	s_waitcnt lgkmcnt(2)
	v_mfma_f32_32x32x16_bf16 v[98:113], v[214:217], v[234:237], v[98:113]
	v_mfma_f32_32x32x16_bf16 v[34:49], v[218:221], v[234:237], v[34:49]
	s_waitcnt lgkmcnt(1)
	v_mfma_f32_32x32x16_bf16 v[82:97], v[214:217], v[238:241], v[82:97]
	v_mfma_f32_32x32x16_bf16 v[18:33], v[218:221], v[238:241], v[18:33]
	s_waitcnt lgkmcnt(0)
	v_mfma_f32_32x32x16_bf16 v[66:81], v[214:217], v[242:245], v[66:81]
	v_mfma_f32_32x32x16_bf16 v[2:17], v[218:221], v[242:245], v[2:17]
	s_setprio 0
	s_waitcnt lgkmcnt(0)
	s_barrier
	s_cmp_gt_u32 s5, 14
	s_cbranch_scc1 .LBB0_83
	s_cmpk_eq_i32 s6, 0x700
	s_waitcnt vmcnt(9)
	ds_write_b128 v189, v[130:133]
	ds_write_b128 v189, v[134:137] offset:4608
	ds_write_b128 v189, v[138:141] offset:9216
	s_waitcnt vmcnt(7)
	ds_write_b128 v189, v[142:145] offset:13824
	ds_write_b128 v189, v[146:149] offset:18432
	s_waitcnt vmcnt(6)
	ds_write_b128 v189, v[150:153] offset:23040
	s_waitcnt vmcnt(5)
	ds_write_b128 v189, v[154:157] offset:27648
	s_waitcnt vmcnt(4)
	ds_write_b128 v189, v[158:161] offset:32256
	s_waitcnt vmcnt(3)
	ds_write_b128 v189, v[162:165] offset:36864
	s_waitcnt vmcnt(2)
	ds_write_b128 v189, v[166:169] offset:41472
	s_waitcnt vmcnt(1)
	ds_write_b128 v189, v[170:173] offset:46080
	s_waitcnt vmcnt(0)
	ds_write_b128 v189, v[174:177] offset:50688
	s_cbranch_scc1 .LBB0_82
	v_lshl_add_u64 v[138:139], v[184:185], 0, s[6:7]
	v_add_co_u32_e32 v130, vcc, 0x14948000, v138
	v_lshl_add_u64 v[170:171], v[182:183], 0, s[6:7]
	s_nop 0
	v_addc_co_u32_e32 v131, vcc, 0, v139, vcc
	v_add_co_u32_e32 v134, vcc, 0x14958000, v138
	s_nop 1
	v_addc_co_u32_e32 v135, vcc, 0, v139, vcc
	v_add_co_u32_e32 v140, vcc, 0x14968000, v138
	global_load_dwordx4 v[130:133], v[130:131], off offset:256
	s_nop 0
	global_load_dwordx4 v[134:137], v[134:135], off offset:256
	v_addc_co_u32_e32 v141, vcc, 0, v139, vcc
	v_add_co_u32_e32 v142, vcc, 0x14978000, v138
	s_nop 1
	v_addc_co_u32_e32 v143, vcc, 0, v139, vcc
	v_add_co_u32_e32 v146, vcc, 0x2628000, v170
	global_load_dwordx4 v[138:141], v[140:141], off offset:256
	s_nop 0
	global_load_dwordx4 v[142:145], v[142:143], off offset:256
	v_addc_co_u32_e32 v147, vcc, 0, v171, vcc
	v_add_co_u32_e32 v150, vcc, 0x2638000, v170
	s_nop 1
	v_addc_co_u32_e32 v151, vcc, 0, v171, vcc
	v_add_co_u32_e32 v154, vcc, 0x2648000, v170
	global_load_dwordx4 v[146:149], v[146:147], off offset:256
	s_nop 0
	global_load_dwordx4 v[150:153], v[150:151], off offset:256
	v_addc_co_u32_e32 v155, vcc, 0, v171, vcc
	v_add_co_u32_e32 v158, vcc, 0x2658000, v170
	s_nop 1
	v_addc_co_u32_e32 v159, vcc, 0, v171, vcc
	v_add_co_u32_e32 v162, vcc, 0x2668000, v170
	global_load_dwordx4 v[154:157], v[154:155], off offset:256
	s_nop 0
	global_load_dwordx4 v[158:161], v[158:159], off offset:256
	v_addc_co_u32_e32 v163, vcc, 0, v171, vcc
	v_add_co_u32_e32 v166, vcc, 0x2678000, v170
	s_nop 1
	v_addc_co_u32_e32 v167, vcc, 0, v171, vcc
	v_add_co_u32_e32 v172, vcc, 0x2688000, v170
	global_load_dwordx4 v[162:165], v[162:163], off offset:256
	s_nop 0
	global_load_dwordx4 v[166:169], v[166:167], off offset:256
	v_addc_co_u32_e32 v173, vcc, 0, v171, vcc
	v_add_co_u32_e32 v174, vcc, 0x2698000, v170
	s_nop 1
	v_addc_co_u32_e32 v175, vcc, 0, v171, vcc
	global_load_dwordx4 v[170:173], v[172:173], off offset:256
	s_nop 0
	global_load_dwordx4 v[174:177], v[174:175], off offset:256
	s_branch .LBB0_82

; __device__ __forceinline__ void lds_barrier() { asm volatile("s_waitcnt lgkmcnt(0)\n\ts_barrier" ::: "memory"); }
; __device__ __forceinline__ void gemm_big(const bf16_t* __restrict__ A, long lda, const bf16_t* __restrict__ Bt, int K, f32x16 (&acc)[2][4], unsigned char* lds) {
;     ...
;     const bf16_t* ap = A + (long)lrow * lda + lc * 8;
;     const bf16_t* bp = Bt + (long)lrow * K + lc * 8;
;     u32x4 ra[4], rb[8];
;     auto gload = [&](int kc) {
; #pragma unroll
;         for (int i = 0; i < 4; ++i) ra[i] = *(const u32x4*)(ap + (long)(32 * i) * lda + kc * 64);
; #pragma unroll
;         for (int i = 0; i < 8; ++i) rb[i] = *(const u32x4*)(bp + (long)(32 * i) * K + kc * 64);
;     };
;     auto lstore = [&]() {
; #pragma unroll
;         for (int i = 0; i < 4; ++i) *(u32x4*)(As + (lrow + 32 * i) * GLD + lc * 8) = ra[i];
; #pragma unroll
;         for (int i = 0; i < 8; ++i) *(u32x4*)(Bs + (lrow + 32 * i) * GLD + lc * 8) = rb[i];
;     };
;     const bf16_t* Ac = As + (wr * 64 + r) * GLD + h * 8;
;     const bf16_t* Bc = Bs + (wc * 128 + r) * GLD + h * 8;
;     gload(0);
;     __syncthreads();
;     lstore();
;     if (nk > 1) gload(1);
;     lds_barrier();
; __device__ __forceinline__ bool tile_at(int k, int NPM, int NPN, int& pm, int& pn) {
;     const int nb = gridDim.x >> 3, x = blockIdx.x & 7, jb = blockIdx.x >> 3;
;     const int t = jb + k * nb, perx = (NPM >> 3) * NPN;
;     if (t >= perx) return false;
;     const int pmg = t / (8 * NPN), rem = t - pmg * 8 * NPN;
;     pn = rem >> 3; pm = x * (NPM >> 3) + pmg * 8 + (rem & 7);
.LBB0_112:
	s_mul_hi_u32 s5, s4, 0xaaaaaaab
	s_lshr_b32 s5, s5, 6
	s_and_b32 s23, s4, 7
	v_readlane_b32 s31, v252, 8
	s_mul_i32 s6, s5, 0xffffffa0
	s_or_b32 s15, s23, s31
	s_lshl_b32 s30, s5, 3
	s_add_i32 s6, s6, s4
	s_add_i32 s15, s15, s30
	v_mov_b32_e32 v78, v179
	s_ashr_i32 s4, s6, 3
	s_lshl_b32 s5, s15, 18
	s_add_u32 s26, s3, s5
	s_waitcnt vmcnt(27)
	v_ashrrev_i32_e32 v50, 3, v78
	s_waitcnt vmcnt(26)
	v_ashrrev_i32_e32 v51, 31, v50
	s_addc_u32 s27, s8, 0
	s_waitcnt vmcnt(24)
	v_lshlrev_b64 v[52:53], 11, v[50:51]
	v_lshlrev_b32_e32 v0, 4, v78
	v_lshl_add_u64 v[2:3], s[26:27], 0, v[52:53]
	v_and_b32_e32 v0, 0x70, v0
	v_lshl_add_u64 v[54:55], v[2:3], 0, v[0:1]
	s_ashr_i32 s5, s4, 31
	v_add_co_u32_e32 v58, vcc, s67, v54
	s_lshl_b64 s[6:7], s[4:5], 19
	s_nop 0
	v_addc_co_u32_e32 v59, vcc, 0, v55, vcc
	s_mov_b32 s5, 0x20000
	s_add_u32 s28, s9, s6
	v_add_co_u32_e32 v60, vcc, s5, v54
	s_addc_u32 s29, s10, s7
	s_nop 0
	v_addc_co_u32_e32 v61, vcc, 0, v55, vcc
	s_mov_b32 s26, 0x30000
	v_lshl_add_u64 v[2:3], s[28:29], 0, v[52:53]
	s_waitcnt vmcnt(23)
	v_add_co_u32_e32 v62, vcc, s26, v54
	v_lshl_add_u64 v[56:57], v[2:3], 0, v[0:1]
	s_waitcnt vmcnt(22)
	v_addc_co_u32_e32 v63, vcc, 0, v55, vcc
	s_waitcnt vmcnt(21)
	v_add_co_u32_e32 v64, vcc, s67, v56
	s_setprio 3
	global_load_dwordx4 v[2:5], v[58:59], off
	global_load_dwordx4 v[6:9], v[60:61], off
	s_waitcnt vmcnt(22)
	v_addc_co_u32_e32 v65, vcc, 0, v57, vcc
	s_waitcnt vmcnt(21)
	v_add_co_u32_e32 v66, vcc, s5, v56
	s_mov_b32 s5, 0x40000
	s_waitcnt vmcnt(20)
	v_addc_co_u32_e32 v67, vcc, 0, v57, vcc
	s_waitcnt vmcnt(19)
	v_add_co_u32_e32 v68, vcc, s26, v56
	global_load_dwordx4 v[10:13], v[54:55], off
	global_load_dwordx4 v[14:17], v[56:57], off
	s_waitcnt vmcnt(20)
	v_addc_co_u32_e32 v69, vcc, 0, v57, vcc
	v_add_co_u32_e32 v70, vcc, s5, v56
	s_mov_b32 s5, 0x50000
	s_nop 0
	v_addc_co_u32_e32 v71, vcc, 0, v57, vcc
	v_add_co_u32_e32 v72, vcc, s5, v56
	s_mov_b32 s5, 0x60000
	s_nop 0
	v_addc_co_u32_e32 v73, vcc, 0, v57, vcc
	v_add_co_u32_e32 v74, vcc, s5, v56
	s_mov_b32 s5, 0x70000
	s_nop 0
	v_addc_co_u32_e32 v75, vcc, 0, v57, vcc
	v_add_co_u32_e32 v76, vcc, s5, v56
	global_load_dwordx4 v[18:21], v[62:63], off
	global_load_dwordx4 v[22:25], v[64:65], off
	global_load_dwordx4 v[26:29], v[66:67], off
	global_load_dwordx4 v[30:33], v[68:69], off
	global_load_dwordx4 v[34:37], v[70:71], off
	global_load_dwordx4 v[38:41], v[72:73], off
	v_addc_co_u32_e32 v77, vcc, 0, v57, vcc
	global_load_dwordx4 v[42:45], v[74:75], off
	global_load_dwordx4 v[46:49], v[76:77], off
	s_movk_i32 s26, 0x90
	v_mul_lo_u32 v50, v50, s26
	v_add3_u32 v189, 0, v50, v0
	s_waitcnt vmcnt(63) expcnt(7) lgkmcnt(15)
	s_barrier
	v_and_b32_e32 v51, 31, v78
	v_lshrrev_b32_e32 v79, 1, v78
	s_mov_b32 s5, 0xfffffc0
	v_and_or_b32 v80, v79, s5, v51
	v_lshlrev_b32_e32 v78, 1, v78
	s_movk_i32 s5, 0x80
	v_and_or_b32 v51, v78, s5, v51
	s_add_i32 s5, s31, s30
	s_add_i32 s5, s5, s23
	s_lshl_b32 s5, s5, 18
	v_mul_lo_u32 v80, v80, s26
	v_and_b32_e32 v79, 16, v79
	v_mul_u32_u24_e32 v51, 0x90, v51
	v_add3_u32 v187, 0, v80, v79
	v_add3_u32 v188, 0, v51, v79
	s_waitcnt vmcnt(9)
	ds_write_b128 v189, v[10:13]
	ds_write_b128 v189, v[2:5] offset:4608
	ds_write_b128 v189, v[6:9] offset:9216
	s_waitcnt vmcnt(7)
	ds_write_b128 v189, v[18:21] offset:13824
	ds_write_b128 v189, v[14:17] offset:18432
	s_waitcnt vmcnt(6)
	ds_write_b128 v189, v[22:25] offset:23040
	s_waitcnt vmcnt(5)
	ds_write_b128 v189, v[26:29] offset:27648
	s_waitcnt vmcnt(4)
	ds_write_b128 v189, v[30:33] offset:32256
	s_waitcnt vmcnt(3)
	ds_write_b128 v189, v[34:37] offset:36864
	s_waitcnt vmcnt(2)
	ds_write_b128 v189, v[38:41] offset:41472
	s_waitcnt vmcnt(1)
	ds_write_b128 v189, v[42:45] offset:46080
	s_waitcnt vmcnt(0)
	ds_write_b128 v189, v[46:49] offset:50688
	global_load_dwordx4 v[134:137], v[58:59], off offset:128
	global_load_dwordx4 v[138:141], v[60:61], off offset:128
	global_load_dwordx4 v[130:133], v[54:55], off offset:128
	global_load_dwordx4 v[146:149], v[56:57], off offset:128
	global_load_dwordx4 v[142:145], v[62:63], off offset:128
	global_load_dwordx4 v[150:153], v[64:65], off offset:128
	global_load_dwordx4 v[154:157], v[66:67], off offset:128
	global_load_dwordx4 v[158:161], v[68:69], off offset:128
	global_load_dwordx4 v[162:165], v[70:71], off offset:128
	global_load_dwordx4 v[166:169], v[72:73], off offset:128
	global_load_dwordx4 v[170:173], v[74:75], off offset:128
	global_load_dwordx4 v[174:177], v[76:77], off offset:128
	v_lshl_add_u64 v[2:3], s[6:7], 0, v[52:53]
	s_waitcnt lgkmcnt(0)
	s_barrier
; __device__ __forceinline__ void gemm_big(const bf16_t* __restrict__ A, long lda, const bf16_t* __restrict__ Bt, int K, f32x16 (&acc)[2][4], unsigned char* lds) {
;     ...
;     const bf16_t* ap = A + (long)lrow * lda + lc * 8;
;     const bf16_t* bp = Bt + (long)lrow * K + lc * 8;
	v_or_b32_e32 v2, v2, v0
	s_add_u32 s6, s12, s5
	v_lshl_add_u64 v[182:183], s[0:1], 0, v[2:3]
	v_or_b32_e32 v52, v52, v0
	s_addc_u32 s7, s13, 0
	v_mov_b32_e32 v2, 0
	v_lshl_add_u64 v[184:185], s[6:7], 0, v[52:53]
	s_mov_b64 s[6:7], 0
	s_mov_b32 s5, 0
	v_mov_b32_e32 v3, v2
	v_mov_b32_e32 v4, v2
	v_mov_b32_e32 v5, v2
	v_mov_b32_e32 v6, v2
	v_mov_b32_e32 v7, v2
	v_mov_b32_e32 v8, v2
	v_mov_b32_e32 v9, v2
	v_mov_b32_e32 v10, v2
	v_mov_b32_e32 v11, v2
	v_mov_b32_e32 v12, v2
	v_mov_b32_e32 v13, v2
	v_mov_b32_e32 v14, v2
	v_mov_b32_e32 v15, v2
	v_mov_b32_e32 v16, v2
	v_mov_b32_e32 v17, v2
	v_mov_b32_e32 v18, v2
	v_mov_b32_e32 v19, v2
	v_mov_b32_e32 v20, v2
	v_mov_b32_e32 v21, v2
	v_mov_b32_e32 v22, v2
	v_mov_b32_e32 v23, v2
	v_mov_b32_e32 v24, v2
	v_mov_b32_e32 v25, v2
	v_mov_b32_e32 v26, v2
	v_mov_b32_e32 v27, v2
	v_mov_b32_e32 v28, v2
	v_mov_b32_e32 v29, v2
	v_mov_b32_e32 v30, v2
	v_mov_b32_e32 v31, v2
	v_mov_b32_e32 v32, v2
	v_mov_b32_e32 v33, v2
	v_mov_b32_e32 v34, v2
	v_mov_b32_e32 v35, v2
	v_mov_b32_e32 v36, v2
	v_mov_b32_e32 v37, v2
	v_mov_b32_e32 v38, v2
	v_mov_b32_e32 v39, v2
	v_mov_b32_e32 v40, v2
	v_mov_b32_e32 v41, v2
	v_mov_b32_e32 v42, v2
	v_mov_b32_e32 v43, v2
	v_mov_b32_e32 v44, v2
	v_mov_b32_e32 v45, v2
	v_mov_b32_e32 v46, v2
	v_mov_b32_e32 v47, v2
	v_mov_b32_e32 v48, v2
	v_mov_b32_e32 v49, v2
	v_mov_b32_e32 v50, v2
	v_mov_b32_e32 v51, v2
	v_mov_b32_e32 v52, v2
	v_mov_b32_e32 v53, v2
	v_mov_b32_e32 v54, v2
	v_mov_b32_e32 v55, v2
	v_mov_b32_e32 v56, v2
	v_mov_b32_e32 v57, v2
	v_mov_b32_e32 v58, v2
	v_mov_b32_e32 v59, v2
	v_mov_b32_e32 v60, v2
	v_mov_b32_e32 v61, v2
	v_mov_b32_e32 v62, v2
	v_mov_b32_e32 v63, v2
	v_mov_b32_e32 v64, v2
	v_mov_b32_e32 v65, v2
	v_mov_b32_e32 v66, v2
	v_mov_b32_e32 v67, v2
	v_mov_b32_e32 v68, v2
	v_mov_b32_e32 v69, v2
	v_mov_b32_e32 v70, v2
	v_mov_b32_e32 v71, v2
	v_mov_b32_e32 v72, v2
	v_mov_b32_e32 v73, v2
	v_mov_b32_e32 v74, v2
	v_mov_b32_e32 v75, v2
	v_mov_b32_e32 v76, v2
	v_mov_b32_e32 v77, v2
	v_mov_b32_e32 v78, v2
	v_mov_b32_e32 v79, v2
	v_mov_b32_e32 v80, v2
	v_mov_b32_e32 v81, v2
	v_mov_b32_e32 v82, v2
	v_mov_b32_e32 v83, v2
	v_mov_b32_e32 v84, v2
	v_mov_b32_e32 v85, v2
	v_mov_b32_e32 v86, v2
	v_mov_b32_e32 v87, v2
	v_mov_b32_e32 v88, v2
	v_mov_b32_e32 v89, v2
	v_mov_b32_e32 v90, v2
	v_mov_b32_e32 v91, v2
	v_mov_b32_e32 v92, v2
	v_mov_b32_e32 v93, v2
	v_mov_b32_e32 v94, v2
	v_mov_b32_e32 v95, v2
	v_mov_b32_e32 v96, v2
	v_mov_b32_e32 v97, v2
	v_mov_b32_e32 v98, v2
	v_mov_b32_e32 v99, v2
	v_mov_b32_e32 v100, v2
	v_mov_b32_e32 v101, v2
	v_mov_b32_e32 v102, v2
	v_mov_b32_e32 v103, v2
	v_mov_b32_e32 v104, v2
	v_mov_b32_e32 v105, v2
	v_mov_b32_e32 v106, v2
	v_mov_b32_e32 v107, v2
	v_mov_b32_e32 v108, v2
	v_mov_b32_e32 v109, v2
	v_mov_b32_e32 v110, v2
	v_mov_b32_e32 v111, v2
	v_mov_b32_e32 v112, v2
	v_mov_b32_e32 v113, v2
	v_mov_b32_e32 v114, v2
	v_mov_b32_e32 v115, v2
	v_mov_b32_e32 v116, v2
	v_mov_b32_e32 v117, v2
	v_mov_b32_e32 v118, v2
	v_mov_b32_e32 v119, v2
	v_mov_b32_e32 v120, v2
	v_mov_b32_e32 v121, v2
	v_mov_b32_e32 v122, v2
	v_mov_b32_e32 v123, v2
	v_mov_b32_e32 v124, v2
	v_mov_b32_e32 v125, v2
	v_mov_b32_e32 v126, v2
	v_mov_b32_e32 v127, v2
	v_mov_b32_e32 v128, v2
	v_mov_b32_e32 v129, v2
	s_setprio 0
	s_branch .LBB0_115

; __device__ __forceinline__ void lds_barrier() { asm volatile("s_waitcnt lgkmcnt(0)\n\ts_barrier" ::: "memory"); }
; __device__ __forceinline__ f32x16 mfma32(bf16x8 a, bf16x8 b, f32x16 c) { return __builtin_amdgcn_mfma_f32_32x32x16_bf16(a, b, c, 0, 0, 0); }
; __device__ __forceinline__ void gemm_big(const bf16_t* __restrict__ A, long lda, const bf16_t* __restrict__ Bt, int K, f32x16 (&acc)[2][4], unsigned char* lds) {
;     ...
;     for (int kc = 0; kc < nk; ++kc) {
;         bf16x8 af[2][2], bfr[2][4];
;         af[0][0] = *(const bf16x8*)(Ac); af[0][1] = *(const bf16x8*)(Ac + 32 * GLD);
; #pragma unroll
;         for (int ni = 0; ni < 4; ++ni) bfr[0][ni] = *(const bf16x8*)(Bc + ni * 32 * GLD);
;         __builtin_amdgcn_s_setprio(3);
; #pragma unroll
;         for (int ks = 0; ks < 4; ++ks) {
;             const int cb = ks & 1, nb = cb ^ 1;
;             if (ks < 3) {
;                 af[nb][0] = *(const bf16x8*)(Ac + (ks + 1) * 16); af[nb][1] = *(const bf16x8*)(Ac + 32 * GLD + (ks + 1) * 16);
; #pragma unroll
;                 for (int ni = 0; ni < 4; ++ni) bfr[nb][ni] = *(const bf16x8*)(Bc + ni * 32 * GLD + (ks + 1) * 16);
;             }
;             __builtin_amdgcn_sched_barrier(0);
; #pragma unroll
;             for (int ni = 0; ni < 4; ++ni) { acc[0][ni] = mfma32(af[cb][0], bfr[cb][ni], acc[0][ni]); acc[1][ni] = mfma32(af[cb][1], bfr[cb][ni], acc[1][ni]); }
;             __builtin_amdgcn_sched_barrier(0);
;         }
;         __builtin_amdgcn_s_setprio(0);
;         lds_barrier();
;         if (kc + 1 < nk) {
;             lstore();
;             if (kc + 2 < nk) gload(kc + 2);
;             lds_barrier();
;         }
.Lmy_gorig_5:
	ds_read_b128 v[190:193], v187
	ds_read_b128 v[194:197], v187 offset:4608
	ds_read_b128 v[198:201], v188 offset:18432
	ds_read_b128 v[202:205], v188 offset:23040
	ds_read_b128 v[206:209], v188 offset:27648
	ds_read_b128 v[210:213], v188 offset:32256
	ds_read_b128 v[214:217], v187 offset:32
	ds_read_b128 v[218:221], v187 offset:4640
	ds_read_b128 v[224:227], v188 offset:18464
	ds_read_b128 v[234:237], v188 offset:23072
	ds_read_b128 v[238:241], v188 offset:27680
	ds_read_b128 v[242:245], v188 offset:32288
	s_waitcnt lgkmcnt(9)
	v_mfma_f32_32x32x16_bf16 v[114:129], v[190:193], v[198:201], v[114:129]
	v_mfma_f32_32x32x16_bf16 v[98:113], v[194:197], v[198:201], v[98:113]
	s_waitcnt lgkmcnt(8)
	v_mfma_f32_32x32x16_bf16 v[82:97], v[190:193], v[202:205], v[82:97]
	v_mfma_f32_32x32x16_bf16 v[66:81], v[194:197], v[202:205], v[66:81]
	s_waitcnt lgkmcnt(7)
	v_mfma_f32_32x32x16_bf16 v[50:65], v[190:193], v[206:209], v[50:65]
	v_mfma_f32_32x32x16_bf16 v[34:49], v[194:197], v[206:209], v[34:49]
	s_waitcnt lgkmcnt(6)
	v_mfma_f32_32x32x16_bf16 v[18:33], v[190:193], v[210:213], v[18:33]
	v_mfma_f32_32x32x16_bf16 v[2:17], v[194:197], v[210:213], v[2:17]
	ds_read_b128 v[190:193], v187 offset:64
	ds_read_b128 v[194:197], v187 offset:4672
	ds_read_b128 v[198:201], v188 offset:18496
	ds_read_b128 v[202:205], v188 offset:23104
	ds_read_b128 v[206:209], v188 offset:27712
	ds_read_b128 v[210:213], v188 offset:32320
	s_waitcnt lgkmcnt(9)
	v_mfma_f32_32x32x16_bf16 v[114:129], v[214:217], v[224:227], v[114:129]
	v_mfma_f32_32x32x16_bf16 v[98:113], v[218:221], v[224:227], v[98:113]
	s_waitcnt lgkmcnt(8)
	v_mfma_f32_32x32x16_bf16 v[82:97], v[214:217], v[234:237], v[82:97]
	v_mfma_f32_32x32x16_bf16 v[66:81], v[218:221], v[234:237], v[66:81]
	s_waitcnt lgkmcnt(7)
	v_mfma_f32_32x32x16_bf16 v[50:65], v[214:217], v[238:241], v[50:65]
	v_mfma_f32_32x32x16_bf16 v[34:49], v[218:221], v[238:241], v[34:49]
	s_waitcnt lgkmcnt(6)
	v_mfma_f32_32x32x16_bf16 v[18:33], v[214:217], v[242:245], v[18:33]
	v_mfma_f32_32x32x16_bf16 v[2:17], v[218:221], v[242:245], v[2:17]
	ds_read_b128 v[214:217], v187 offset:96
	ds_read_b128 v[218:221], v187 offset:4704
	ds_read_b128 v[224:227], v188 offset:18528
	ds_read_b128 v[234:237], v188 offset:23136
	ds_read_b128 v[238:241], v188 offset:27744
	ds_read_b128 v[242:245], v188 offset:32352
	s_waitcnt lgkmcnt(9)
	v_mfma_f32_32x32x16_bf16 v[114:129], v[190:193], v[198:201], v[114:129]
	v_mfma_f32_32x32x16_bf16 v[98:113], v[194:197], v[198:201], v[98:113]
	s_waitcnt lgkmcnt(8)
	v_mfma_f32_32x32x16_bf16 v[82:97], v[190:193], v[202:205], v[82:97]
	v_mfma_f32_32x32x16_bf16 v[66:81], v[194:197], v[202:205], v[66:81]
	s_waitcnt lgkmcnt(7)
	v_mfma_f32_32x32x16_bf16 v[50:65], v[190:193], v[206:209], v[50:65]
	v_mfma_f32_32x32x16_bf16 v[34:49], v[194:197], v[206:209], v[34:49]
	s_waitcnt lgkmcnt(6)
	v_mfma_f32_32x32x16_bf16 v[18:33], v[190:193], v[210:213], v[18:33]
	v_mfma_f32_32x32x16_bf16 v[2:17], v[194:197], v[210:213], v[2:17]
	s_waitcnt lgkmcnt(3)
	v_mfma_f32_32x32x16_bf16 v[114:129], v[214:217], v[224:227], v[114:129]
	v_mfma_f32_32x32x16_bf16 v[98:113], v[218:221], v[224:227], v[98:113]
	s_waitcnt lgkmcnt(2)
	v_mfma_f32_32x32x16_bf16 v[82:97], v[214:217], v[234:237], v[82:97]
	v_mfma_f32_32x32x16_bf16 v[66:81], v[218:221], v[234:237], v[66:81]
	s_waitcnt lgkmcnt(1)
	v_mfma_f32_32x32x16_bf16 v[50:65], v[214:217], v[238:241], v[50:65]
	v_mfma_f32_32x32x16_bf16 v[34:49], v[218:221], v[238:241], v[34:49]
	s_waitcnt lgkmcnt(0)
	v_mfma_f32_32x32x16_bf16 v[18:33], v[214:217], v[242:245], v[18:33]
	v_mfma_f32_32x32x16_bf16 v[2:17], v[218:221], v[242:245], v[2:17]
	s_setprio 0
	s_waitcnt lgkmcnt(0)
	s_barrier
	s_cmp_gt_u32 s5, 14
	s_cbranch_scc1 .LBB0_114
	s_cmpk_eq_i32 s6, 0x700
	s_waitcnt vmcnt(9)
	ds_write_b128 v189, v[130:133]
	ds_write_b128 v189, v[134:137] offset:4608
	ds_write_b128 v189, v[138:141] offset:9216
	s_waitcnt vmcnt(7)
	ds_write_b128 v189, v[142:145] offset:13824
	ds_write_b128 v189, v[146:149] offset:18432
	s_waitcnt vmcnt(6)
	ds_write_b128 v189, v[150:153] offset:23040
	s_waitcnt vmcnt(5)
	ds_write_b128 v189, v[154:157] offset:27648
	s_waitcnt vmcnt(4)
	ds_write_b128 v189, v[158:161] offset:32256
	s_waitcnt vmcnt(3)
	ds_write_b128 v189, v[162:165] offset:36864
	s_waitcnt vmcnt(2)
	ds_write_b128 v189, v[166:169] offset:41472
	s_waitcnt vmcnt(1)
	ds_write_b128 v189, v[170:173] offset:46080
	s_waitcnt vmcnt(0)
	ds_write_b128 v189, v[174:177] offset:50688
	s_cbranch_scc1 .LBB0_113
	v_lshl_add_u64 v[138:139], v[184:185], 0, s[6:7]
	v_add_co_u32_e32 v130, vcc, 0x38a8000, v138
	v_lshl_add_u64 v[170:171], v[182:183], 0, s[6:7]
	s_nop 0
	v_addc_co_u32_e32 v131, vcc, 0, v139, vcc
	v_add_co_u32_e32 v134, vcc, 0x38b8000, v138
	s_nop 1
	v_addc_co_u32_e32 v135, vcc, 0, v139, vcc
	v_add_co_u32_e32 v140, vcc, 0x38c8000, v138
	global_load_dwordx4 v[130:133], v[130:131], off offset:256
	s_nop 0
	global_load_dwordx4 v[134:137], v[134:135], off offset:256
	v_addc_co_u32_e32 v141, vcc, 0, v139, vcc
	v_add_co_u32_e32 v142, vcc, 0x38d8000, v138
	s_nop 1
	v_addc_co_u32_e32 v143, vcc, 0, v139, vcc
	v_add_co_u32_e32 v146, vcc, 0x1c88000, v170
	global_load_dwordx4 v[138:141], v[140:141], off offset:256
	s_nop 0
	global_load_dwordx4 v[142:145], v[142:143], off offset:256
	v_addc_co_u32_e32 v147, vcc, 0, v171, vcc
	v_add_co_u32_e32 v150, vcc, 0x1c98000, v170
	s_nop 1
	v_addc_co_u32_e32 v151, vcc, 0, v171, vcc
	v_add_co_u32_e32 v154, vcc, 0x1ca8000, v170
	global_load_dwordx4 v[146:149], v[146:147], off offset:256
	s_nop 0
	global_load_dwordx4 v[150:153], v[150:151], off offset:256
	v_addc_co_u32_e32 v155, vcc, 0, v171, vcc
	v_add_co_u32_e32 v158, vcc, 0x1cb8000, v170
	s_nop 1
	v_addc_co_u32_e32 v159, vcc, 0, v171, vcc
	v_add_co_u32_e32 v162, vcc, 0x1cc8000, v170
	global_load_dwordx4 v[154:157], v[154:155], off offset:256
	s_nop 0
	global_load_dwordx4 v[158:161], v[158:159], off offset:256
	v_addc_co_u32_e32 v163, vcc, 0, v171, vcc
	v_add_co_u32_e32 v166, vcc, 0x1cd8000, v170
	s_nop 1
	v_addc_co_u32_e32 v167, vcc, 0, v171, vcc
	v_add_co_u32_e32 v172, vcc, 0x1ce8000, v170
	global_load_dwordx4 v[162:165], v[162:163], off offset:256
	s_nop 0
	global_load_dwordx4 v[166:169], v[166:167], off offset:256
	v_addc_co_u32_e32 v173, vcc, 0, v171, vcc
	v_add_co_u32_e32 v174, vcc, 0x1cf8000, v170
	s_nop 1
	v_addc_co_u32_e32 v175, vcc, 0, v171, vcc
	global_load_dwordx4 v[170:173], v[172:173], off offset:256
	s_nop 0
	global_load_dwordx4 v[174:177], v[174:175], off offset:256
	s_branch .LBB0_113

; __device__ __forceinline__ void lds_barrier() { asm volatile("s_waitcnt lgkmcnt(0)\n\ts_barrier" ::: "memory"); }
; __device__ __forceinline__ void gemm_big(const bf16_t* __restrict__ A, long lda, const bf16_t* __restrict__ Bt, int K, f32x16 (&acc)[2][4], unsigned char* lds) {
;     ...
;     const bf16_t* ap = A + (long)lrow * lda + lc * 8;
;     const bf16_t* bp = Bt + (long)lrow * K + lc * 8;
;     u32x4 ra[4], rb[8];
;     auto gload = [&](int kc) {
; #pragma unroll
;         for (int i = 0; i < 4; ++i) ra[i] = *(const u32x4*)(ap + (long)(32 * i) * lda + kc * 64);
; #pragma unroll
;         for (int i = 0; i < 8; ++i) rb[i] = *(const u32x4*)(bp + (long)(32 * i) * K + kc * 64);
;     };
;     auto lstore = [&]() {
; #pragma unroll
;         for (int i = 0; i < 4; ++i) *(u32x4*)(As + (lrow + 32 * i) * GLD + lc * 8) = ra[i];
; #pragma unroll
;         for (int i = 0; i < 8; ++i) *(u32x4*)(Bs + (lrow + 32 * i) * GLD + lc * 8) = rb[i];
;     };
;     const bf16_t* Ac = As + (wr * 64 + r) * GLD + h * 8;
;     const bf16_t* Bc = Bs + (wc * 128 + r) * GLD + h * 8;
;     gload(0);
;     __syncthreads();
;     lstore();
;     if (nk > 1) gload(1);
;     lds_barrier();
; __device__ __forceinline__ void mla_up_tile(const Params& p, int b, int it, unsigned char* lds) {
;     ...
;         const int pn = it % 3, pm = it / 3;
;         gemm_big(PB + (size_t)pm * 128 * PBW + PB_CQ, PBW, wb + W_UQ + (size_t)pn * 256 * 256, 256, acc, lds);
.LBB0_279:
	s_and_b64 vcc, exec, s[4:5]
	s_cbranch_vccz .LBB0_272
	s_mul_hi_i32 s15, s14, 0x55555556
	s_lshr_b32 s4, s15, 31
	s_add_i32 s15, s15, s4
	s_mul_i32 s4, s15, 3
	s_sub_i32 s4, s14, s4
	s_mul_i32 s6, s15, 0xf8000
	s_mul_hi_i32 s5, s15, 0xf8000
	s_add_u32 s38, s3, s6
	s_addc_u32 s39, s8, s5
	v_mov_b32_e32 v82, v179
	v_mov_b64_e32 v[2:3], s[38:39]
	s_waitcnt vmcnt(27)
	v_ashrrev_i32_e32 v50, 3, v82
	s_waitcnt vmcnt(5)
	v_lshlrev_b32_e32 v4, 4, v82
	s_ashr_i32 s5, s4, 31
	v_mad_i64_i32 v[2:3], s[38:39], v50, s60, v[2:3]
	s_waitcnt vmcnt(25)
	v_and_b32_e32 v52, 0x70, v4
	s_waitcnt vmcnt(24)
	v_mov_b32_e32 v53, v1
	s_lshl_b64 s[6:7], s[4:5], 17
	v_lshl_add_u64 v[54:55], v[2:3], 0, v[52:53]
	s_mov_b32 s5, 0x3e000
	v_add_co_u32_e32 v60, vcc, s5, v54
	s_mov_b32 s5, 0x7c000
	s_nop 0
	v_addc_co_u32_e32 v61, vcc, 0, v55, vcc
	s_add_u32 s40, s11, s6
	v_ashrrev_i32_e32 v51, 31, v50
	s_waitcnt vmcnt(23)
	v_add_co_u32_e32 v62, vcc, s5, v54
	s_addc_u32 s41, s12, s7
	v_lshlrev_b64 v[56:57], 9, v[50:51]
	s_waitcnt vmcnt(22)
	v_addc_co_u32_e32 v63, vcc, 0, v55, vcc
	s_mov_b32 s5, 0xba000
	v_lshl_add_u64 v[2:3], s[40:41], 0, v[56:57]
	s_waitcnt vmcnt(21)
	v_add_co_u32_e32 v64, vcc, s5, v54
	v_lshl_add_u64 v[58:59], v[2:3], 0, v[52:53]
	s_waitcnt vmcnt(20)
	v_addc_co_u32_e32 v65, vcc, 0, v55, vcc
	s_waitcnt vmcnt(19)
	v_add_co_u32_e32 v66, vcc, s33, v58
	s_mov_b32 s5, 0x8000
	s_waitcnt vmcnt(18)
	v_addc_co_u32_e32 v67, vcc, 0, v59, vcc
	s_waitcnt vmcnt(17)
	v_add_co_u32_e32 v68, vcc, s5, v58
	s_mov_b32 s5, 0x14000
	s_waitcnt vmcnt(16)
	v_addc_co_u32_e32 v69, vcc, 0, v59, vcc
	v_add_co_u32_e32 v70, vcc, s84, v58
	s_setprio 3
	global_load_dwordx4 v[2:5], v[60:61], off offset:3072
	global_load_dwordx4 v[6:9], v[62:63], off offset:3072
	v_addc_co_u32_e32 v71, vcc, 0, v59, vcc
	v_add_co_u32_e32 v72, vcc, s67, v58
	global_load_dwordx4 v[10:13], v[54:55], off offset:3072
	global_load_dwordx4 v[14:17], v[58:59], off
	v_addc_co_u32_e32 v73, vcc, 0, v59, vcc
	v_add_co_u32_e32 v74, vcc, s5, v58
	global_load_dwordx4 v[18:21], v[64:65], off offset:3072
	global_load_dwordx4 v[22:25], v[66:67], off
	v_addc_co_u32_e32 v75, vcc, 0, v59, vcc
	v_add_co_u32_e32 v76, vcc, s85, v58
	global_load_dwordx4 v[26:29], v[68:69], off
	global_load_dwordx4 v[30:33], v[70:71], off
	v_addc_co_u32_e32 v77, vcc, 0, v59, vcc
	v_add_co_u32_e32 v78, vcc, s18, v58
	global_load_dwordx4 v[34:37], v[72:73], off
	global_load_dwordx4 v[38:41], v[74:75], off
	v_addc_co_u32_e32 v79, vcc, 0, v59, vcc
	global_load_dwordx4 v[42:45], v[76:77], off
	global_load_dwordx4 v[46:49], v[78:79], off
	s_movk_i32 s23, 0x90
	v_mad_i64_i32 v[80:81], s[38:39], v50, s60, 0
	v_mul_lo_u32 v50, v50, s23
	v_add3_u32 v191, 0, v50, v52
	s_waitcnt lgkmcnt(0)
	s_barrier
	v_and_b32_e32 v51, 31, v82
	v_lshrrev_b32_e32 v53, 1, v82
	s_mov_b32 s5, 0xfffffc0
	v_and_or_b32 v83, v53, s5, v51
	v_lshlrev_b32_e32 v82, 1, v82
	s_movk_i32 s5, 0x80
	v_and_or_b32 v51, v82, s5, v51
	v_mul_lo_u32 v83, v83, s23
	v_and_b32_e32 v53, 16, v53
	v_mul_u32_u24_e32 v51, 0x90, v51
	v_add3_u32 v189, 0, v83, v53
	v_add3_u32 v190, 0, v51, v53
	s_mov_b32 s5, 0
	s_waitcnt vmcnt(9)
	ds_write_b128 v191, v[10:13]
	ds_write_b128 v191, v[2:5] offset:4608
	ds_write_b128 v191, v[6:9] offset:9216
	s_waitcnt vmcnt(7)
	ds_write_b128 v191, v[18:21] offset:13824
	ds_write_b128 v191, v[14:17] offset:18432
	s_waitcnt vmcnt(6)
	ds_write_b128 v191, v[22:25] offset:23040
	s_waitcnt vmcnt(5)
	ds_write_b128 v191, v[26:29] offset:27648
	s_waitcnt vmcnt(4)
	ds_write_b128 v191, v[30:33] offset:32256
	s_waitcnt vmcnt(3)
	ds_write_b128 v191, v[34:37] offset:36864
	s_waitcnt vmcnt(2)
	ds_write_b128 v191, v[38:41] offset:41472
	s_waitcnt vmcnt(1)
	ds_write_b128 v191, v[42:45] offset:46080
	s_waitcnt vmcnt(0)
	ds_write_b128 v191, v[46:49] offset:50688
	global_load_dwordx4 v[134:137], v[60:61], off offset:3200
	global_load_dwordx4 v[138:141], v[62:63], off offset:3200
	global_load_dwordx4 v[130:133], v[54:55], off offset:3200
	global_load_dwordx4 v[146:149], v[58:59], off offset:128
	global_load_dwordx4 v[142:145], v[64:65], off offset:3200
	global_load_dwordx4 v[150:153], v[66:67], off offset:128
	global_load_dwordx4 v[154:157], v[68:69], off offset:128
	global_load_dwordx4 v[158:161], v[70:71], off offset:128
	global_load_dwordx4 v[162:165], v[72:73], off offset:128
	global_load_dwordx4 v[166:169], v[74:75], off offset:128
	global_load_dwordx4 v[170:173], v[76:77], off offset:128
	global_load_dwordx4 v[174:177], v[78:79], off offset:128
	v_lshl_add_u64 v[2:3], s[6:7], 0, v[56:57]
	v_or_b32_e32 v2, v2, v52
	v_lshl_add_u64 v[182:183], s[0:1], 0, v[2:3]
	v_mov_b32_e32 v2, 0xf8000
	v_mad_i64_i32 v[2:3], s[6:7], s15, v2, v[80:81]
	s_waitcnt lgkmcnt(0)
	s_barrier
; __device__ __forceinline__ void gemm_big(const bf16_t* __restrict__ A, long lda, const bf16_t* __restrict__ Bt, int K, f32x16 (&acc)[2][4], unsigned char* lds) {
;     ...
;     const bf16_t* ap = A + (long)lrow * lda + lc * 8;
;     const bf16_t* bp = Bt + (long)lrow * K + lc * 8;
	v_or_b32_e32 v2, v2, v52
	v_lshl_add_u64 v[184:185], s[0:1], 0, v[2:3]
	v_mov_b32_e32 v2, 0
	s_mov_b64 s[6:7], 0
	v_mov_b32_e32 v3, v2
	v_mov_b32_e32 v4, v2
	v_mov_b32_e32 v5, v2
	v_mov_b32_e32 v6, v2
	v_mov_b32_e32 v7, v2
	v_mov_b32_e32 v8, v2
	v_mov_b32_e32 v9, v2
	v_mov_b32_e32 v10, v2
	v_mov_b32_e32 v11, v2
	v_mov_b32_e32 v12, v2
	v_mov_b32_e32 v13, v2
	v_mov_b32_e32 v14, v2
	v_mov_b32_e32 v15, v2
	v_mov_b32_e32 v16, v2
	v_mov_b32_e32 v17, v2
	v_mov_b32_e32 v66, v2
	v_mov_b32_e32 v67, v2
	v_mov_b32_e32 v68, v2
	v_mov_b32_e32 v69, v2
	v_mov_b32_e32 v70, v2
	v_mov_b32_e32 v71, v2
	v_mov_b32_e32 v72, v2
	v_mov_b32_e32 v73, v2
	v_mov_b32_e32 v74, v2
	v_mov_b32_e32 v75, v2
	v_mov_b32_e32 v76, v2
	v_mov_b32_e32 v77, v2
	v_mov_b32_e32 v78, v2
	v_mov_b32_e32 v79, v2
	v_mov_b32_e32 v80, v2
	v_mov_b32_e32 v81, v2
	v_mov_b32_e32 v18, v2
	v_mov_b32_e32 v19, v2
	v_mov_b32_e32 v20, v2
	v_mov_b32_e32 v21, v2
	v_mov_b32_e32 v22, v2
	v_mov_b32_e32 v23, v2
	v_mov_b32_e32 v24, v2
	v_mov_b32_e32 v25, v2
	v_mov_b32_e32 v26, v2
	v_mov_b32_e32 v27, v2
	v_mov_b32_e32 v28, v2
	v_mov_b32_e32 v29, v2
	v_mov_b32_e32 v30, v2
	v_mov_b32_e32 v31, v2
	v_mov_b32_e32 v32, v2
	v_mov_b32_e32 v33, v2
	v_mov_b32_e32 v82, v2
	v_mov_b32_e32 v83, v2
	v_mov_b32_e32 v84, v2
	v_mov_b32_e32 v85, v2
	v_mov_b32_e32 v86, v2
	v_mov_b32_e32 v87, v2
	v_mov_b32_e32 v88, v2
	v_mov_b32_e32 v89, v2
	v_mov_b32_e32 v90, v2
	v_mov_b32_e32 v91, v2
	v_mov_b32_e32 v92, v2
	v_mov_b32_e32 v93, v2
	v_mov_b32_e32 v94, v2
	v_mov_b32_e32 v95, v2
	v_mov_b32_e32 v96, v2
	v_mov_b32_e32 v97, v2
	v_mov_b32_e32 v34, v2
	v_mov_b32_e32 v35, v2
	v_mov_b32_e32 v36, v2
	v_mov_b32_e32 v37, v2
	v_mov_b32_e32 v38, v2
	v_mov_b32_e32 v39, v2
	v_mov_b32_e32 v40, v2
	v_mov_b32_e32 v41, v2
	v_mov_b32_e32 v42, v2
	v_mov_b32_e32 v43, v2
	v_mov_b32_e32 v44, v2
	v_mov_b32_e32 v45, v2
	v_mov_b32_e32 v46, v2
	v_mov_b32_e32 v47, v2
	v_mov_b32_e32 v48, v2
	v_mov_b32_e32 v49, v2
	v_mov_b32_e32 v98, v2
	v_mov_b32_e32 v99, v2
	v_mov_b32_e32 v100, v2
	v_mov_b32_e32 v101, v2
	v_mov_b32_e32 v102, v2
	v_mov_b32_e32 v103, v2
	v_mov_b32_e32 v104, v2
	v_mov_b32_e32 v105, v2
	v_mov_b32_e32 v106, v2
	v_mov_b32_e32 v107, v2
	v_mov_b32_e32 v108, v2
	v_mov_b32_e32 v109, v2
	v_mov_b32_e32 v110, v2
	v_mov_b32_e32 v111, v2
	v_mov_b32_e32 v112, v2
	v_mov_b32_e32 v113, v2
	v_mov_b32_e32 v50, v2
	v_mov_b32_e32 v51, v2
	v_mov_b32_e32 v52, v2
	v_mov_b32_e32 v53, v2
	v_mov_b32_e32 v54, v2
	v_mov_b32_e32 v55, v2
	v_mov_b32_e32 v56, v2
	v_mov_b32_e32 v57, v2
	v_mov_b32_e32 v58, v2
	v_mov_b32_e32 v59, v2
	v_mov_b32_e32 v60, v2
	v_mov_b32_e32 v61, v2
	v_mov_b32_e32 v62, v2
	v_mov_b32_e32 v63, v2
	v_mov_b32_e32 v64, v2
	v_mov_b32_e32 v65, v2
	v_mov_b32_e32 v114, v2
	v_mov_b32_e32 v115, v2
	v_mov_b32_e32 v116, v2
	v_mov_b32_e32 v117, v2
	v_mov_b32_e32 v118, v2
	v_mov_b32_e32 v119, v2
	v_mov_b32_e32 v120, v2
	v_mov_b32_e32 v121, v2
	v_mov_b32_e32 v122, v2
	v_mov_b32_e32 v123, v2
	v_mov_b32_e32 v124, v2
	v_mov_b32_e32 v125, v2
	v_mov_b32_e32 v126, v2
	v_mov_b32_e32 v127, v2
	v_mov_b32_e32 v128, v2
	v_mov_b32_e32 v129, v2
	s_setprio 0
	s_branch .LBB0_283

; __device__ __forceinline__ void lds_barrier() { asm volatile("s_waitcnt lgkmcnt(0)\n\ts_barrier" ::: "memory"); }
; __device__ __forceinline__ f32x16 mfma32(bf16x8 a, bf16x8 b, f32x16 c) { return __builtin_amdgcn_mfma_f32_32x32x16_bf16(a, b, c, 0, 0, 0); }
; __device__ __forceinline__ void gemm_big(const bf16_t* __restrict__ A, long lda, const bf16_t* __restrict__ Bt, int K, f32x16 (&acc)[2][4], unsigned char* lds) {
;     ...
;     for (int kc = 0; kc < nk; ++kc) {
;         bf16x8 af[2][2], bfr[2][4];
;         af[0][0] = *(const bf16x8*)(Ac); af[0][1] = *(const bf16x8*)(Ac + 32 * GLD);
; #pragma unroll
;         for (int ni = 0; ni < 4; ++ni) bfr[0][ni] = *(const bf16x8*)(Bc + ni * 32 * GLD);
;         __builtin_amdgcn_s_setprio(3);
; #pragma unroll
;         for (int ks = 0; ks < 4; ++ks) {
;             const int cb = ks & 1, nb = cb ^ 1;
;             if (ks < 3) {
;                 af[nb][0] = *(const bf16x8*)(Ac + (ks + 1) * 16); af[nb][1] = *(const bf16x8*)(Ac + 32 * GLD + (ks + 1) * 16);
; #pragma unroll
;                 for (int ni = 0; ni < 4; ++ni) bfr[nb][ni] = *(const bf16x8*)(Bc + ni * 32 * GLD + (ks + 1) * 16);
;             }
;             __builtin_amdgcn_sched_barrier(0);
; #pragma unroll
;             for (int ni = 0; ni < 4; ++ni) { acc[0][ni] = mfma32(af[cb][0], bfr[cb][ni], acc[0][ni]); acc[1][ni] = mfma32(af[cb][1], bfr[cb][ni], acc[1][ni]); }
;             __builtin_amdgcn_sched_barrier(0);
;         }
;         __builtin_amdgcn_s_setprio(0);
;         lds_barrier();
;         if (kc + 1 < nk) {
;             lstore();
;             if (kc + 2 < nk) gload(kc + 2);
;             lds_barrier();
;         }
.Lmy_gorig_3:
	ds_read_b128 v[192:195], v189
	ds_read_b128 v[196:199], v189 offset:4608
	ds_read_b128 v[200:203], v190 offset:18432
	ds_read_b128 v[204:207], v190 offset:23040
	ds_read_b128 v[208:211], v190 offset:27648
	ds_read_b128 v[212:215], v190 offset:32256
	ds_read_b128 v[216:219], v189 offset:32
	ds_read_b128 v[224:227], v189 offset:4640
	ds_read_b128 v[234:237], v190 offset:18464
	ds_read_b128 v[238:241], v190 offset:23072
	ds_read_b128 v[242:245], v190 offset:27680
	ds_read_b128 v[246:249], v190 offset:32288
	s_waitcnt lgkmcnt(9)
	v_mfma_f32_32x32x16_bf16 v[114:129], v[192:195], v[200:203], v[114:129]
	v_mfma_f32_32x32x16_bf16 v[50:65], v[196:199], v[200:203], v[50:65]
	s_waitcnt lgkmcnt(8)
	v_mfma_f32_32x32x16_bf16 v[98:113], v[192:195], v[204:207], v[98:113]
	v_mfma_f32_32x32x16_bf16 v[34:49], v[196:199], v[204:207], v[34:49]
	s_waitcnt lgkmcnt(7)
	v_mfma_f32_32x32x16_bf16 v[82:97], v[192:195], v[208:211], v[82:97]
	v_mfma_f32_32x32x16_bf16 v[18:33], v[196:199], v[208:211], v[18:33]
	s_waitcnt lgkmcnt(6)
	v_mfma_f32_32x32x16_bf16 v[66:81], v[192:195], v[212:215], v[66:81]
	v_mfma_f32_32x32x16_bf16 v[2:17], v[196:199], v[212:215], v[2:17]
	ds_read_b128 v[192:195], v189 offset:64
	ds_read_b128 v[196:199], v189 offset:4672
	ds_read_b128 v[200:203], v190 offset:18496
	ds_read_b128 v[204:207], v190 offset:23104
	ds_read_b128 v[208:211], v190 offset:27712
	ds_read_b128 v[212:215], v190 offset:32320
	s_waitcnt lgkmcnt(9)
	v_mfma_f32_32x32x16_bf16 v[114:129], v[216:219], v[234:237], v[114:129]
	v_mfma_f32_32x32x16_bf16 v[50:65], v[224:227], v[234:237], v[50:65]
	s_waitcnt lgkmcnt(8)
	v_mfma_f32_32x32x16_bf16 v[98:113], v[216:219], v[238:241], v[98:113]
	v_mfma_f32_32x32x16_bf16 v[34:49], v[224:227], v[238:241], v[34:49]
	s_waitcnt lgkmcnt(7)
	v_mfma_f32_32x32x16_bf16 v[82:97], v[216:219], v[242:245], v[82:97]
	v_mfma_f32_32x32x16_bf16 v[18:33], v[224:227], v[242:245], v[18:33]
	s_waitcnt lgkmcnt(6)
	v_mfma_f32_32x32x16_bf16 v[66:81], v[216:219], v[246:249], v[66:81]
	v_mfma_f32_32x32x16_bf16 v[2:17], v[224:227], v[246:249], v[2:17]
	ds_read_b128 v[216:219], v189 offset:96
	ds_read_b128 v[224:227], v189 offset:4704
	ds_read_b128 v[234:237], v190 offset:18528
	ds_read_b128 v[238:241], v190 offset:23136
	ds_read_b128 v[242:245], v190 offset:27744
	ds_read_b128 v[246:249], v190 offset:32352
	s_waitcnt lgkmcnt(9)
	v_mfma_f32_32x32x16_bf16 v[114:129], v[192:195], v[200:203], v[114:129]
	v_mfma_f32_32x32x16_bf16 v[50:65], v[196:199], v[200:203], v[50:65]
	s_waitcnt lgkmcnt(8)
	v_mfma_f32_32x32x16_bf16 v[98:113], v[192:195], v[204:207], v[98:113]
	v_mfma_f32_32x32x16_bf16 v[34:49], v[196:199], v[204:207], v[34:49]
	s_waitcnt lgkmcnt(7)
	v_mfma_f32_32x32x16_bf16 v[82:97], v[192:195], v[208:211], v[82:97]
	v_mfma_f32_32x32x16_bf16 v[18:33], v[196:199], v[208:211], v[18:33]
	s_waitcnt lgkmcnt(6)
	v_mfma_f32_32x32x16_bf16 v[66:81], v[192:195], v[212:215], v[66:81]
	v_mfma_f32_32x32x16_bf16 v[2:17], v[196:199], v[212:215], v[2:17]
	s_waitcnt lgkmcnt(3)
	v_mfma_f32_32x32x16_bf16 v[114:129], v[216:219], v[234:237], v[114:129]
	v_mfma_f32_32x32x16_bf16 v[50:65], v[224:227], v[234:237], v[50:65]
	s_waitcnt lgkmcnt(2)
	v_mfma_f32_32x32x16_bf16 v[98:113], v[216:219], v[238:241], v[98:113]
	v_mfma_f32_32x32x16_bf16 v[34:49], v[224:227], v[238:241], v[34:49]
	s_waitcnt lgkmcnt(1)
	v_mfma_f32_32x32x16_bf16 v[82:97], v[216:219], v[242:245], v[82:97]
	v_mfma_f32_32x32x16_bf16 v[18:33], v[224:227], v[242:245], v[18:33]
	s_waitcnt lgkmcnt(0)
	v_mfma_f32_32x32x16_bf16 v[66:81], v[216:219], v[246:249], v[66:81]
	v_mfma_f32_32x32x16_bf16 v[2:17], v[224:227], v[246:249], v[2:17]
	s_setprio 0
	s_waitcnt lgkmcnt(0)
	s_barrier
	s_cmp_gt_u32 s5, 2
	s_cbranch_scc1 .LBB0_282
	s_cmpk_eq_i32 s6, 0x100
	s_waitcnt vmcnt(9)
	ds_write_b128 v191, v[130:133]
	ds_write_b128 v191, v[134:137] offset:4608
	ds_write_b128 v191, v[138:141] offset:9216
	s_waitcnt vmcnt(7)
	ds_write_b128 v191, v[142:145] offset:13824
	ds_write_b128 v191, v[146:149] offset:18432
	s_waitcnt vmcnt(6)
	ds_write_b128 v191, v[150:153] offset:23040
	s_waitcnt vmcnt(5)
	ds_write_b128 v191, v[154:157] offset:27648
	s_waitcnt vmcnt(4)
	ds_write_b128 v191, v[158:161] offset:32256
	s_waitcnt vmcnt(3)
	ds_write_b128 v191, v[162:165] offset:36864
	s_waitcnt vmcnt(2)
	ds_write_b128 v191, v[166:169] offset:41472
	s_waitcnt vmcnt(1)
	ds_write_b128 v191, v[170:173] offset:46080
	s_waitcnt vmcnt(0)
	ds_write_b128 v191, v[174:177] offset:50688
	s_cbranch_scc1 .LBB0_281
	v_lshl_add_u64 v[138:139], v[184:185], 0, s[6:7]
	v_add_co_u32_e32 v130, vcc, 0x78a8000, v138
	v_lshl_add_u64 v[170:171], v[182:183], 0, s[6:7]
	s_nop 0
	v_addc_co_u32_e32 v131, vcc, 0, v139, vcc
	v_add_co_u32_e32 v134, vcc, 0x78e6000, v138
	s_nop 1
	v_addc_co_u32_e32 v135, vcc, 0, v139, vcc
	v_add_co_u32_e32 v140, vcc, 0x7924000, v138
	global_load_dwordx4 v[130:133], v[130:131], off offset:3328
	s_nop 0
	global_load_dwordx4 v[134:137], v[134:135], off offset:3328
	v_addc_co_u32_e32 v141, vcc, 0, v139, vcc
	v_add_co_u32_e32 v142, vcc, 0x7962000, v138
	s_nop 1
	v_addc_co_u32_e32 v143, vcc, 0, v139, vcc
	v_add_co_u32_e32 v146, vcc, 0x2288000, v170
	global_load_dwordx4 v[138:141], v[140:141], off offset:3328
	s_nop 0
	global_load_dwordx4 v[142:145], v[142:143], off offset:3328
	v_addc_co_u32_e32 v147, vcc, 0, v171, vcc
	v_add_co_u32_e32 v150, vcc, 0x228c000, v170
	s_nop 1
	v_addc_co_u32_e32 v151, vcc, 0, v171, vcc
	v_add_co_u32_e32 v154, vcc, 0x2290000, v170
	global_load_dwordx4 v[146:149], v[146:147], off offset:256
	s_nop 0
	global_load_dwordx4 v[150:153], v[150:151], off offset:256
	v_addc_co_u32_e32 v155, vcc, 0, v171, vcc
	v_add_co_u32_e32 v158, vcc, 0x2294000, v170
	s_nop 1
	v_addc_co_u32_e32 v159, vcc, 0, v171, vcc
	v_add_co_u32_e32 v162, vcc, 0x2298000, v170
	global_load_dwordx4 v[154:157], v[154:155], off offset:256
	s_nop 0
	global_load_dwordx4 v[158:161], v[158:159], off offset:256
	v_addc_co_u32_e32 v163, vcc, 0, v171, vcc
	v_add_co_u32_e32 v166, vcc, 0x229c000, v170
	s_nop 1
	v_addc_co_u32_e32 v167, vcc, 0, v171, vcc
	v_add_co_u32_e32 v172, vcc, 0x22a0000, v170
	global_load_dwordx4 v[162:165], v[162:163], off offset:256
	s_nop 0
	global_load_dwordx4 v[166:169], v[166:167], off offset:256
	v_addc_co_u32_e32 v173, vcc, 0, v171, vcc
	v_add_co_u32_e32 v174, vcc, 0x22a4000, v170
	s_nop 1
	v_addc_co_u32_e32 v175, vcc, 0, v171, vcc
	global_load_dwordx4 v[170:173], v[172:173], off offset:256
	s_nop 0
	global_load_dwordx4 v[174:177], v[174:175], off offset:256
	s_branch .LBB0_281

; __device__ __forceinline__ void lds_barrier() { asm volatile("s_waitcnt lgkmcnt(0)\n\ts_barrier" ::: "memory"); }
; __device__ __forceinline__ void gemm_big(const bf16_t* __restrict__ A, long lda, const bf16_t* __restrict__ Bt, int K, f32x16 (&acc)[2][4], unsigned char* lds) {
;     ...
;     const bf16_t* ap = A + (long)lrow * lda + lc * 8;
;     const bf16_t* bp = Bt + (long)lrow * K + lc * 8;
;     u32x4 ra[4], rb[8];
;     auto gload = [&](int kc) {
; #pragma unroll
;         for (int i = 0; i < 4; ++i) ra[i] = *(const u32x4*)(ap + (long)(32 * i) * lda + kc * 64);
; #pragma unroll
;         for (int i = 0; i < 8; ++i) rb[i] = *(const u32x4*)(bp + (long)(32 * i) * K + kc * 64);
;     };
;     auto lstore = [&]() {
; #pragma unroll
;         for (int i = 0; i < 4; ++i) *(u32x4*)(As + (lrow + 32 * i) * GLD + lc * 8) = ra[i];
; #pragma unroll
;         for (int i = 0; i < 8; ++i) *(u32x4*)(Bs + (lrow + 32 * i) * GLD + lc * 8) = rb[i];
;     };
;     const bf16_t* Ac = As + (wr * 64 + r) * GLD + h * 8;
;     const bf16_t* Bc = Bs + (wc * 128 + r) * GLD + h * 8;
;     gload(0);
;     __syncthreads();
;     lstore();
;     if (nk > 1) gload(1);
;     lds_barrier();
.LBB0_675:
	s_ashr_i32 s31, s30, 31
	v_mov_b32_e32 v78, v179
	s_lshl_b64 s[0:1], s[30:31], 18
	s_add_u32 s6, s10, s0
	s_waitcnt vmcnt(27)
	v_ashrrev_i32_e32 v50, 3, v78
	s_waitcnt vmcnt(26)
	v_ashrrev_i32_e32 v51, 31, v50
	s_addc_u32 s7, s11, s1
	s_waitcnt vmcnt(24)
	v_lshlrev_b64 v[52:53], 11, v[50:51]
	v_lshlrev_b32_e32 v0, 4, v78
	v_lshl_add_u64 v[2:3], s[6:7], 0, v[52:53]
	v_and_b32_e32 v0, 0x70, v0
	v_lshl_add_u64 v[54:55], v[2:3], 0, v[0:1]
	s_ashr_i32 s29, s28, 31
	v_add_co_u32_e32 v58, vcc, s67, v54
	s_lshl_b64 s[4:5], s[28:29], 19
	s_nop 0
	v_addc_co_u32_e32 v59, vcc, 0, v55, vcc
	s_mov_b32 s6, 0x20000
	s_add_u32 s8, s12, s4
	v_add_co_u32_e32 v60, vcc, s6, v54
	s_addc_u32 s9, s13, s5
	s_nop 0
	v_addc_co_u32_e32 v61, vcc, 0, v55, vcc
	s_mov_b32 s7, 0x30000
	v_lshl_add_u64 v[2:3], s[8:9], 0, v[52:53]
	s_waitcnt vmcnt(23)
	v_add_co_u32_e32 v62, vcc, s7, v54
	v_lshl_add_u64 v[56:57], v[2:3], 0, v[0:1]
	s_waitcnt vmcnt(22)
	v_addc_co_u32_e32 v63, vcc, 0, v55, vcc
	s_waitcnt vmcnt(21)
	v_add_co_u32_e32 v64, vcc, s67, v56
	s_setprio 3
	global_load_dwordx4 v[2:5], v[58:59], off
	global_load_dwordx4 v[6:9], v[60:61], off
	s_waitcnt vmcnt(22)
	v_addc_co_u32_e32 v65, vcc, 0, v57, vcc
	s_waitcnt vmcnt(21)
	v_add_co_u32_e32 v66, vcc, s6, v56
	s_mov_b32 s6, 0x40000
	s_waitcnt vmcnt(20)
	v_addc_co_u32_e32 v67, vcc, 0, v57, vcc
	s_waitcnt vmcnt(19)
	v_add_co_u32_e32 v68, vcc, s7, v56
	global_load_dwordx4 v[10:13], v[54:55], off
	global_load_dwordx4 v[14:17], v[56:57], off
	s_waitcnt vmcnt(20)
	v_addc_co_u32_e32 v69, vcc, 0, v57, vcc
	v_add_co_u32_e32 v70, vcc, s6, v56
	s_mov_b32 s6, 0x50000
	s_nop 0
	v_addc_co_u32_e32 v71, vcc, 0, v57, vcc
	v_add_co_u32_e32 v72, vcc, s6, v56
	s_mov_b32 s6, 0x60000
	s_nop 0
	v_addc_co_u32_e32 v73, vcc, 0, v57, vcc
	v_add_co_u32_e32 v74, vcc, s6, v56
	s_mov_b32 s6, 0x70000
	s_nop 0
	v_addc_co_u32_e32 v75, vcc, 0, v57, vcc
	v_add_co_u32_e32 v76, vcc, s6, v56
	global_load_dwordx4 v[18:21], v[62:63], off
	global_load_dwordx4 v[22:25], v[64:65], off
	global_load_dwordx4 v[26:29], v[66:67], off
	global_load_dwordx4 v[30:33], v[68:69], off
	global_load_dwordx4 v[34:37], v[70:71], off
	global_load_dwordx4 v[38:41], v[72:73], off
	v_addc_co_u32_e32 v77, vcc, 0, v57, vcc
	global_load_dwordx4 v[42:45], v[74:75], off
	global_load_dwordx4 v[46:49], v[76:77], off
	v_and_b32_e32 v51, 31, v78
	v_lshrrev_b32_e32 v79, 1, v78
	s_mov_b32 s7, 0xfffffc0
	v_lshlrev_b32_e32 v78, 1, v78
	v_and_or_b32 v80, v79, s7, v51
	s_movk_i32 s7, 0x80
	v_and_or_b32 v51, v78, s7, v51
	s_movk_i32 s7, 0x90
	v_mul_lo_u32 v50, v50, s7
	v_add3_u32 v188, 0, v50, v0
	s_barrier
	v_and_b32_e32 v79, 16, v79
	v_mul_lo_u32 v78, v80, s7
	v_mul_u32_u24_e32 v51, 0x90, v51
	s_mov_b32 s6, 0
	v_add3_u32 v189, 0, v78, v79
	v_add3_u32 v190, 0, v51, v79
	s_waitcnt vmcnt(9)
	ds_write_b128 v188, v[10:13]
	ds_write_b128 v188, v[2:5] offset:4608
	ds_write_b128 v188, v[6:9] offset:9216
	s_waitcnt vmcnt(7)
	ds_write_b128 v188, v[18:21] offset:13824
	ds_write_b128 v188, v[14:17] offset:18432
	s_waitcnt vmcnt(6)
	ds_write_b128 v188, v[22:25] offset:23040
	s_waitcnt vmcnt(5)
	ds_write_b128 v188, v[26:29] offset:27648
	s_waitcnt vmcnt(4)
	ds_write_b128 v188, v[30:33] offset:32256
	s_waitcnt vmcnt(3)
	ds_write_b128 v188, v[34:37] offset:36864
	s_waitcnt vmcnt(2)
	ds_write_b128 v188, v[38:41] offset:41472
	s_waitcnt vmcnt(1)
	ds_write_b128 v188, v[42:45] offset:46080
	s_waitcnt vmcnt(0)
	ds_write_b128 v188, v[46:49] offset:50688
	global_load_dwordx4 v[134:137], v[58:59], off offset:128
	global_load_dwordx4 v[138:141], v[60:61], off offset:128
	global_load_dwordx4 v[130:133], v[54:55], off offset:128
	global_load_dwordx4 v[146:149], v[56:57], off offset:128
	global_load_dwordx4 v[142:145], v[62:63], off offset:128
	global_load_dwordx4 v[150:153], v[64:65], off offset:128
	global_load_dwordx4 v[154:157], v[66:67], off offset:128
	global_load_dwordx4 v[158:161], v[68:69], off offset:128
	global_load_dwordx4 v[162:165], v[70:71], off offset:128
	global_load_dwordx4 v[166:169], v[72:73], off offset:128
	global_load_dwordx4 v[170:173], v[74:75], off offset:128
	global_load_dwordx4 v[174:177], v[76:77], off offset:128
	v_lshl_add_u64 v[2:3], s[4:5], 0, v[52:53]
	v_or_b32_e32 v2, v2, v0
	v_lshl_add_u64 v[182:183], s[20:21], 0, v[2:3]
	v_lshl_add_u64 v[2:3], s[0:1], 0, v[52:53]
	s_waitcnt lgkmcnt(0)
	s_barrier
; __device__ __forceinline__ void gemm_big(const bf16_t* __restrict__ A, long lda, const bf16_t* __restrict__ Bt, int K, f32x16 (&acc)[2][4], unsigned char* lds) {
;     ...
;     const bf16_t* ap = A + (long)lrow * lda + lc * 8;
;     const bf16_t* bp = Bt + (long)lrow * K + lc * 8;
	v_or_b32_e32 v2, v2, v0
	v_lshl_add_u64 v[184:185], s[26:27], 0, v[2:3]
	v_mov_b32_e32 v2, 0
	s_mov_b64 s[0:1], 0
	v_mov_b32_e32 v3, v2
	v_mov_b32_e32 v4, v2
	v_mov_b32_e32 v5, v2
	v_mov_b32_e32 v6, v2
	v_mov_b32_e32 v7, v2
	v_mov_b32_e32 v8, v2
	v_mov_b32_e32 v9, v2
	v_mov_b32_e32 v10, v2
	v_mov_b32_e32 v11, v2
	v_mov_b32_e32 v12, v2
	v_mov_b32_e32 v13, v2
	v_mov_b32_e32 v14, v2
	v_mov_b32_e32 v15, v2
	v_mov_b32_e32 v16, v2
	v_mov_b32_e32 v17, v2
	v_mov_b32_e32 v18, v2
	v_mov_b32_e32 v19, v2
	v_mov_b32_e32 v20, v2
	v_mov_b32_e32 v21, v2
	v_mov_b32_e32 v22, v2
	v_mov_b32_e32 v23, v2
	v_mov_b32_e32 v24, v2
	v_mov_b32_e32 v25, v2
	v_mov_b32_e32 v26, v2
	v_mov_b32_e32 v27, v2
	v_mov_b32_e32 v28, v2
	v_mov_b32_e32 v29, v2
	v_mov_b32_e32 v30, v2
	v_mov_b32_e32 v31, v2
	v_mov_b32_e32 v32, v2
	v_mov_b32_e32 v33, v2
	v_mov_b32_e32 v34, v2
	v_mov_b32_e32 v35, v2
	v_mov_b32_e32 v36, v2
	v_mov_b32_e32 v37, v2
	v_mov_b32_e32 v38, v2
	v_mov_b32_e32 v39, v2
	v_mov_b32_e32 v40, v2
	v_mov_b32_e32 v41, v2
	v_mov_b32_e32 v42, v2
	v_mov_b32_e32 v43, v2
	v_mov_b32_e32 v44, v2
	v_mov_b32_e32 v45, v2
	v_mov_b32_e32 v46, v2
	v_mov_b32_e32 v47, v2
	v_mov_b32_e32 v48, v2
	v_mov_b32_e32 v49, v2
	v_mov_b32_e32 v50, v2
	v_mov_b32_e32 v51, v2
	v_mov_b32_e32 v52, v2
	v_mov_b32_e32 v53, v2
	v_mov_b32_e32 v54, v2
	v_mov_b32_e32 v55, v2
	v_mov_b32_e32 v56, v2
	v_mov_b32_e32 v57, v2
	v_mov_b32_e32 v58, v2
	v_mov_b32_e32 v59, v2
	v_mov_b32_e32 v60, v2
	v_mov_b32_e32 v61, v2
	v_mov_b32_e32 v62, v2
	v_mov_b32_e32 v63, v2
	v_mov_b32_e32 v64, v2
	v_mov_b32_e32 v65, v2
	v_mov_b32_e32 v66, v2
	v_mov_b32_e32 v67, v2
	v_mov_b32_e32 v68, v2
	v_mov_b32_e32 v69, v2
	v_mov_b32_e32 v70, v2
	v_mov_b32_e32 v71, v2
	v_mov_b32_e32 v72, v2
	v_mov_b32_e32 v73, v2
	v_mov_b32_e32 v74, v2
	v_mov_b32_e32 v75, v2
	v_mov_b32_e32 v76, v2
	v_mov_b32_e32 v77, v2
	v_mov_b32_e32 v78, v2
	v_mov_b32_e32 v79, v2
	v_mov_b32_e32 v80, v2
	v_mov_b32_e32 v81, v2
	v_mov_b32_e32 v82, v2
	v_mov_b32_e32 v83, v2
	v_mov_b32_e32 v84, v2
	v_mov_b32_e32 v85, v2
	v_mov_b32_e32 v86, v2
	v_mov_b32_e32 v87, v2
	v_mov_b32_e32 v88, v2
	v_mov_b32_e32 v89, v2
	v_mov_b32_e32 v90, v2
	v_mov_b32_e32 v91, v2
	v_mov_b32_e32 v92, v2
	v_mov_b32_e32 v93, v2
	v_mov_b32_e32 v94, v2
	v_mov_b32_e32 v95, v2
	v_mov_b32_e32 v96, v2
	v_mov_b32_e32 v97, v2
	v_mov_b32_e32 v98, v2
	v_mov_b32_e32 v99, v2
	v_mov_b32_e32 v100, v2
	v_mov_b32_e32 v101, v2
	v_mov_b32_e32 v102, v2
	v_mov_b32_e32 v103, v2
	v_mov_b32_e32 v104, v2
	v_mov_b32_e32 v105, v2
	v_mov_b32_e32 v106, v2
	v_mov_b32_e32 v107, v2
	v_mov_b32_e32 v108, v2
	v_mov_b32_e32 v109, v2
	v_mov_b32_e32 v110, v2
	v_mov_b32_e32 v111, v2
	v_mov_b32_e32 v112, v2
	v_mov_b32_e32 v113, v2
	v_mov_b32_e32 v114, v2
	v_mov_b32_e32 v115, v2
	v_mov_b32_e32 v116, v2
	v_mov_b32_e32 v117, v2
	v_mov_b32_e32 v118, v2
	v_mov_b32_e32 v119, v2
	v_mov_b32_e32 v120, v2
	v_mov_b32_e32 v121, v2
	v_mov_b32_e32 v122, v2
	v_mov_b32_e32 v123, v2
	v_mov_b32_e32 v124, v2
	v_mov_b32_e32 v125, v2
	v_mov_b32_e32 v126, v2
	v_mov_b32_e32 v127, v2
	v_mov_b32_e32 v128, v2
	v_mov_b32_e32 v129, v2
	s_setprio 0
	s_branch .LBB0_678

; __device__ __forceinline__ void lds_barrier() { asm volatile("s_waitcnt lgkmcnt(0)\n\ts_barrier" ::: "memory"); }
; __device__ __forceinline__ f32x16 mfma32(bf16x8 a, bf16x8 b, f32x16 c) { return __builtin_amdgcn_mfma_f32_32x32x16_bf16(a, b, c, 0, 0, 0); }
; __device__ __forceinline__ void gemm_big(const bf16_t* __restrict__ A, long lda, const bf16_t* __restrict__ Bt, int K, f32x16 (&acc)[2][4], unsigned char* lds) {
;     ...
;     for (int kc = 0; kc < nk; ++kc) {
;         bf16x8 af[2][2], bfr[2][4];
;         af[0][0] = *(const bf16x8*)(Ac); af[0][1] = *(const bf16x8*)(Ac + 32 * GLD);
; #pragma unroll
;         for (int ni = 0; ni < 4; ++ni) bfr[0][ni] = *(const bf16x8*)(Bc + ni * 32 * GLD);
;         __builtin_amdgcn_s_setprio(3);
; #pragma unroll
;         for (int ks = 0; ks < 4; ++ks) {
;             const int cb = ks & 1, nb = cb ^ 1;
;             if (ks < 3) {
;                 af[nb][0] = *(const bf16x8*)(Ac + (ks + 1) * 16); af[nb][1] = *(const bf16x8*)(Ac + 32 * GLD + (ks + 1) * 16);
; #pragma unroll
;                 for (int ni = 0; ni < 4; ++ni) bfr[nb][ni] = *(const bf16x8*)(Bc + ni * 32 * GLD + (ks + 1) * 16);
;             }
;             __builtin_amdgcn_sched_barrier(0);
; #pragma unroll
;             for (int ni = 0; ni < 4; ++ni) { acc[0][ni] = mfma32(af[cb][0], bfr[cb][ni], acc[0][ni]); acc[1][ni] = mfma32(af[cb][1], bfr[cb][ni], acc[1][ni]); }
;             __builtin_amdgcn_sched_barrier(0);
;         }
;         __builtin_amdgcn_s_setprio(0);
;         lds_barrier();
;         if (kc + 1 < nk) {
;             lstore();
;             if (kc + 2 < nk) gload(kc + 2);
;             lds_barrier();
;         }
.Lmy_gorig_2:
	ds_read_b128 v[192:195], v189
	ds_read_b128 v[196:199], v189 offset:4608
	ds_read_b128 v[200:203], v190 offset:18432
	ds_read_b128 v[204:207], v190 offset:23040
	ds_read_b128 v[208:211], v190 offset:27648
	ds_read_b128 v[212:215], v190 offset:32256
	ds_read_b128 v[216:219], v189 offset:32
	ds_read_b128 v[234:237], v189 offset:4640
	ds_read_b128 v[238:241], v190 offset:18464
	ds_read_b128 v[242:245], v190 offset:23072
	ds_read_b128 v[246:249], v190 offset:27680
	ds_read_b128 v[224:227], v190 offset:32288
	s_waitcnt lgkmcnt(9)
	v_mfma_f32_32x32x16_bf16 v[114:129], v[192:195], v[200:203], v[114:129]
	v_mfma_f32_32x32x16_bf16 v[98:113], v[196:199], v[200:203], v[98:113]
	s_waitcnt lgkmcnt(8)
	v_mfma_f32_32x32x16_bf16 v[82:97], v[192:195], v[204:207], v[82:97]
	v_mfma_f32_32x32x16_bf16 v[66:81], v[196:199], v[204:207], v[66:81]
	s_waitcnt lgkmcnt(7)
	v_mfma_f32_32x32x16_bf16 v[50:65], v[192:195], v[208:211], v[50:65]
	v_mfma_f32_32x32x16_bf16 v[34:49], v[196:199], v[208:211], v[34:49]
	s_waitcnt lgkmcnt(6)
	v_mfma_f32_32x32x16_bf16 v[18:33], v[192:195], v[212:215], v[18:33]
	v_mfma_f32_32x32x16_bf16 v[2:17], v[196:199], v[212:215], v[2:17]
	ds_read_b128 v[192:195], v189 offset:64
	ds_read_b128 v[196:199], v189 offset:4672
	ds_read_b128 v[200:203], v190 offset:18496
	ds_read_b128 v[204:207], v190 offset:23104
	ds_read_b128 v[208:211], v190 offset:27712
	ds_read_b128 v[212:215], v190 offset:32320
	s_waitcnt lgkmcnt(9)
	v_mfma_f32_32x32x16_bf16 v[114:129], v[216:219], v[238:241], v[114:129]
	v_mfma_f32_32x32x16_bf16 v[98:113], v[234:237], v[238:241], v[98:113]
	s_waitcnt lgkmcnt(8)
	v_mfma_f32_32x32x16_bf16 v[82:97], v[216:219], v[242:245], v[82:97]
	v_mfma_f32_32x32x16_bf16 v[66:81], v[234:237], v[242:245], v[66:81]
	s_waitcnt lgkmcnt(7)
	v_mfma_f32_32x32x16_bf16 v[50:65], v[216:219], v[246:249], v[50:65]
	v_mfma_f32_32x32x16_bf16 v[34:49], v[234:237], v[246:249], v[34:49]
	s_waitcnt lgkmcnt(6)
	v_mfma_f32_32x32x16_bf16 v[18:33], v[216:219], v[224:227], v[18:33]
	v_mfma_f32_32x32x16_bf16 v[2:17], v[234:237], v[224:227], v[2:17]
	ds_read_b128 v[216:219], v189 offset:96
	ds_read_b128 v[224:227], v189 offset:4704
	ds_read_b128 v[234:237], v190 offset:18528
	ds_read_b128 v[238:241], v190 offset:23136
	ds_read_b128 v[242:245], v190 offset:27744
	ds_read_b128 v[246:249], v190 offset:32352
	s_waitcnt lgkmcnt(9)
	v_mfma_f32_32x32x16_bf16 v[114:129], v[192:195], v[200:203], v[114:129]
	v_mfma_f32_32x32x16_bf16 v[98:113], v[196:199], v[200:203], v[98:113]
	s_waitcnt lgkmcnt(8)
	v_mfma_f32_32x32x16_bf16 v[82:97], v[192:195], v[204:207], v[82:97]
	v_mfma_f32_32x32x16_bf16 v[66:81], v[196:199], v[204:207], v[66:81]
	s_waitcnt lgkmcnt(7)
	v_mfma_f32_32x32x16_bf16 v[50:65], v[192:195], v[208:211], v[50:65]
	v_mfma_f32_32x32x16_bf16 v[34:49], v[196:199], v[208:211], v[34:49]
	s_waitcnt lgkmcnt(6)
	v_mfma_f32_32x32x16_bf16 v[18:33], v[192:195], v[212:215], v[18:33]
	v_mfma_f32_32x32x16_bf16 v[2:17], v[196:199], v[212:215], v[2:17]
	s_waitcnt lgkmcnt(3)
	v_mfma_f32_32x32x16_bf16 v[114:129], v[216:219], v[234:237], v[114:129]
	v_mfma_f32_32x32x16_bf16 v[98:113], v[224:227], v[234:237], v[98:113]
	s_waitcnt lgkmcnt(2)
	v_mfma_f32_32x32x16_bf16 v[82:97], v[216:219], v[238:241], v[82:97]
	v_mfma_f32_32x32x16_bf16 v[66:81], v[224:227], v[238:241], v[66:81]
	s_waitcnt lgkmcnt(1)
	v_mfma_f32_32x32x16_bf16 v[50:65], v[216:219], v[242:245], v[50:65]
	v_mfma_f32_32x32x16_bf16 v[34:49], v[224:227], v[242:245], v[34:49]
	s_waitcnt lgkmcnt(0)
	v_mfma_f32_32x32x16_bf16 v[18:33], v[216:219], v[246:249], v[18:33]
	v_mfma_f32_32x32x16_bf16 v[2:17], v[224:227], v[246:249], v[2:17]
	s_setprio 0
	s_waitcnt lgkmcnt(0)
	s_barrier
	s_cmp_gt_u32 s6, 14
	s_cbranch_scc1 .LBB0_677
	s_cmpk_eq_i32 s0, 0x700
	s_waitcnt vmcnt(9)
	ds_write_b128 v188, v[130:133]
	ds_write_b128 v188, v[134:137] offset:4608
	ds_write_b128 v188, v[138:141] offset:9216
	s_waitcnt vmcnt(7)
	ds_write_b128 v188, v[142:145] offset:13824
	ds_write_b128 v188, v[146:149] offset:18432
	s_waitcnt vmcnt(6)
	ds_write_b128 v188, v[150:153] offset:23040
	s_waitcnt vmcnt(5)
	ds_write_b128 v188, v[154:157] offset:27648
	s_waitcnt vmcnt(4)
	ds_write_b128 v188, v[158:161] offset:32256
	s_waitcnt vmcnt(3)
	ds_write_b128 v188, v[162:165] offset:36864
	s_waitcnt vmcnt(2)
	ds_write_b128 v188, v[166:169] offset:41472
	s_waitcnt vmcnt(1)
	ds_write_b128 v188, v[170:173] offset:46080
	s_waitcnt vmcnt(0)
	ds_write_b128 v188, v[174:177] offset:50688
	s_cbranch_scc1 .LBB0_676
	v_lshl_add_u64 v[138:139], v[184:185], 0, s[0:1]
	v_add_co_u32_e32 v130, vcc, 0x38a8000, v138
	v_lshl_add_u64 v[170:171], v[182:183], 0, s[0:1]
	s_nop 0
	v_addc_co_u32_e32 v131, vcc, 0, v139, vcc
	v_add_co_u32_e32 v134, vcc, 0x38b8000, v138
	s_nop 1
	v_addc_co_u32_e32 v135, vcc, 0, v139, vcc
	v_add_co_u32_e32 v140, vcc, 0x38c8000, v138
	global_load_dwordx4 v[130:133], v[130:131], off offset:256
	s_nop 0
	global_load_dwordx4 v[134:137], v[134:135], off offset:256
	v_addc_co_u32_e32 v141, vcc, 0, v139, vcc
	v_add_co_u32_e32 v142, vcc, 0x38d8000, v138
	s_nop 1
	v_addc_co_u32_e32 v143, vcc, 0, v139, vcc
	v_add_co_u32_e32 v146, vcc, 0x1488000, v170
	global_load_dwordx4 v[138:141], v[140:141], off offset:256
	s_nop 0
	global_load_dwordx4 v[142:145], v[142:143], off offset:256
	v_addc_co_u32_e32 v147, vcc, 0, v171, vcc
	v_add_co_u32_e32 v150, vcc, 0x1498000, v170
	s_nop 1
	v_addc_co_u32_e32 v151, vcc, 0, v171, vcc
	v_add_co_u32_e32 v154, vcc, 0x14a8000, v170
	global_load_dwordx4 v[146:149], v[146:147], off offset:256
	s_nop 0
	global_load_dwordx4 v[150:153], v[150:151], off offset:256
	v_addc_co_u32_e32 v155, vcc, 0, v171, vcc
	v_add_co_u32_e32 v158, vcc, 0x14b8000, v170
	s_nop 1
	v_addc_co_u32_e32 v159, vcc, 0, v171, vcc
	v_add_co_u32_e32 v162, vcc, 0x14c8000, v170
	global_load_dwordx4 v[154:157], v[154:155], off offset:256
	s_nop 0
	global_load_dwordx4 v[158:161], v[158:159], off offset:256
	v_addc_co_u32_e32 v163, vcc, 0, v171, vcc
	v_add_co_u32_e32 v166, vcc, 0x14d8000, v170
	s_nop 1
	v_addc_co_u32_e32 v167, vcc, 0, v171, vcc
	v_add_co_u32_e32 v172, vcc, 0x14e8000, v170
	global_load_dwordx4 v[162:165], v[162:163], off offset:256
	s_nop 0
	global_load_dwordx4 v[166:169], v[166:167], off offset:256
	v_addc_co_u32_e32 v173, vcc, 0, v171, vcc
	v_add_co_u32_e32 v174, vcc, 0x14f8000, v170
	s_nop 1
	v_addc_co_u32_e32 v175, vcc, 0, v171, vcc
	global_load_dwordx4 v[170:173], v[172:173], off offset:256
	s_nop 0
	global_load_dwordx4 v[174:177], v[174:175], off offset:256
	s_branch .LBB0_676

; __device__ __forceinline__ void lds_barrier() { asm volatile("s_waitcnt lgkmcnt(0)\n\ts_barrier" ::: "memory"); }
; __device__ __forceinline__ void gemm_big(const bf16_t* __restrict__ A, long lda, const bf16_t* __restrict__ Bt, int K, f32x16 (&acc)[2][4], unsigned char* lds) {
;     ...
;     const bf16_t* ap = A + (long)lrow * lda + lc * 8;
;     const bf16_t* bp = Bt + (long)lrow * K + lc * 8;
;     u32x4 ra[4], rb[8];
;     auto gload = [&](int kc) {
; #pragma unroll
;         for (int i = 0; i < 4; ++i) ra[i] = *(const u32x4*)(ap + (long)(32 * i) * lda + kc * 64);
; #pragma unroll
;         for (int i = 0; i < 8; ++i) rb[i] = *(const u32x4*)(bp + (long)(32 * i) * K + kc * 64);
;     };
;     auto lstore = [&]() {
; #pragma unroll
;         for (int i = 0; i < 4; ++i) *(u32x4*)(As + (lrow + 32 * i) * GLD + lc * 8) = ra[i];
; #pragma unroll
;         for (int i = 0; i < 8; ++i) *(u32x4*)(Bs + (lrow + 32 * i) * GLD + lc * 8) = rb[i];
;     };
;     const bf16_t* Ac = As + (wr * 64 + r) * GLD + h * 8;
;     const bf16_t* Bc = Bs + (wc * 128 + r) * GLD + h * 8;
;     gload(0);
;     __syncthreads();
;     lstore();
;     if (nk > 1) gload(1);
;     lds_barrier();
; __device__ __forceinline__ bool tile_at(int k, int NPM, int NPN, int& pm, int& pn) {
;     const int nb = gridDim.x >> 3, x = blockIdx.x & 7, jb = blockIdx.x >> 3;
;     const int t = jb + k * nb, perx = (NPM >> 3) * NPN;
;     if (t >= perx) return false;
;     const int pmg = t / (8 * NPN), rem = t - pmg * 8 * NPN;
;     pn = rem >> 3; pm = x * (NPM >> 3) + pmg * 8 + (rem & 7);
.LBB0_772:
	s_lshr_b32 s5, s4, 2
	s_and_b32 s20, s5, 0x7fffff8
	s_and_b32 s21, s4, 7
	v_readlane_b32 s23, v252, 2
	s_lshl_b32 s5, s20, 2
	s_or_b32 s12, s21, s23
	s_sub_i32 s5, s4, s5
	s_add_i32 s12, s12, s20
	s_ashr_i32 s13, s5, 3
	s_mul_i32 s4, s12, 0xb0000
	s_mul_hi_u32 s5, s12, 0xb0000
	s_add_u32 s4, s6, s4
	s_addc_u32 s5, s7, s5
	s_mul_i32 s14, s13, 0x160000
	v_mov_b32_e32 v74, v179
	s_mul_hi_i32 s15, s13, 0x160000
	s_add_u32 s14, s8, s14
	v_mov_b64_e32 v[2:3], s[4:5]
	v_ashrrev_i32_e32 v75, 3, v74
	v_lshlrev_b32_e32 v0, 4, v74
	s_addc_u32 s15, s9, s15
	v_mad_i64_i32 v[2:3], s[4:5], v75, s63, v[2:3]
	v_and_b32_e32 v0, 0x70, v0
	v_lshl_add_u64 v[50:51], v[2:3], 0, v[0:1]
	v_mov_b64_e32 v[2:3], s[14:15]
	v_mad_i64_i32 v[2:3], s[4:5], v75, s63, v[2:3]
	s_mov_b32 s4, 0x2c000
	s_nop 0
	v_add_co_u32_e32 v54, vcc, s4, v50
	s_mov_b32 s5, 0x58000
	s_nop 0
	v_addc_co_u32_e32 v55, vcc, 0, v51, vcc
	v_add_co_u32_e32 v56, vcc, s5, v50
	s_mov_b32 s14, 0x84000
	s_nop 0
	v_addc_co_u32_e32 v57, vcc, 0, v51, vcc
	v_add_co_u32_e32 v58, vcc, s14, v50
	v_lshl_add_u64 v[52:53], v[2:3], 0, v[0:1]
	s_nop 0
	v_addc_co_u32_e32 v59, vcc, 0, v51, vcc
	v_add_co_u32_e32 v60, vcc, s4, v52
	s_mov_b32 s4, 0xb0000
	s_nop 0
	v_addc_co_u32_e32 v61, vcc, 0, v53, vcc
	v_add_co_u32_e32 v62, vcc, s5, v52
	s_setprio 3
	global_load_dwordx4 v[2:5], v[54:55], off
	global_load_dwordx4 v[6:9], v[56:57], off
	v_addc_co_u32_e32 v63, vcc, 0, v53, vcc
	v_add_co_u32_e32 v64, vcc, s14, v52
	global_load_dwordx4 v[10:13], v[50:51], off
	global_load_dwordx4 v[14:17], v[52:53], off
	v_addc_co_u32_e32 v65, vcc, 0, v53, vcc
	v_add_co_u32_e32 v66, vcc, s4, v52
	s_mov_b32 s4, 0xdc000
	s_nop 0
	v_addc_co_u32_e32 v67, vcc, 0, v53, vcc
	v_add_co_u32_e32 v68, vcc, s4, v52
	s_mov_b32 s4, 0x108000
	s_nop 0
	v_addc_co_u32_e32 v69, vcc, 0, v53, vcc
	v_add_co_u32_e32 v70, vcc, s4, v52
	s_mov_b32 s4, 0x134000
	s_nop 0
	v_addc_co_u32_e32 v71, vcc, 0, v53, vcc
	v_add_co_u32_e32 v72, vcc, s4, v52
	global_load_dwordx4 v[18:21], v[58:59], off
	global_load_dwordx4 v[22:25], v[60:61], off
	global_load_dwordx4 v[26:29], v[62:63], off
	global_load_dwordx4 v[30:33], v[64:65], off
	global_load_dwordx4 v[34:37], v[66:67], off
	global_load_dwordx4 v[38:41], v[68:69], off
	v_addc_co_u32_e32 v73, vcc, 0, v53, vcc
	global_load_dwordx4 v[42:45], v[70:71], off
	global_load_dwordx4 v[46:49], v[72:73], off
	v_and_b32_e32 v76, 31, v74
	v_lshrrev_b32_e32 v77, 1, v74
	s_mov_b32 s4, 0xfffffc0
	v_and_or_b32 v78, v77, s4, v76
	v_lshlrev_b32_e32 v74, 1, v74
	s_movk_i32 s4, 0x80
	v_and_or_b32 v74, v74, s4, v76
	s_movk_i32 s5, 0x90
	v_and_b32_e32 v77, 16, v77
	v_mul_u32_u24_e32 v74, 0x90, v74
	v_add3_u32 v188, 0, v74, v77
	v_mul_lo_u32 v74, v75, s5
	v_add3_u32 v189, 0, v74, v0
	s_barrier
	v_mul_lo_u32 v78, v78, s5
	v_add3_u32 v187, 0, v78, v77
	s_mov_b32 s14, 0
	s_waitcnt vmcnt(9)
	ds_write_b128 v189, v[10:13]
	ds_write_b128 v189, v[2:5] offset:4608
	ds_write_b128 v189, v[6:9] offset:9216
	s_waitcnt vmcnt(7)
	ds_write_b128 v189, v[18:21] offset:13824
	ds_write_b128 v189, v[14:17] offset:18432
	s_waitcnt vmcnt(6)
	ds_write_b128 v189, v[22:25] offset:23040
	s_waitcnt vmcnt(5)
	ds_write_b128 v189, v[26:29] offset:27648
	s_waitcnt vmcnt(4)
	ds_write_b128 v189, v[30:33] offset:32256
	s_waitcnt vmcnt(3)
	ds_write_b128 v189, v[34:37] offset:36864
	s_waitcnt vmcnt(2)
	ds_write_b128 v189, v[38:41] offset:41472
	s_waitcnt vmcnt(1)
	ds_write_b128 v189, v[42:45] offset:46080
	s_waitcnt vmcnt(0)
	ds_write_b128 v189, v[46:49] offset:50688
	global_load_dwordx4 v[134:137], v[54:55], off offset:128
	global_load_dwordx4 v[138:141], v[56:57], off offset:128
	global_load_dwordx4 v[130:133], v[50:51], off offset:128
	global_load_dwordx4 v[146:149], v[52:53], off offset:128
	global_load_dwordx4 v[142:145], v[58:59], off offset:128
	global_load_dwordx4 v[150:153], v[60:61], off offset:128
	global_load_dwordx4 v[154:157], v[62:63], off offset:128
	global_load_dwordx4 v[158:161], v[64:65], off offset:128
	global_load_dwordx4 v[162:165], v[66:67], off offset:128
	global_load_dwordx4 v[166:169], v[68:69], off offset:128
	global_load_dwordx4 v[170:173], v[70:71], off offset:128
	global_load_dwordx4 v[174:177], v[72:73], off offset:128
	v_mad_i64_i32 v[2:3], s[4:5], v75, s63, 0
	v_mad_i64_i32 v[4:5], s[4:5], s13, v250, v[2:3]
	s_add_i32 s4, s23, s20
	s_add_i32 s4, s4, s21
	v_mad_u64_u32 v[2:3], s[4:5], s4, v251, v[2:3]
	s_waitcnt lgkmcnt(0)
	s_barrier
; __device__ __forceinline__ void gemm_big(const bf16_t* __restrict__ A, long lda, const bf16_t* __restrict__ Bt, int K, f32x16 (&acc)[2][4], unsigned char* lds) {
;     ...
;     const bf16_t* ap = A + (long)lrow * lda + lc * 8;
;     const bf16_t* bp = Bt + (long)lrow * K + lc * 8;
	v_or_b32_e32 v2, v2, v0
	v_or_b32_e32 v4, v4, v0
	v_lshl_add_u64 v[184:185], s[0:1], 0, v[2:3]
	v_mov_b32_e32 v2, 0
	v_lshl_add_u64 v[182:183], s[0:1], 0, v[4:5]
	s_mov_b64 s[4:5], 0
	v_mov_b32_e32 v3, v2
	v_mov_b32_e32 v4, v2
	v_mov_b32_e32 v5, v2
	v_mov_b32_e32 v6, v2
	v_mov_b32_e32 v7, v2
	v_mov_b32_e32 v8, v2
	v_mov_b32_e32 v9, v2
	v_mov_b32_e32 v10, v2
	v_mov_b32_e32 v11, v2
	v_mov_b32_e32 v12, v2
	v_mov_b32_e32 v13, v2
	v_mov_b32_e32 v14, v2
	v_mov_b32_e32 v15, v2
	v_mov_b32_e32 v16, v2
	v_mov_b32_e32 v17, v2
	v_mov_b32_e32 v66, v2
	v_mov_b32_e32 v67, v2
	v_mov_b32_e32 v68, v2
	v_mov_b32_e32 v69, v2
	v_mov_b32_e32 v70, v2
	v_mov_b32_e32 v71, v2
	v_mov_b32_e32 v72, v2
	v_mov_b32_e32 v73, v2
	v_mov_b32_e32 v74, v2
	v_mov_b32_e32 v75, v2
	v_mov_b32_e32 v76, v2
	v_mov_b32_e32 v77, v2
	v_mov_b32_e32 v78, v2
	v_mov_b32_e32 v79, v2
	v_mov_b32_e32 v80, v2
	v_mov_b32_e32 v81, v2
	v_mov_b32_e32 v18, v2
	v_mov_b32_e32 v19, v2
	v_mov_b32_e32 v20, v2
	v_mov_b32_e32 v21, v2
	v_mov_b32_e32 v22, v2
	v_mov_b32_e32 v23, v2
	v_mov_b32_e32 v24, v2
	v_mov_b32_e32 v25, v2
	v_mov_b32_e32 v26, v2
	v_mov_b32_e32 v27, v2
	v_mov_b32_e32 v28, v2
	v_mov_b32_e32 v29, v2
	v_mov_b32_e32 v30, v2
	v_mov_b32_e32 v31, v2
	v_mov_b32_e32 v32, v2
	v_mov_b32_e32 v33, v2
	v_mov_b32_e32 v82, v2
	v_mov_b32_e32 v83, v2
	v_mov_b32_e32 v84, v2
	v_mov_b32_e32 v85, v2
	v_mov_b32_e32 v86, v2
	v_mov_b32_e32 v87, v2
	v_mov_b32_e32 v88, v2
	v_mov_b32_e32 v89, v2
	v_mov_b32_e32 v90, v2
	v_mov_b32_e32 v91, v2
	v_mov_b32_e32 v92, v2
	v_mov_b32_e32 v93, v2
	v_mov_b32_e32 v94, v2
	v_mov_b32_e32 v95, v2
	v_mov_b32_e32 v96, v2
	v_mov_b32_e32 v97, v2
	v_mov_b32_e32 v34, v2
	v_mov_b32_e32 v35, v2
	v_mov_b32_e32 v36, v2
	v_mov_b32_e32 v37, v2
	v_mov_b32_e32 v38, v2
	v_mov_b32_e32 v39, v2
	v_mov_b32_e32 v40, v2
	v_mov_b32_e32 v41, v2
	v_mov_b32_e32 v42, v2
	v_mov_b32_e32 v43, v2
	v_mov_b32_e32 v44, v2
	v_mov_b32_e32 v45, v2
	v_mov_b32_e32 v46, v2
	v_mov_b32_e32 v47, v2
	v_mov_b32_e32 v48, v2
	v_mov_b32_e32 v49, v2
	v_mov_b32_e32 v98, v2
	v_mov_b32_e32 v99, v2
	v_mov_b32_e32 v100, v2
	v_mov_b32_e32 v101, v2
	v_mov_b32_e32 v102, v2
	v_mov_b32_e32 v103, v2
	v_mov_b32_e32 v104, v2
	v_mov_b32_e32 v105, v2
	v_mov_b32_e32 v106, v2
	v_mov_b32_e32 v107, v2
	v_mov_b32_e32 v108, v2
	v_mov_b32_e32 v109, v2
	v_mov_b32_e32 v110, v2
	v_mov_b32_e32 v111, v2
	v_mov_b32_e32 v112, v2
	v_mov_b32_e32 v113, v2
	v_mov_b32_e32 v50, v2
	v_mov_b32_e32 v51, v2
	v_mov_b32_e32 v52, v2
	v_mov_b32_e32 v53, v2
	v_mov_b32_e32 v54, v2
	v_mov_b32_e32 v55, v2
	v_mov_b32_e32 v56, v2
	v_mov_b32_e32 v57, v2
	v_mov_b32_e32 v58, v2
	v_mov_b32_e32 v59, v2
	v_mov_b32_e32 v60, v2
	v_mov_b32_e32 v61, v2
	v_mov_b32_e32 v62, v2
	v_mov_b32_e32 v63, v2
	v_mov_b32_e32 v64, v2
	v_mov_b32_e32 v65, v2
	v_mov_b32_e32 v114, v2
	v_mov_b32_e32 v115, v2
	v_mov_b32_e32 v116, v2
	v_mov_b32_e32 v117, v2
	v_mov_b32_e32 v118, v2
	v_mov_b32_e32 v119, v2
	v_mov_b32_e32 v120, v2
	v_mov_b32_e32 v121, v2
	v_mov_b32_e32 v122, v2
	v_mov_b32_e32 v123, v2
	v_mov_b32_e32 v124, v2
	v_mov_b32_e32 v125, v2
	v_mov_b32_e32 v126, v2
	v_mov_b32_e32 v127, v2
	v_mov_b32_e32 v128, v2
	v_mov_b32_e32 v129, v2
	s_setprio 0
	s_branch .LBB0_775

; __device__ __forceinline__ void lds_barrier() { asm volatile("s_waitcnt lgkmcnt(0)\n\ts_barrier" ::: "memory"); }
; __device__ __forceinline__ f32x16 mfma32(bf16x8 a, bf16x8 b, f32x16 c) { return __builtin_amdgcn_mfma_f32_32x32x16_bf16(a, b, c, 0, 0, 0); }
; __device__ __forceinline__ void gemm_big(const bf16_t* __restrict__ A, long lda, const bf16_t* __restrict__ Bt, int K, f32x16 (&acc)[2][4], unsigned char* lds) {
;     ...
;     for (int kc = 0; kc < nk; ++kc) {
;         bf16x8 af[2][2], bfr[2][4];
;         af[0][0] = *(const bf16x8*)(Ac); af[0][1] = *(const bf16x8*)(Ac + 32 * GLD);
; #pragma unroll
;         for (int ni = 0; ni < 4; ++ni) bfr[0][ni] = *(const bf16x8*)(Bc + ni * 32 * GLD);
;         __builtin_amdgcn_s_setprio(3);
; #pragma unroll
;         for (int ks = 0; ks < 4; ++ks) {
;             const int cb = ks & 1, nb = cb ^ 1;
;             if (ks < 3) {
;                 af[nb][0] = *(const bf16x8*)(Ac + (ks + 1) * 16); af[nb][1] = *(const bf16x8*)(Ac + 32 * GLD + (ks + 1) * 16);
; #pragma unroll
;                 for (int ni = 0; ni < 4; ++ni) bfr[nb][ni] = *(const bf16x8*)(Bc + ni * 32 * GLD + (ks + 1) * 16);
;             }
;             __builtin_amdgcn_sched_barrier(0);
; #pragma unroll
;             for (int ni = 0; ni < 4; ++ni) { acc[0][ni] = mfma32(af[cb][0], bfr[cb][ni], acc[0][ni]); acc[1][ni] = mfma32(af[cb][1], bfr[cb][ni], acc[1][ni]); }
;             __builtin_amdgcn_sched_barrier(0);
;         }
;         __builtin_amdgcn_s_setprio(0);
;         lds_barrier();
;         if (kc + 1 < nk) {
;             lstore();
;             if (kc + 2 < nk) gload(kc + 2);
;             lds_barrier();
;         }
.Lmy_gorig_1:
	ds_read_b128 v[190:193], v187
	ds_read_b128 v[194:197], v187 offset:4608
	ds_read_b128 v[198:201], v188 offset:18432
	ds_read_b128 v[202:205], v188 offset:23040
	ds_read_b128 v[206:209], v188 offset:27648
	ds_read_b128 v[210:213], v188 offset:32256
	ds_read_b128 v[214:217], v187 offset:32
	ds_read_b128 v[218:221], v187 offset:4640
	ds_read_b128 v[234:237], v188 offset:18464
	ds_read_b128 v[238:241], v188 offset:23072
	ds_read_b128 v[242:245], v188 offset:27680
	ds_read_b128 v[246:249], v188 offset:32288
	s_waitcnt lgkmcnt(9)
	v_mfma_f32_32x32x16_bf16 v[114:129], v[190:193], v[198:201], v[114:129]
	v_mfma_f32_32x32x16_bf16 v[50:65], v[194:197], v[198:201], v[50:65]
	s_waitcnt lgkmcnt(8)
	v_mfma_f32_32x32x16_bf16 v[98:113], v[190:193], v[202:205], v[98:113]
	v_mfma_f32_32x32x16_bf16 v[34:49], v[194:197], v[202:205], v[34:49]
	s_waitcnt lgkmcnt(7)
	v_mfma_f32_32x32x16_bf16 v[82:97], v[190:193], v[206:209], v[82:97]
	v_mfma_f32_32x32x16_bf16 v[18:33], v[194:197], v[206:209], v[18:33]
	s_waitcnt lgkmcnt(6)
	v_mfma_f32_32x32x16_bf16 v[66:81], v[190:193], v[210:213], v[66:81]
	v_mfma_f32_32x32x16_bf16 v[2:17], v[194:197], v[210:213], v[2:17]
	ds_read_b128 v[190:193], v187 offset:64
	ds_read_b128 v[194:197], v187 offset:4672
	ds_read_b128 v[198:201], v188 offset:18496
	ds_read_b128 v[202:205], v188 offset:23104
	ds_read_b128 v[206:209], v188 offset:27712
	ds_read_b128 v[210:213], v188 offset:32320
	s_waitcnt lgkmcnt(9)
	v_mfma_f32_32x32x16_bf16 v[114:129], v[214:217], v[234:237], v[114:129]
	v_mfma_f32_32x32x16_bf16 v[50:65], v[218:221], v[234:237], v[50:65]
	s_waitcnt lgkmcnt(8)
	v_mfma_f32_32x32x16_bf16 v[98:113], v[214:217], v[238:241], v[98:113]
	v_mfma_f32_32x32x16_bf16 v[34:49], v[218:221], v[238:241], v[34:49]
	s_waitcnt lgkmcnt(7)
	v_mfma_f32_32x32x16_bf16 v[82:97], v[214:217], v[242:245], v[82:97]
	v_mfma_f32_32x32x16_bf16 v[18:33], v[218:221], v[242:245], v[18:33]
	s_waitcnt lgkmcnt(6)
	v_mfma_f32_32x32x16_bf16 v[66:81], v[214:217], v[246:249], v[66:81]
	v_mfma_f32_32x32x16_bf16 v[2:17], v[218:221], v[246:249], v[2:17]
	ds_read_b128 v[214:217], v187 offset:96
	ds_read_b128 v[218:221], v187 offset:4704
	ds_read_b128 v[234:237], v188 offset:18528
	ds_read_b128 v[238:241], v188 offset:23136
	ds_read_b128 v[242:245], v188 offset:27744
	ds_read_b128 v[246:249], v188 offset:32352
	s_waitcnt lgkmcnt(9)
	v_mfma_f32_32x32x16_bf16 v[114:129], v[190:193], v[198:201], v[114:129]
	v_mfma_f32_32x32x16_bf16 v[50:65], v[194:197], v[198:201], v[50:65]
	s_waitcnt lgkmcnt(8)
	v_mfma_f32_32x32x16_bf16 v[98:113], v[190:193], v[202:205], v[98:113]
	v_mfma_f32_32x32x16_bf16 v[34:49], v[194:197], v[202:205], v[34:49]
	s_waitcnt lgkmcnt(7)
	v_mfma_f32_32x32x16_bf16 v[82:97], v[190:193], v[206:209], v[82:97]
	v_mfma_f32_32x32x16_bf16 v[18:33], v[194:197], v[206:209], v[18:33]
	s_waitcnt lgkmcnt(6)
	v_mfma_f32_32x32x16_bf16 v[66:81], v[190:193], v[210:213], v[66:81]
	v_mfma_f32_32x32x16_bf16 v[2:17], v[194:197], v[210:213], v[2:17]
	s_waitcnt lgkmcnt(3)
	v_mfma_f32_32x32x16_bf16 v[114:129], v[214:217], v[234:237], v[114:129]
	v_mfma_f32_32x32x16_bf16 v[50:65], v[218:221], v[234:237], v[50:65]
	s_waitcnt lgkmcnt(2)
	v_mfma_f32_32x32x16_bf16 v[98:113], v[214:217], v[238:241], v[98:113]
	v_mfma_f32_32x32x16_bf16 v[34:49], v[218:221], v[238:241], v[34:49]
	s_waitcnt lgkmcnt(1)
	v_mfma_f32_32x32x16_bf16 v[82:97], v[214:217], v[242:245], v[82:97]
	v_mfma_f32_32x32x16_bf16 v[18:33], v[218:221], v[242:245], v[18:33]
	s_waitcnt lgkmcnt(0)
	v_mfma_f32_32x32x16_bf16 v[66:81], v[214:217], v[246:249], v[66:81]
	v_mfma_f32_32x32x16_bf16 v[2:17], v[218:221], v[246:249], v[2:17]
	s_setprio 0
	s_waitcnt lgkmcnt(0)
	s_barrier
	s_cmp_gt_u32 s14, 42
	s_cbranch_scc1 .LBB0_774
	s_cmpk_eq_i32 s4, 0x1500
	s_waitcnt vmcnt(9)
	ds_write_b128 v189, v[130:133]
	ds_write_b128 v189, v[134:137] offset:4608
	ds_write_b128 v189, v[138:141] offset:9216
	s_waitcnt vmcnt(7)
	ds_write_b128 v189, v[142:145] offset:13824
	ds_write_b128 v189, v[146:149] offset:18432
	s_waitcnt vmcnt(6)
	ds_write_b128 v189, v[150:153] offset:23040
	s_waitcnt vmcnt(5)
	ds_write_b128 v189, v[154:157] offset:27648
	s_waitcnt vmcnt(4)
	ds_write_b128 v189, v[158:161] offset:32256
	s_waitcnt vmcnt(3)
	ds_write_b128 v189, v[162:165] offset:36864
	s_waitcnt vmcnt(2)
	ds_write_b128 v189, v[166:169] offset:41472
	s_waitcnt vmcnt(1)
	ds_write_b128 v189, v[170:173] offset:46080
	s_waitcnt vmcnt(0)
	ds_write_b128 v189, v[174:177] offset:50688
	s_cbranch_scc1 .LBB0_773
	v_lshl_add_u64 v[138:139], v[184:185], 0, s[4:5]
	v_add_co_u32_e32 v130, vcc, 0x78a8000, v138
	v_lshl_add_u64 v[170:171], v[182:183], 0, s[4:5]
	s_nop 0
	v_addc_co_u32_e32 v131, vcc, 0, v139, vcc
	v_add_co_u32_e32 v134, vcc, 0x78d4000, v138
	s_nop 1
	v_addc_co_u32_e32 v135, vcc, 0, v139, vcc
	v_add_co_u32_e32 v140, vcc, 0x7900000, v138
	global_load_dwordx4 v[130:133], v[130:131], off offset:256
	s_nop 0
	global_load_dwordx4 v[134:137], v[134:135], off offset:256
	v_addc_co_u32_e32 v141, vcc, 0, v139, vcc
	v_add_co_u32_e32 v142, vcc, 0x792c000, v138
	s_nop 1
	v_addc_co_u32_e32 v143, vcc, 0, v139, vcc
	v_add_co_u32_e32 v146, vcc, 0xf08000, v170
	global_load_dwordx4 v[138:141], v[140:141], off offset:256
	s_nop 0
	global_load_dwordx4 v[142:145], v[142:143], off offset:256
	v_addc_co_u32_e32 v147, vcc, 0, v171, vcc
	v_add_co_u32_e32 v150, vcc, 0xf34000, v170
	s_nop 1
	v_addc_co_u32_e32 v151, vcc, 0, v171, vcc
	v_add_co_u32_e32 v154, vcc, 0xf60000, v170
	global_load_dwordx4 v[146:149], v[146:147], off offset:256
	s_nop 0
	global_load_dwordx4 v[150:153], v[150:151], off offset:256
	v_addc_co_u32_e32 v155, vcc, 0, v171, vcc
	v_add_co_u32_e32 v158, vcc, 0xf8c000, v170
	s_nop 1
	v_addc_co_u32_e32 v159, vcc, 0, v171, vcc
	v_add_co_u32_e32 v162, vcc, 0xfb8000, v170
	global_load_dwordx4 v[154:157], v[154:155], off offset:256
	s_nop 0
	global_load_dwordx4 v[158:161], v[158:159], off offset:256
	v_addc_co_u32_e32 v163, vcc, 0, v171, vcc
	v_add_co_u32_e32 v166, vcc, 0xfe4000, v170
	s_nop 1
	v_addc_co_u32_e32 v167, vcc, 0, v171, vcc
	v_add_co_u32_e32 v172, vcc, 0x1010000, v170
	global_load_dwordx4 v[162:165], v[162:163], off offset:256
	s_nop 0
	global_load_dwordx4 v[166:169], v[166:167], off offset:256
	v_addc_co_u32_e32 v173, vcc, 0, v171, vcc
	v_add_co_u32_e32 v174, vcc, 0x103c000, v170
	s_nop 1
	v_addc_co_u32_e32 v175, vcc, 0, v171, vcc
	global_load_dwordx4 v[170:173], v[172:173], off offset:256
	s_nop 0
	global_load_dwordx4 v[174:177], v[174:175], off offset:256
	s_branch .LBB0_773

; __device__ __forceinline__ void lds_barrier() { asm volatile("s_waitcnt lgkmcnt(0)\n\ts_barrier" ::: "memory"); }
; __device__ __forceinline__ void gemm_big(const bf16_t* __restrict__ A, long lda, const bf16_t* __restrict__ Bt, int K, f32x16 (&acc)[2][4], unsigned char* lds) {
;     ...
;     const bf16_t* ap = A + (long)lrow * lda + lc * 8;
;     const bf16_t* bp = Bt + (long)lrow * K + lc * 8;
;     u32x4 ra[4], rb[8];
;     auto gload = [&](int kc) {
; #pragma unroll
;         for (int i = 0; i < 4; ++i) ra[i] = *(const u32x4*)(ap + (long)(32 * i) * lda + kc * 64);
; #pragma unroll
;         for (int i = 0; i < 8; ++i) rb[i] = *(const u32x4*)(bp + (long)(32 * i) * K + kc * 64);
;     };
;     auto lstore = [&]() {
; #pragma unroll
;         for (int i = 0; i < 4; ++i) *(u32x4*)(As + (lrow + 32 * i) * GLD + lc * 8) = ra[i];
; #pragma unroll
;         for (int i = 0; i < 8; ++i) *(u32x4*)(Bs + (lrow + 32 * i) * GLD + lc * 8) = rb[i];
;     };
;     const bf16_t* Ac = As + (wr * 64 + r) * GLD + h * 8;
;     const bf16_t* Bc = Bs + (wc * 128 + r) * GLD + h * 8;
;     gload(0);
;     __syncthreads();
;     lstore();
;     if (nk > 1) gload(1);
;     lds_barrier();
; __device__ __forceinline__ bool tile_at(int k, int NPM, int NPN, int& pm, int& pn) {
;     const int nb = gridDim.x >> 3, x = blockIdx.x & 7, jb = blockIdx.x >> 3;
;     const int t = jb + k * nb, perx = (NPM >> 3) * NPN;
;     if (t >= perx) return false;
;     const int pmg = t / (8 * NPN), rem = t - pmg * 8 * NPN;
;     pn = rem >> 3; pm = x * (NPM >> 3) + pmg * 8 + (rem & 7);
.LBB0_785:
	s_mul_hi_u32 s5, s4, 0xba2e8ba3
	s_lshr_b32 s5, s5, 7
	s_and_b32 s15, s4, 7
	v_readlane_b32 s26, v252, 2
	s_mul_i32 s6, s5, 0xffffff50
	s_or_b32 s14, s15, s26
	s_lshl_b32 s23, s5, 3
	s_add_i32 s6, s6, s4
	s_add_i32 s14, s14, s23
	v_mov_b32_e32 v78, v179
	s_ashr_i32 s4, s6, 3
	s_lshl_b32 s5, s14, 18
	s_add_u32 s20, s10, s5
	s_waitcnt vmcnt(27)
	v_ashrrev_i32_e32 v50, 3, v78
	s_waitcnt vmcnt(26)
	v_ashrrev_i32_e32 v51, 31, v50
	s_addc_u32 s21, s11, 0
	s_waitcnt vmcnt(24)
	v_lshlrev_b64 v[52:53], 11, v[50:51]
	v_lshlrev_b32_e32 v0, 4, v78
	v_lshl_add_u64 v[2:3], s[20:21], 0, v[52:53]
	v_and_b32_e32 v0, 0x70, v0
	v_lshl_add_u64 v[54:55], v[2:3], 0, v[0:1]
	s_ashr_i32 s5, s4, 31
	v_add_co_u32_e32 v58, vcc, s67, v54
	s_lshl_b64 s[6:7], s[4:5], 19
	s_nop 0
	v_addc_co_u32_e32 v59, vcc, 0, v55, vcc
	s_mov_b32 s5, 0x20000
	s_add_u32 s24, s8, s6
	v_add_co_u32_e32 v60, vcc, s5, v54
	s_addc_u32 s25, s9, s7
	s_nop 0
	v_addc_co_u32_e32 v61, vcc, 0, v55, vcc
	s_mov_b32 s20, 0x30000
	v_lshl_add_u64 v[2:3], s[24:25], 0, v[52:53]
	s_waitcnt vmcnt(23)
	v_add_co_u32_e32 v62, vcc, s20, v54
	v_lshl_add_u64 v[56:57], v[2:3], 0, v[0:1]
	s_waitcnt vmcnt(22)
	v_addc_co_u32_e32 v63, vcc, 0, v55, vcc
	s_waitcnt vmcnt(21)
	v_add_co_u32_e32 v64, vcc, s67, v56
	s_setprio 3
	global_load_dwordx4 v[2:5], v[58:59], off
	global_load_dwordx4 v[6:9], v[60:61], off
	s_waitcnt vmcnt(22)
	v_addc_co_u32_e32 v65, vcc, 0, v57, vcc
	s_waitcnt vmcnt(21)
	v_add_co_u32_e32 v66, vcc, s5, v56
	s_mov_b32 s5, 0x40000
	s_waitcnt vmcnt(20)
	v_addc_co_u32_e32 v67, vcc, 0, v57, vcc
	s_waitcnt vmcnt(19)
	v_add_co_u32_e32 v68, vcc, s20, v56
	global_load_dwordx4 v[10:13], v[54:55], off
	global_load_dwordx4 v[14:17], v[56:57], off
	s_waitcnt vmcnt(20)
	v_addc_co_u32_e32 v69, vcc, 0, v57, vcc
	v_add_co_u32_e32 v70, vcc, s5, v56
	s_mov_b32 s5, 0x50000
	s_nop 0
	v_addc_co_u32_e32 v71, vcc, 0, v57, vcc
	v_add_co_u32_e32 v72, vcc, s5, v56
	s_mov_b32 s5, 0x60000
	s_nop 0
	v_addc_co_u32_e32 v73, vcc, 0, v57, vcc
	v_add_co_u32_e32 v74, vcc, s5, v56
	s_mov_b32 s5, 0x70000
	s_nop 0
	v_addc_co_u32_e32 v75, vcc, 0, v57, vcc
	v_add_co_u32_e32 v76, vcc, s5, v56
	global_load_dwordx4 v[18:21], v[62:63], off
	global_load_dwordx4 v[22:25], v[64:65], off
	v_addc_co_u32_e32 v77, vcc, 0, v57, vcc
	global_load_dwordx4 v[26:29], v[66:67], off
	global_load_dwordx4 v[30:33], v[68:69], off
	global_load_dwordx4 v[34:37], v[70:71], off
	global_load_dwordx4 v[38:41], v[72:73], off
	global_load_dwordx4 v[42:45], v[74:75], off
	global_load_dwordx4 v[46:49], v[76:77], off
	s_movk_i32 s20, 0x90
	v_mul_lo_u32 v50, v50, s20
	v_add3_u32 v187, 0, v50, v0
	s_barrier
	v_and_b32_e32 v51, 31, v78
	v_lshrrev_b32_e32 v79, 1, v78
	s_mov_b32 s5, 0xfffffc0
	v_and_or_b32 v80, v79, s5, v51
	s_movk_i32 s5, 0x80
	v_mul_lo_u32 v50, v80, s20
	s_waitcnt vmcnt(9)
	ds_write_b128 v187, v[10:13]
	ds_write_b128 v187, v[2:5] offset:4608
	ds_write_b128 v187, v[6:9] offset:9216
	s_waitcnt vmcnt(7)
	ds_write_b128 v187, v[18:21] offset:13824
	ds_write_b128 v187, v[14:17] offset:18432
	s_waitcnt vmcnt(6)
	ds_write_b128 v187, v[22:25] offset:23040
	s_waitcnt vmcnt(5)
	ds_write_b128 v187, v[26:29] offset:27648
	s_waitcnt vmcnt(4)
	ds_write_b128 v187, v[30:33] offset:32256
	s_waitcnt vmcnt(3)
	ds_write_b128 v187, v[34:37] offset:36864
	s_waitcnt vmcnt(2)
	ds_write_b128 v187, v[38:41] offset:41472
	s_waitcnt vmcnt(1)
	ds_write_b128 v187, v[42:45] offset:46080
	s_waitcnt vmcnt(0)
	ds_write_b128 v187, v[46:49] offset:50688
	global_load_dwordx4 v[134:137], v[58:59], off offset:128
	global_load_dwordx4 v[138:141], v[60:61], off offset:128
	global_load_dwordx4 v[130:133], v[54:55], off offset:128
	global_load_dwordx4 v[146:149], v[56:57], off offset:128
	global_load_dwordx4 v[142:145], v[62:63], off offset:128
	global_load_dwordx4 v[150:153], v[64:65], off offset:128
	global_load_dwordx4 v[154:157], v[66:67], off offset:128
	global_load_dwordx4 v[158:161], v[68:69], off offset:128
	global_load_dwordx4 v[162:165], v[70:71], off offset:128
	global_load_dwordx4 v[166:169], v[72:73], off offset:128
	global_load_dwordx4 v[170:173], v[74:75], off offset:128
	global_load_dwordx4 v[174:177], v[76:77], off offset:128
	v_lshlrev_b32_e32 v3, 1, v78
	v_and_or_b32 v3, v3, s5, v51
	s_add_i32 s5, s26, s23
	v_and_b32_e32 v2, 16, v79
	v_mul_u32_u24_e32 v3, 0x90, v3
	s_add_i32 s5, s5, s15
	v_add3_u32 v188, 0, v50, v2
	v_add3_u32 v189, 0, v3, v2
	v_lshl_add_u64 v[2:3], s[6:7], 0, v[52:53]
	s_lshl_b32 s5, s5, 18
	s_waitcnt lgkmcnt(0)
	s_barrier
; __device__ __forceinline__ void gemm_big(const bf16_t* __restrict__ A, long lda, const bf16_t* __restrict__ Bt, int K, f32x16 (&acc)[2][4], unsigned char* lds) {
;     ...
;     const bf16_t* ap = A + (long)lrow * lda + lc * 8;
;     const bf16_t* bp = Bt + (long)lrow * K + lc * 8;
	v_or_b32_e32 v2, v2, v0
	s_add_u32 s6, s0, s5
	v_lshl_add_u64 v[182:183], s[0:1], 0, v[2:3]
	v_or_b32_e32 v52, v52, v0
	s_addc_u32 s7, s1, 0
	v_mov_b32_e32 v2, 0
	v_lshl_add_u64 v[184:185], s[6:7], 0, v[52:53]
	s_mov_b64 s[6:7], 0
	s_mov_b32 s5, 0
	v_mov_b32_e32 v3, v2
	v_mov_b32_e32 v4, v2
	v_mov_b32_e32 v5, v2
	v_mov_b32_e32 v6, v2
	v_mov_b32_e32 v7, v2
	v_mov_b32_e32 v8, v2
	v_mov_b32_e32 v9, v2
	v_mov_b32_e32 v10, v2
	v_mov_b32_e32 v11, v2
	v_mov_b32_e32 v12, v2
	v_mov_b32_e32 v13, v2
	v_mov_b32_e32 v14, v2
	v_mov_b32_e32 v15, v2
	v_mov_b32_e32 v16, v2
	v_mov_b32_e32 v17, v2
	v_mov_b32_e32 v34, v2
	v_mov_b32_e32 v35, v2
	v_mov_b32_e32 v36, v2
	v_mov_b32_e32 v37, v2
	v_mov_b32_e32 v38, v2
	v_mov_b32_e32 v39, v2
	v_mov_b32_e32 v40, v2
	v_mov_b32_e32 v41, v2
	v_mov_b32_e32 v42, v2
	v_mov_b32_e32 v43, v2
	v_mov_b32_e32 v44, v2
	v_mov_b32_e32 v45, v2
	v_mov_b32_e32 v46, v2
	v_mov_b32_e32 v47, v2
	v_mov_b32_e32 v48, v2
	v_mov_b32_e32 v49, v2
	v_mov_b32_e32 v18, v2
	v_mov_b32_e32 v19, v2
	v_mov_b32_e32 v20, v2
	v_mov_b32_e32 v21, v2
	v_mov_b32_e32 v22, v2
	v_mov_b32_e32 v23, v2
	v_mov_b32_e32 v24, v2
	v_mov_b32_e32 v25, v2
	v_mov_b32_e32 v26, v2
	v_mov_b32_e32 v27, v2
	v_mov_b32_e32 v28, v2
	v_mov_b32_e32 v29, v2
	v_mov_b32_e32 v30, v2
	v_mov_b32_e32 v31, v2
	v_mov_b32_e32 v32, v2
	v_mov_b32_e32 v33, v2
	v_mov_b32_e32 v50, v2
	v_mov_b32_e32 v51, v2
	v_mov_b32_e32 v52, v2
	v_mov_b32_e32 v53, v2
	v_mov_b32_e32 v54, v2
	v_mov_b32_e32 v55, v2
	v_mov_b32_e32 v56, v2
	v_mov_b32_e32 v57, v2
	v_mov_b32_e32 v58, v2
	v_mov_b32_e32 v59, v2
	v_mov_b32_e32 v60, v2
	v_mov_b32_e32 v61, v2
	v_mov_b32_e32 v62, v2
	v_mov_b32_e32 v63, v2
	v_mov_b32_e32 v64, v2
	v_mov_b32_e32 v65, v2
	v_mov_b32_e32 v66, v2
	v_mov_b32_e32 v67, v2
	v_mov_b32_e32 v68, v2
	v_mov_b32_e32 v69, v2
	v_mov_b32_e32 v70, v2
	v_mov_b32_e32 v71, v2
	v_mov_b32_e32 v72, v2
	v_mov_b32_e32 v73, v2
	v_mov_b32_e32 v74, v2
	v_mov_b32_e32 v75, v2
	v_mov_b32_e32 v76, v2
	v_mov_b32_e32 v77, v2
	v_mov_b32_e32 v78, v2
	v_mov_b32_e32 v79, v2
	v_mov_b32_e32 v80, v2
	v_mov_b32_e32 v81, v2
	v_mov_b32_e32 v98, v2
	v_mov_b32_e32 v99, v2
	v_mov_b32_e32 v100, v2
	v_mov_b32_e32 v101, v2
	v_mov_b32_e32 v102, v2
	v_mov_b32_e32 v103, v2
	v_mov_b32_e32 v104, v2
	v_mov_b32_e32 v105, v2
	v_mov_b32_e32 v106, v2
	v_mov_b32_e32 v107, v2
	v_mov_b32_e32 v108, v2
	v_mov_b32_e32 v109, v2
	v_mov_b32_e32 v110, v2
	v_mov_b32_e32 v111, v2
	v_mov_b32_e32 v112, v2
	v_mov_b32_e32 v113, v2
	v_mov_b32_e32 v82, v2
	v_mov_b32_e32 v83, v2
	v_mov_b32_e32 v84, v2
	v_mov_b32_e32 v85, v2
	v_mov_b32_e32 v86, v2
	v_mov_b32_e32 v87, v2
	v_mov_b32_e32 v88, v2
	v_mov_b32_e32 v89, v2
	v_mov_b32_e32 v90, v2
	v_mov_b32_e32 v91, v2
	v_mov_b32_e32 v92, v2
	v_mov_b32_e32 v93, v2
	v_mov_b32_e32 v94, v2
	v_mov_b32_e32 v95, v2
	v_mov_b32_e32 v96, v2
	v_mov_b32_e32 v97, v2
	v_mov_b32_e32 v114, v2
	v_mov_b32_e32 v115, v2
	v_mov_b32_e32 v116, v2
	v_mov_b32_e32 v117, v2
	v_mov_b32_e32 v118, v2
	v_mov_b32_e32 v119, v2
	v_mov_b32_e32 v120, v2
	v_mov_b32_e32 v121, v2
	v_mov_b32_e32 v122, v2
	v_mov_b32_e32 v123, v2
	v_mov_b32_e32 v124, v2
	v_mov_b32_e32 v125, v2
	v_mov_b32_e32 v126, v2
	v_mov_b32_e32 v127, v2
	v_mov_b32_e32 v128, v2
	v_mov_b32_e32 v129, v2
	s_setprio 0
	s_branch .LBB0_788

; __device__ __forceinline__ void lds_barrier() { asm volatile("s_waitcnt lgkmcnt(0)\n\ts_barrier" ::: "memory"); }
; __device__ __forceinline__ f32x16 mfma32(bf16x8 a, bf16x8 b, f32x16 c) { return __builtin_amdgcn_mfma_f32_32x32x16_bf16(a, b, c, 0, 0, 0); }
; __device__ __forceinline__ void gemm_big(const bf16_t* __restrict__ A, long lda, const bf16_t* __restrict__ Bt, int K, f32x16 (&acc)[2][4], unsigned char* lds) {
;     ...
;     for (int kc = 0; kc < nk; ++kc) {
;         bf16x8 af[2][2], bfr[2][4];
;         af[0][0] = *(const bf16x8*)(Ac); af[0][1] = *(const bf16x8*)(Ac + 32 * GLD);
; #pragma unroll
;         for (int ni = 0; ni < 4; ++ni) bfr[0][ni] = *(const bf16x8*)(Bc + ni * 32 * GLD);
;         __builtin_amdgcn_s_setprio(3);
; #pragma unroll
;         for (int ks = 0; ks < 4; ++ks) {
;             const int cb = ks & 1, nb = cb ^ 1;
;             if (ks < 3) {
;                 af[nb][0] = *(const bf16x8*)(Ac + (ks + 1) * 16); af[nb][1] = *(const bf16x8*)(Ac + 32 * GLD + (ks + 1) * 16);
; #pragma unroll
;                 for (int ni = 0; ni < 4; ++ni) bfr[nb][ni] = *(const bf16x8*)(Bc + ni * 32 * GLD + (ks + 1) * 16);
;             }
;             __builtin_amdgcn_sched_barrier(0);
; #pragma unroll
;             for (int ni = 0; ni < 4; ++ni) { acc[0][ni] = mfma32(af[cb][0], bfr[cb][ni], acc[0][ni]); acc[1][ni] = mfma32(af[cb][1], bfr[cb][ni], acc[1][ni]); }
;             __builtin_amdgcn_sched_barrier(0);
;         }
;         __builtin_amdgcn_s_setprio(0);
;         lds_barrier();
;         if (kc + 1 < nk) {
;             lstore();
;             if (kc + 2 < nk) gload(kc + 2);
;             lds_barrier();
;         }
.Lmy_gorig_0:
	ds_read_b128 v[190:193], v188
	ds_read_b128 v[194:197], v188 offset:4608
	ds_read_b128 v[198:201], v189 offset:18432
	ds_read_b128 v[202:205], v189 offset:23040
	ds_read_b128 v[206:209], v189 offset:27648
	ds_read_b128 v[210:213], v189 offset:32256
	ds_read_b128 v[214:217], v188 offset:32
	ds_read_b128 v[234:237], v188 offset:4640
	ds_read_b128 v[238:241], v189 offset:18464
	ds_read_b128 v[242:245], v189 offset:23072
	ds_read_b128 v[246:249], v189 offset:27680
	ds_read_b128 v[218:221], v189 offset:32288
	s_waitcnt lgkmcnt(9)
	v_mfma_f32_32x32x16_bf16 v[114:129], v[190:193], v[198:201], v[114:129]
	v_mfma_f32_32x32x16_bf16 v[82:97], v[194:197], v[198:201], v[82:97]
	s_waitcnt lgkmcnt(8)
	v_mfma_f32_32x32x16_bf16 v[98:113], v[190:193], v[202:205], v[98:113]
	v_mfma_f32_32x32x16_bf16 v[66:81], v[194:197], v[202:205], v[66:81]
	s_waitcnt lgkmcnt(7)
	v_mfma_f32_32x32x16_bf16 v[50:65], v[190:193], v[206:209], v[50:65]
	v_mfma_f32_32x32x16_bf16 v[18:33], v[194:197], v[206:209], v[18:33]
	s_waitcnt lgkmcnt(6)
	v_mfma_f32_32x32x16_bf16 v[34:49], v[190:193], v[210:213], v[34:49]
	v_mfma_f32_32x32x16_bf16 v[2:17], v[194:197], v[210:213], v[2:17]
	ds_read_b128 v[190:193], v188 offset:64
	ds_read_b128 v[194:197], v188 offset:4672
	ds_read_b128 v[198:201], v189 offset:18496
	ds_read_b128 v[202:205], v189 offset:23104
	ds_read_b128 v[206:209], v189 offset:27712
	ds_read_b128 v[210:213], v189 offset:32320
	s_waitcnt lgkmcnt(9)
	v_mfma_f32_32x32x16_bf16 v[114:129], v[214:217], v[238:241], v[114:129]
	v_mfma_f32_32x32x16_bf16 v[82:97], v[234:237], v[238:241], v[82:97]
	s_waitcnt lgkmcnt(8)
	v_mfma_f32_32x32x16_bf16 v[98:113], v[214:217], v[242:245], v[98:113]
	v_mfma_f32_32x32x16_bf16 v[66:81], v[234:237], v[242:245], v[66:81]
	s_waitcnt lgkmcnt(7)
	v_mfma_f32_32x32x16_bf16 v[50:65], v[214:217], v[246:249], v[50:65]
	v_mfma_f32_32x32x16_bf16 v[18:33], v[234:237], v[246:249], v[18:33]
	s_waitcnt lgkmcnt(6)
	v_mfma_f32_32x32x16_bf16 v[34:49], v[214:217], v[218:221], v[34:49]
	v_mfma_f32_32x32x16_bf16 v[2:17], v[234:237], v[218:221], v[2:17]
	ds_read_b128 v[214:217], v188 offset:96
	ds_read_b128 v[218:221], v188 offset:4704
	ds_read_b128 v[234:237], v189 offset:18528
	ds_read_b128 v[238:241], v189 offset:23136
	ds_read_b128 v[242:245], v189 offset:27744
	ds_read_b128 v[246:249], v189 offset:32352
	s_waitcnt lgkmcnt(9)
	v_mfma_f32_32x32x16_bf16 v[114:129], v[190:193], v[198:201], v[114:129]
	v_mfma_f32_32x32x16_bf16 v[82:97], v[194:197], v[198:201], v[82:97]
	s_waitcnt lgkmcnt(8)
	v_mfma_f32_32x32x16_bf16 v[98:113], v[190:193], v[202:205], v[98:113]
	v_mfma_f32_32x32x16_bf16 v[66:81], v[194:197], v[202:205], v[66:81]
	s_waitcnt lgkmcnt(7)
	v_mfma_f32_32x32x16_bf16 v[50:65], v[190:193], v[206:209], v[50:65]
	v_mfma_f32_32x32x16_bf16 v[18:33], v[194:197], v[206:209], v[18:33]
	s_waitcnt lgkmcnt(6)
	v_mfma_f32_32x32x16_bf16 v[34:49], v[190:193], v[210:213], v[34:49]
	v_mfma_f32_32x32x16_bf16 v[2:17], v[194:197], v[210:213], v[2:17]
	s_waitcnt lgkmcnt(3)
	v_mfma_f32_32x32x16_bf16 v[114:129], v[214:217], v[234:237], v[114:129]
	v_mfma_f32_32x32x16_bf16 v[82:97], v[218:221], v[234:237], v[82:97]
	s_waitcnt lgkmcnt(2)
	v_mfma_f32_32x32x16_bf16 v[98:113], v[214:217], v[238:241], v[98:113]
	v_mfma_f32_32x32x16_bf16 v[66:81], v[218:221], v[238:241], v[66:81]
	s_waitcnt lgkmcnt(1)
	v_mfma_f32_32x32x16_bf16 v[50:65], v[214:217], v[242:245], v[50:65]
	v_mfma_f32_32x32x16_bf16 v[18:33], v[218:221], v[242:245], v[18:33]
	s_waitcnt lgkmcnt(0)
	v_mfma_f32_32x32x16_bf16 v[34:49], v[214:217], v[246:249], v[34:49]
	v_mfma_f32_32x32x16_bf16 v[2:17], v[218:221], v[246:249], v[2:17]
	s_setprio 0
	s_waitcnt lgkmcnt(0)
	s_barrier
	s_cmp_gt_u32 s5, 14
	s_cbranch_scc1 .LBB0_787
	s_cmpk_eq_i32 s6, 0x700
	s_waitcnt vmcnt(9)
	ds_write_b128 v187, v[130:133]
	ds_write_b128 v187, v[134:137] offset:4608
	ds_write_b128 v187, v[138:141] offset:9216
	s_waitcnt vmcnt(7)
	ds_write_b128 v187, v[142:145] offset:13824
	ds_write_b128 v187, v[146:149] offset:18432
	s_waitcnt vmcnt(6)
	ds_write_b128 v187, v[150:153] offset:23040
	s_waitcnt vmcnt(5)
	ds_write_b128 v187, v[154:157] offset:27648
	s_waitcnt vmcnt(4)
	ds_write_b128 v187, v[158:161] offset:32256
	s_waitcnt vmcnt(3)
	ds_write_b128 v187, v[162:165] offset:36864
	s_waitcnt vmcnt(2)
	ds_write_b128 v187, v[166:169] offset:41472
	s_waitcnt vmcnt(1)
	ds_write_b128 v187, v[170:173] offset:46080
	s_waitcnt vmcnt(0)
	ds_write_b128 v187, v[174:177] offset:50688
	s_cbranch_scc1 .LBB0_786
	v_lshl_add_u64 v[138:139], v[184:185], 0, s[6:7]
	v_add_co_u32_e32 v130, vcc, 0x38a8000, v138
	v_lshl_add_u64 v[170:171], v[182:183], 0, s[6:7]
	s_nop 0
	v_addc_co_u32_e32 v131, vcc, 0, v139, vcc
	v_add_co_u32_e32 v134, vcc, 0x38b8000, v138
	s_nop 1
	v_addc_co_u32_e32 v135, vcc, 0, v139, vcc
	v_add_co_u32_e32 v140, vcc, 0x38c8000, v138
	global_load_dwordx4 v[130:133], v[130:131], off offset:256
	s_nop 0
	global_load_dwordx4 v[134:137], v[134:135], off offset:256
	v_addc_co_u32_e32 v141, vcc, 0, v139, vcc
	v_add_co_u32_e32 v142, vcc, 0x38d8000, v138
	s_nop 1
	v_addc_co_u32_e32 v143, vcc, 0, v139, vcc
	v_add_co_u32_e32 v146, vcc, 0x408000, v170
	global_load_dwordx4 v[138:141], v[140:141], off offset:256
	s_nop 0
	global_load_dwordx4 v[142:145], v[142:143], off offset:256
	v_addc_co_u32_e32 v147, vcc, 0, v171, vcc
	v_add_co_u32_e32 v150, vcc, 0x418000, v170
	s_nop 1
	v_addc_co_u32_e32 v151, vcc, 0, v171, vcc
	v_add_co_u32_e32 v154, vcc, 0x428000, v170
	global_load_dwordx4 v[146:149], v[146:147], off offset:256
	s_nop 0
	global_load_dwordx4 v[150:153], v[150:151], off offset:256
	v_addc_co_u32_e32 v155, vcc, 0, v171, vcc
	v_add_co_u32_e32 v158, vcc, 0x438000, v170
	s_nop 1
	v_addc_co_u32_e32 v159, vcc, 0, v171, vcc
	v_add_co_u32_e32 v162, vcc, 0x448000, v170
	global_load_dwordx4 v[154:157], v[154:155], off offset:256
	s_nop 0
	global_load_dwordx4 v[158:161], v[158:159], off offset:256
	v_addc_co_u32_e32 v163, vcc, 0, v171, vcc
	v_add_co_u32_e32 v166, vcc, 0x458000, v170
	s_nop 1
	v_addc_co_u32_e32 v167, vcc, 0, v171, vcc
	v_add_co_u32_e32 v172, vcc, 0x468000, v170
	global_load_dwordx4 v[162:165], v[162:163], off offset:256
	s_nop 0
	global_load_dwordx4 v[166:169], v[166:167], off offset:256
	v_addc_co_u32_e32 v173, vcc, 0, v171, vcc
	v_add_co_u32_e32 v174, vcc, 0x478000, v170
	s_nop 1
	v_addc_co_u32_e32 v175, vcc, 0, v171, vcc
	global_load_dwordx4 v[170:173], v[172:173], off offset:256
	s_nop 0
	global_load_dwordx4 v[174:177], v[174:175], off offset:256
	s_branch .LBB0_786
